# every label keeps its baseline byte offset mod 8 (15 pad nops after edited regions) and the four GEMM K-loop heads are 64-byte aligned
# speedup vs baseline: 1.0002x; 1.0002x over previous
.LBB0_10:
	s_add_i32 s3, s3, s98
	s_cmp_lt_i32 s3, s99
	s_cbranch_scc0 .Lconv_ret
	s_nop 0

.Lrp_p0_nog:
	s_waitcnt vmcnt(0)
	s_branch .LBB0_64
	s_nop 0

.LBB0_64:
	s_and_b64 vcc, exec, s[4:5]
	s_cbranch_vccnz .LBB0_63
	global_load_dwordx4 v[18:21], v[32:33], off offset:-4096
	global_load_dwordx4 v[6:9], v[32:33], off offset:-2048
	global_load_dwordx4 v[2:5], v[32:33], off offset:16
	global_load_dwordx4 v[46:49], v[32:33], off offset:-4080
	global_load_dwordx4 v[22:25], v[32:33], off
	global_load_dwordx4 v[50:53], v[32:33], off offset:-2032
	global_load_dwordx4 v[14:17], v[32:33], off offset:2048
	global_load_dwordx4 v[10:13], v[32:33], off offset:2064
	global_load_dwordx4 v[54:57], v[26:27], off
	global_load_dwordx4 v[58:61], v[26:27], off offset:16
	v_cmp_lt_i32_e32 vcc, v40, v39
	s_waitcnt vmcnt(9)
	v_mov_b32_e32 v64, v19
	v_cndmask_b32_e32 v62, v38, v40, vcc
	v_mov_b32_e32 v68, v21
	s_waitcnt vmcnt(6)
	v_mov_b32_e32 v65, v47
	v_mov_b32_e32 v69, v49
	v_lshlrev_b32_e32 v85, 2, v62
	v_mov_b32_e32 v62, v18
	v_mov_b32_e32 v66, v20
	v_pk_mul_f32 v[70:71], v[8:9], v[8:9]
	v_pk_mul_f32 v[72:73], v[6:7], v[6:7]
	v_mov_b32_e32 v63, v46
	v_mov_b32_e32 v67, v48
	v_pk_mul_f32 v[64:65], v[64:65], v[64:65]
	v_pk_mul_f32 v[68:69], v[68:69], v[68:69]
	v_pk_mov_b32 v[86:87], v[72:73], v[70:71] op_sel:[1,0]
	v_mov_b32_e32 v73, v71
	v_pk_fma_f32 v[62:63], v[62:63], v[62:63], v[64:65]
	v_pk_fma_f32 v[64:65], v[66:67], v[66:67], v[68:69]
	v_pk_mul_f32 v[74:75], v[4:5], v[4:5]
	v_pk_mul_f32 v[76:77], v[2:3], v[2:3]
	s_waitcnt vmcnt(4)
	v_mul_f32_e32 v78, v51, v51
	v_mul_f32_e32 v80, v53, v53
	v_pk_add_f32 v[66:67], v[86:87], v[72:73]
	v_pk_add_f32 v[62:63], v[62:63], v[64:65]
	v_mul_f32_e32 v88, v24, v24
	v_mul_f32_e32 v89, v25, v25
	v_mul_f32_e32 v92, v23, v23
	v_mul_f32_e32 v93, v22, v22
	v_pk_mov_b32 v[70:71], v[76:77], v[74:75] op_sel:[1,0]
	v_mov_b32_e32 v77, v75
	v_pk_fma_f32 v[74:75], v[50:51], v[50:51], v[78:79] op_sel_hi:[1,1,0]
	v_pk_fma_f32 v[78:79], v[52:53], v[52:53], v[80:81] op_sel_hi:[1,1,0]
	v_pk_add_f32 v[66:67], v[66:67], v[66:67] op_sel:[0,1] op_sel_hi:[1,0]
	v_pk_add_f32 v[62:63], v[62:63], v[62:63] op_sel:[0,1] op_sel_hi:[1,0]
	v_mov_b32_e32 v75, v88
	v_mov_b32_e32 v79, v89
	v_mov_b32_e32 v67, v92
	v_mov_b32_e32 v63, v93
	v_pk_add_f32 v[64:65], v[74:75], v[78:79]
	v_pk_add_f32 v[62:63], v[62:63], v[66:67]
	s_waitcnt vmcnt(3)
	v_mul_f32_e32 v82, v15, v15
	v_mul_f32_e32 v84, v17, v17
	v_pk_add_f32 v[68:69], v[70:71], v[76:77]
	v_pk_add_f32 v[62:63], v[62:63], v[64:65]
	s_waitcnt vmcnt(2)
	v_mul_f32_e32 v90, v12, v12
	v_mul_f32_e32 v91, v13, v13
	v_mul_f32_e32 v94, v10, v10
	v_mul_f32_e32 v95, v11, v11
	v_pk_fma_f32 v[80:81], v[14:15], v[14:15], v[82:83] op_sel_hi:[1,1,0]
	v_pk_fma_f32 v[82:83], v[16:17], v[16:17], v[84:85] op_sel_hi:[1,1,0]
	v_pk_add_f32 v[68:69], v[68:69], v[68:69] op_sel:[0,1] op_sel_hi:[1,0]
	v_pk_add_f32 v[62:63], v[62:63], v[62:63] op_sel:[0,1] op_sel_hi:[1,0]
	v_mov_b32_e32 v81, v90
	v_mov_b32_e32 v83, v91
	v_mov_b32_e32 v69, v95
	v_mov_b32_e32 v63, v94
	v_pk_add_f32 v[70:71], v[80:81], v[82:83]
	v_pk_add_f32 v[62:63], v[62:63], v[68:69]
	v_cmp_lt_i32_e32 vcc, v41, v39
	v_pk_add_f32 v[62:63], v[62:63], v[70:71]
	s_waitcnt vmcnt(1)
	v_pk_mul_f32 v[18:19], v[18:19], v[54:55]
	v_add_f32_e32 v62, v62, v63
	ds_bpermute_b32 v63, v85, v62
	v_cndmask_b32_e32 v64, v38, v41, vcc
	v_lshlrev_b32_e32 v64, 2, v64
	v_cmp_lt_i32_e32 vcc, v42, v39
	v_pk_mul_f32 v[20:21], v[20:21], v[56:57]
	s_waitcnt lgkmcnt(0)
	v_add_f32_e32 v62, v62, v63
	ds_bpermute_b32 v63, v64, v62
	v_cndmask_b32_e32 v64, v38, v42, vcc
	v_lshlrev_b32_e32 v64, 2, v64
	v_cmp_lt_i32_e32 vcc, v43, v39
	s_waitcnt vmcnt(0)
	v_pk_mul_f32 v[46:47], v[46:47], v[58:59]
	s_waitcnt lgkmcnt(0)
	v_add_f32_e32 v62, v62, v63
	ds_bpermute_b32 v63, v64, v62
	v_cndmask_b32_e32 v64, v38, v43, vcc
	v_lshlrev_b32_e32 v64, 2, v64
	v_cmp_lt_i32_e32 vcc, v44, v39
	v_pk_mul_f32 v[48:49], v[48:49], v[60:61]
	s_waitcnt lgkmcnt(0)
	v_add_f32_e32 v62, v62, v63
	ds_bpermute_b32 v63, v64, v62
	v_cndmask_b32_e32 v64, v38, v44, vcc
	v_lshlrev_b32_e32 v64, 2, v64
	v_cmp_lt_i32_e32 vcc, v45, v39
	s_waitcnt lgkmcnt(0)
	v_add_f32_e32 v62, v62, v63
	ds_bpermute_b32 v63, v64, v62
	v_cndmask_b32_e32 v64, v38, v45, vcc
	v_lshlrev_b32_e32 v64, 2, v64
	s_waitcnt lgkmcnt(0)
	v_add_f32_e32 v62, v62, v63
	ds_bpermute_b32 v63, v64, v62
	s_waitcnt lgkmcnt(0)
	v_add_f32_e32 v62, v62, v63
	v_fmamk_f32 v62, v62, 0x3a000000, v1
	v_mul_f32_e32 v63, 0x4f800000, v62
	v_cmp_gt_f32_e32 vcc, s3, v62
	s_nop 1
	v_cndmask_b32_e32 v62, v62, v63, vcc
	v_sqrt_f32_e32 v63, v62
	s_nop 0
	v_add_u32_e32 v54, -1, v63
	v_add_u32_e32 v55, 1, v63
	v_fma_f32 v56, -v54, v63, v62
	v_fma_f32 v57, -v55, v63, v62
	v_cmp_ge_f32_e64 s[6:7], 0, v56
	s_nop 1
	v_cndmask_b32_e64 v54, v63, v54, s[6:7]
	v_cmp_lt_f32_e64 s[6:7], 0, v57
	s_nop 1
	v_cndmask_b32_e64 v54, v54, v55, s[6:7]
	v_mul_f32_e32 v55, 0x37800000, v54
	v_cndmask_b32_e32 v54, v54, v55, vcc
	v_cmp_class_f32_e32 vcc, v62, v37
	s_nop 1
	v_cndmask_b32_e32 v54, v54, v62, vcc
	v_div_scale_f32 v55, s[6:7], v54, v54, 1.0
	v_rcp_f32_e32 v56, v55
	v_div_scale_f32 v57, vcc, 1.0, v54, 1.0
	v_fma_f32 v58, -v55, v56, 1.0
	v_fmac_f32_e32 v56, v58, v56
	v_mul_f32_e32 v58, v57, v56
	v_fma_f32 v59, -v55, v58, v57
	v_fmac_f32_e32 v58, v59, v56
	v_fma_f32 v55, -v55, v58, v57
	v_div_fmas_f32 v55, v55, v56, v58
	v_div_fixup_f32 v54, v55, v54, 1.0
	v_pk_mul_f32 v[20:21], v[20:21], v[54:55] op_sel_hi:[1,0]
	v_pk_mul_f32 v[18:19], v[18:19], v[54:55] op_sel_hi:[1,0]
	v_pk_mul_f32 v[48:49], v[48:49], v[54:55] op_sel_hi:[1,0]
	v_pk_mul_f32 v[46:47], v[46:47], v[54:55] op_sel_hi:[1,0]
	v_bfe_u32 v55, v18, 16, 1
	v_bfe_u32 v57, v20, 16, 1
	v_bfe_u32 v59, v46, 16, 1
	v_bfe_u32 v61, v48, 16, 1
	v_bfe_u32 v56, v19, 16, 1
	v_bfe_u32 v58, v21, 16, 1
	v_bfe_u32 v60, v47, 16, 1
	v_bfe_u32 v62, v49, 16, 1
	v_add3_u32 v18, v18, v55, s11
	v_add3_u32 v20, v20, v57, s11
	v_add3_u32 v46, v46, v59, s11
	v_add3_u32 v48, v48, v61, s11
	v_add3_u32 v19, v19, v56, s11
	v_add3_u32 v21, v21, v58, s11
	v_add3_u32 v47, v47, v60, s11
	v_add3_u32 v49, v49, v62, s11
	v_lshrrev_b32_e32 v18, 16, v18
	v_lshrrev_b32_e32 v20, 16, v20
	v_lshrrev_b32_e32 v46, 16, v46
	v_lshrrev_b32_e32 v48, 16, v48
	v_and_or_b32 v18, v19, s16, v18
	v_and_or_b32 v19, v21, s16, v20
	v_and_or_b32 v20, v47, s16, v46
	v_and_or_b32 v21, v49, s16, v48
	global_store_dwordx4 v[34:35], v[18:21], off
	s_nop 1
	v_mov_b64_e32 v[18:19], v[100:101]
	v_mov_b64_e32 v[20:21], v[102:103]
	s_nop 0
	v_mov_b64_e32 v[46:47], v[104:105]
	v_mov_b64_e32 v[48:49], v[106:107]
	v_pk_mul_f32 v[8:9], v[8:9], v[20:21]
	v_pk_mul_f32 v[6:7], v[6:7], v[18:19]
	v_pk_mul_f32 v[18:19], v[52:53], v[48:49]
	v_pk_mul_f32 v[20:21], v[50:51], v[46:47]
	v_pk_mul_f32 v[8:9], v[8:9], v[54:55] op_sel_hi:[1,0]
	v_pk_mul_f32 v[6:7], v[6:7], v[54:55] op_sel_hi:[1,0]
	v_pk_mul_f32 v[18:19], v[18:19], v[54:55] op_sel_hi:[1,0]
	v_pk_mul_f32 v[20:21], v[20:21], v[54:55] op_sel_hi:[1,0]
	v_bfe_u32 v46, v6, 16, 1
	v_bfe_u32 v48, v8, 16, 1
	v_bfe_u32 v50, v20, 16, 1
	v_bfe_u32 v52, v18, 16, 1
	v_bfe_u32 v47, v7, 16, 1
	v_bfe_u32 v49, v9, 16, 1
	v_bfe_u32 v51, v21, 16, 1
	v_bfe_u32 v53, v19, 16, 1
	v_add3_u32 v6, v6, v46, s11
	v_add3_u32 v8, v8, v48, s11
	v_add3_u32 v20, v20, v50, s11
	v_add3_u32 v18, v18, v52, s11
	v_add3_u32 v7, v7, v47, s11
	v_add3_u32 v9, v9, v49, s11
	v_add3_u32 v21, v21, v51, s11
	v_add3_u32 v19, v19, v53, s11
	v_lshrrev_b32_e32 v6, 16, v6
	v_lshrrev_b32_e32 v8, 16, v8
	v_lshrrev_b32_e32 v20, 16, v20
	v_lshrrev_b32_e32 v18, 16, v18
	v_and_or_b32 v6, v7, s16, v6
	v_and_or_b32 v7, v9, s16, v8
	v_and_or_b32 v8, v21, s16, v20
	v_and_or_b32 v9, v19, s16, v18
	global_store_dwordx4 v[34:35], v[6:9], off offset:1024
	s_nop 1
	v_mov_b64_e32 v[6:7], v[108:109]
	v_mov_b64_e32 v[8:9], v[110:111]
	s_nop 0
	v_mov_b64_e32 v[18:19], v[112:113]
	v_mov_b64_e32 v[20:21], v[114:115]
	v_pk_mul_f32 v[8:9], v[24:25], v[8:9]
	v_pk_mul_f32 v[6:7], v[22:23], v[6:7]
	v_pk_mul_f32 v[4:5], v[4:5], v[20:21]
	v_pk_mul_f32 v[2:3], v[2:3], v[18:19]
	v_pk_mul_f32 v[8:9], v[8:9], v[54:55] op_sel_hi:[1,0]
	v_pk_mul_f32 v[6:7], v[6:7], v[54:55] op_sel_hi:[1,0]
	v_pk_mul_f32 v[4:5], v[54:55], v[4:5] op_sel_hi:[0,1]
	v_pk_mul_f32 v[2:3], v[54:55], v[2:3] op_sel_hi:[0,1]
	v_bfe_u32 v18, v6, 16, 1
	v_bfe_u32 v20, v8, 16, 1
	v_bfe_u32 v22, v2, 16, 1
	v_bfe_u32 v23, v3, 16, 1
	v_bfe_u32 v24, v4, 16, 1
	v_bfe_u32 v19, v7, 16, 1
	v_bfe_u32 v21, v9, 16, 1
	v_bfe_u32 v25, v5, 16, 1
	v_add3_u32 v6, v6, v18, s11
	v_add3_u32 v8, v8, v20, s11
	v_add3_u32 v2, v2, v22, s11
	v_add3_u32 v18, v3, v23, s11
	v_add3_u32 v3, v4, v24, s11
	v_add3_u32 v7, v7, v19, s11
	v_add3_u32 v9, v9, v21, s11
	v_add3_u32 v5, v5, v25, s11
	v_lshrrev_b32_e32 v4, 16, v6
	v_lshrrev_b32_e32 v6, 16, v8
	v_lshrrev_b32_e32 v8, 16, v2
	v_lshrrev_b32_e32 v19, 16, v3
	v_and_or_b32 v2, v7, s16, v4
	v_and_or_b32 v3, v9, s16, v6
	v_and_or_b32 v4, v18, s16, v8
	v_and_or_b32 v5, v5, s16, v19
	global_store_dwordx4 v[34:35], v[2:5], off offset:2048
	s_nop 1
	v_mov_b64_e32 v[2:3], v[116:117]
	v_mov_b64_e32 v[4:5], v[118:119]
	s_nop 0
	v_mov_b64_e32 v[6:7], v[120:121]
	v_mov_b64_e32 v[8:9], v[122:123]
	v_pk_mul_f32 v[4:5], v[16:17], v[4:5]
	v_pk_mul_f32 v[2:3], v[14:15], v[2:3]
	v_pk_mul_f32 v[8:9], v[12:13], v[8:9]
	v_pk_mul_f32 v[6:7], v[10:11], v[6:7]
	v_pk_mul_f32 v[4:5], v[54:55], v[4:5] op_sel_hi:[0,1]
	v_pk_mul_f32 v[2:3], v[54:55], v[2:3] op_sel_hi:[0,1]
	v_pk_mul_f32 v[8:9], v[54:55], v[8:9] op_sel_hi:[0,1]
	v_pk_mul_f32 v[6:7], v[54:55], v[6:7] op_sel_hi:[0,1]
	v_bfe_u32 v10, v2, 16, 1
	v_bfe_u32 v12, v4, 16, 1
	v_bfe_u32 v14, v6, 16, 1
	v_bfe_u32 v16, v8, 16, 1
	v_bfe_u32 v11, v3, 16, 1
	v_bfe_u32 v13, v5, 16, 1
	v_bfe_u32 v15, v7, 16, 1
	v_bfe_u32 v17, v9, 16, 1
	v_add3_u32 v2, v2, v10, s11
	v_add3_u32 v4, v4, v12, s11
	v_add3_u32 v6, v6, v14, s11
	v_add3_u32 v8, v8, v16, s11
	v_add3_u32 v3, v3, v11, s11
	v_add3_u32 v5, v5, v13, s11
	v_add3_u32 v7, v7, v15, s11
	v_add3_u32 v9, v9, v17, s11
	v_lshrrev_b32_e32 v2, 16, v2
	v_lshrrev_b32_e32 v4, 16, v4
	v_lshrrev_b32_e32 v6, 16, v6
	v_lshrrev_b32_e32 v8, 16, v8
	v_and_or_b32 v2, v3, s16, v2
	v_and_or_b32 v3, v5, s16, v4
	v_and_or_b32 v4, v7, s16, v6
	v_and_or_b32 v5, v9, s16, v8
	global_store_dwordx4 v[34:35], v[2:5], off offset:3072
	s_branch .LBB0_63
	s_nop 0

.Lslot_a_done:
	s_mov_b64 s[6:7], s[0:1]
	s_getreg_b32 s8, hwreg(HW_REG_XCC_ID, 0, 4)
	s_waitcnt vmcnt(0)
	s_waitcnt vmcnt(0)
	s_barrier
	s_and_saveexec_b64 s[4:5], s[46:47]
	s_cbranch_execz .LBB0_196
	v_readlane_b32 s9, v254, 27
	s_load_dwordx2 s[6:7], s[6:7], 0x100
	s_waitcnt vmcnt(0) expcnt(0) lgkmcnt(0)
	v_mov_b32_e32 v0, s9
	ds_read_b32 v2, v0
	v_readlane_b32 s9, v254, 28
	s_and_b32 s50, s8, 15
	s_waitcnt lgkmcnt(0)
	v_cmp_ne_u32_e32 vcc, 0, v2
	v_mov_b32_e32 v0, s9
	ds_read_b32 v0, v0
	s_cbranch_vccnz .LBB0_160
	s_add_u32 s8, s6, 0x1200
	s_addc_u32 s9, s7, 0
	s_add_u32 s12, s6, 0x1400
	s_addc_u32 s13, s7, 0
	s_add_u32 s14, s6, 0x1500
	s_addc_u32 s15, s7, 0
	s_add_u32 s16, s6, 0x1600
	s_addc_u32 s17, s7, 0
	s_add_u32 s18, s6, 0x1700
	s_addc_u32 s19, s7, 0
	s_add_u32 s20, s6, 0x1800
	s_addc_u32 s21, s7, 0
	s_add_u32 s22, s6, 0x1900
	s_addc_u32 s23, s7, 0
	s_add_u32 s24, s6, 0x1a00
	s_addc_u32 s25, s7, 0
	s_add_u32 s26, s6, 0x1b00
	s_addc_u32 s27, s7, 0
	s_add_u32 s28, s6, 0x1c00
	s_addc_u32 s29, s7, 0
	s_add_u32 s30, s6, 0x1d00
	s_addc_u32 s31, s7, 0
	s_add_u32 s34, s6, 0x1e00
	s_addc_u32 s35, s7, 0
	s_add_u32 s36, s6, 0x1f00
	s_addc_u32 s37, s7, 0
	s_add_u32 s38, s6, 0x2000
	s_addc_u32 s39, s7, 0
	s_add_u32 s40, s6, 0x2100
	s_addc_u32 s41, s7, 0
	s_add_u32 s42, s6, 0x2200
	s_addc_u32 s43, s7, 0
	s_add_u32 s44, s6, 0x2300
	s_addc_u32 s45, s7, 0
	s_mov_b32 s51, 1
	s_branch .LBB0_148
	s_nop 0

.LBB0_289:
	v_lshl_add_u64 v[0:1], s[16:17], 0, v[192:193]
	v_add_co_u32_e32 v4, vcc, 0x1000, v0
	v_lshl_add_u64 v[32:33], s[20:21], 0, v[52:53]
	s_nop 0
	v_addc_co_u32_e32 v5, vcc, 0, v1, vcc
	v_add_co_u32_e32 v34, vcc, 0x1ba00000, v32
	global_load_dwordx4 v[8:11], v[0:1], off offset:16
	global_load_dwordx4 v[12:15], v[0:1], off
	global_load_dwordx4 v[16:19], v[0:1], off offset:2064
	global_load_dwordx4 v[20:23], v[0:1], off offset:2048
	v_lshl_add_u64 v[2:3], v[0:1], 0, s[28:29]
	v_lshl_add_u64 v[0:1], v[0:1], 0, s[26:27]
	v_addc_co_u32_e32 v35, vcc, 0, v33, vcc
	global_load_dwordx4 v[28:31], v[4:5], off
	global_load_dwordx4 v[24:27], v[2:3], off offset:16
	s_nop 0
	global_load_dwordx4 v[4:7], v[4:5], off offset:2048
	s_nop 0
	global_load_dwordx4 v[0:3], v[0:1], off offset:16
	s_nop 0
	global_load_dwordx4 v[64:67], v[34:35], off
	global_load_dwordx4 v[68:71], v[34:35], off offset:1024
	global_load_dwordx4 v[58:61], v[34:35], off offset:2048
	global_load_dwordx4 v[88:91], v[34:35], off offset:3072
	s_mov_b32 s4, 0xf800000
	s_waitcnt vmcnt(3)
	v_and_b32_e32 v75, 0xffff0000, v66
	v_and_b32_e32 v74, 0xffff0000, v64
	v_and_b32_e32 v79, 0xffff0000, v67
	v_and_b32_e32 v78, 0xffff0000, v65
	v_lshlrev_b32_e32 v73, 16, v66
	v_lshlrev_b32_e32 v72, 16, v64
	v_lshlrev_b32_e32 v77, 16, v67
	v_lshlrev_b32_e32 v76, 16, v65
	v_pk_mul_f32 v[34:35], v[74:75], v[74:75]
	v_pk_mul_f32 v[64:65], v[78:79], v[78:79]
	v_pk_fma_f32 v[34:35], v[72:73], v[72:73], v[34:35]
	v_pk_fma_f32 v[64:65], v[76:77], v[76:77], v[64:65]
	s_waitcnt vmcnt(2)
	v_lshlrev_b32_e32 v32, 16, v70
	v_pk_add_f32 v[34:35], v[34:35], v[64:65]
	v_and_b32_e32 v33, 0xffff0000, v70
	v_pk_add_f32 v[64:65], v[34:35], v[34:35] op_sel_hi:[0,1]
	v_lshlrev_b32_e32 v35, 16, v69
	v_lshlrev_b32_e32 v34, 16, v68
	v_and_b32_e32 v69, 0xffff0000, v69
	v_and_b32_e32 v68, 0xffff0000, v68
	s_waitcnt vmcnt(1)
	v_lshlrev_b32_e32 v36, 16, v58
	v_pk_mul_f32 v[66:67], v[68:69], v[68:69]
	v_lshlrev_b32_e32 v70, 16, v71
	s_waitcnt vmcnt(0)
	v_lshlrev_b32_e32 v56, 16, v90
	v_and_b32_e32 v85, 0xffff0000, v90
	v_lshlrev_b32_e32 v54, 16, v91
	v_and_b32_e32 v55, 0xffff0000, v91
	v_pk_fma_f32 v[66:67], v[34:35], v[34:35], v[66:67]
	v_mul_f32_e32 v37, v32, v32
	v_mul_f32_e32 v91, v33, v33
	v_and_b32_e32 v71, 0xffff0000, v71
	v_mul_f32_e32 v62, v70, v70
	v_mov_b32_e32 v90, v36
	v_and_b32_e32 v86, 0xffff0000, v58
	v_lshlrev_b32_e32 v38, 16, v59
	v_and_b32_e32 v39, 0xffff0000, v59
	v_pk_add_f32 v[66:67], v[66:67], v[66:67] op_sel_hi:[0,1]
	v_pk_fma_f32 v[92:93], v[70:71], v[70:71], v[62:63] op_sel_hi:[1,1,0]
	v_pk_add_f32 v[90:91], v[36:37], v[90:91]
	v_mul_f32_e32 v92, v86, v86
	v_mul_f32_e32 v64, v38, v38
	v_mul_f32_e32 v66, v39, v39
	v_mul_f32_e32 v94, v36, v36
	v_mov_b32_e32 v95, v91
	v_pk_add_f32 v[90:91], v[94:95], v[92:93]
	v_pk_add_f32 v[64:65], v[64:65], v[66:67]
	v_and_b32_e32 v67, 0xffff0000, v61
	v_pk_add_f32 v[64:65], v[90:91], v[64:65]
	v_and_b32_e32 v66, 0xffff0000, v60
	v_pk_add_f32 v[90:91], v[64:65], v[64:65] op_sel_hi:[0,1]
	v_lshlrev_b32_e32 v65, 16, v61
	v_lshlrev_b32_e32 v64, 16, v60
	v_pk_mul_f32 v[60:61], v[66:67], v[66:67]
	v_lshlrev_b32_e32 v58, 16, v88
	v_pk_fma_f32 v[60:61], v[64:65], v[64:65], v[60:61]
	v_and_b32_e32 v59, 0xffff0000, v88
	v_pk_add_f32 v[92:93], v[60:61], v[60:61] op_sel_hi:[0,1]
	v_lshlrev_b32_e32 v60, 16, v89
	v_mul_f32_e32 v57, v58, v58
	v_mul_f32_e32 v95, v59, v59
	v_and_b32_e32 v61, 0xffff0000, v89
	v_mul_f32_e32 v62, v60, v60
	v_mov_b32_e32 v94, v56
	v_pk_fma_f32 v[88:89], v[60:61], v[60:61], v[62:63] op_sel_hi:[1,1,0]
	v_pk_add_f32 v[94:95], v[56:57], v[94:95]
	v_mul_f32_e32 v88, v85, v85
	v_mul_f32_e32 v92, v54, v54
	v_mul_f32_e32 v90, v55, v55
	v_mul_f32_e32 v96, v56, v56
	v_mov_b32_e32 v97, v95
	v_pk_add_f32 v[88:89], v[96:97], v[88:89]
	v_pk_add_f32 v[90:91], v[92:93], v[90:91]
	v_mov_b32_e32 v96, v72
	v_pk_add_f32 v[88:89], v[88:89], v[90:91]
	v_mov_b32_e32 v97, v74
	v_add_f32_e32 v37, v88, v89
	ds_bpermute_b32 v57, v63, v37
	v_mov_b32_e32 v74, v73
	s_waitcnt lgkmcnt(0)
	v_add_f32_e32 v37, v37, v57
	ds_bpermute_b32 v57, v80, v37
	s_waitcnt lgkmcnt(0)
	v_add_f32_e32 v37, v37, v57
	ds_bpermute_b32 v57, v81, v37
	s_waitcnt lgkmcnt(0)
	v_add_f32_e32 v37, v37, v57
	ds_bpermute_b32 v57, v82, v37
	s_waitcnt lgkmcnt(0)
	v_add_f32_e32 v37, v37, v57
	ds_bpermute_b32 v57, v83, v37
	s_waitcnt lgkmcnt(0)
	v_add_f32_e32 v37, v37, v57
	ds_bpermute_b32 v57, v84, v37
	s_waitcnt lgkmcnt(0)
	v_add_f32_e32 v37, v37, v57
	v_fmamk_f32 v37, v37, 0x3a000000, v219
	v_cmp_gt_f32_e32 vcc, s4, v37
	v_mul_f32_e32 v57, 0x4f800000, v37
	s_nop 0
	v_cndmask_b32_e32 v37, v37, v57, vcc
	v_sqrt_f32_e32 v57, v37
	s_nop 0
	v_add_u32_e32 v62, -1, v57
	v_fma_f32 v87, -v62, v57, v37
	v_cmp_ge_f32_e64 s[6:7], 0, v87
	v_add_u32_e32 v87, 1, v57
	s_nop 0
	v_cndmask_b32_e64 v62, v57, v62, s[6:7]
	v_fma_f32 v57, -v87, v57, v37
	v_cmp_lt_f32_e64 s[6:7], 0, v57
	s_nop 1
	v_cndmask_b32_e64 v57, v62, v87, s[6:7]
	v_mul_f32_e32 v62, 0x37800000, v57
	v_cndmask_b32_e32 v57, v57, v62, vcc
	v_cmp_class_f32_e32 vcc, v37, v220
	s_nop 1
	v_cndmask_b32_e32 v37, v57, v37, vcc
	v_div_scale_f32 v57, s[4:5], v37, v37, 0.5
	v_rcp_f32_e32 v62, v57
	s_nop 0
	v_fma_f32 v87, -v57, v62, 1.0
	v_fmac_f32_e32 v62, v87, v62
	v_div_scale_f32 v87, vcc, 0.5, v37, 0.5
	v_mul_f32_e32 v88, v87, v62
	v_fma_f32 v89, -v57, v88, v87
	v_fmac_f32_e32 v88, v89, v62
	v_fma_f32 v57, -v57, v88, v87
	v_div_fmas_f32 v57, v57, v62, v88
	v_mov_b64_e32 v[88:89], v[100:101]
	v_mov_b64_e32 v[90:91], v[102:103]
	v_mov_b64_e32 v[92:93], v[104:105]
	v_mov_b64_e32 v[94:95], v[106:107]
	v_div_fixup_f32 v62, v57, v37, 0.5
	v_mov_b32_e32 v37, v86
	v_mov_b32_e32 v57, v85
	s_andn2_b64 vcc, exec, s[10:11]
	v_pk_mul_f32 v[72:73], v[88:89], v[74:75]
	v_pk_mul_f32 v[92:93], v[92:93], v[96:97]
	v_mov_b32_e32 v97, v78
	v_mov_b32_e32 v78, v77
	v_pk_mul_f32 v[74:75], v[90:91], v[78:79]
	v_mov_b32_e32 v96, v76
	v_pk_fma_f32 v[10:11], v[74:75], v[62:63], v[10:11] op_sel_hi:[1,0,1]
	v_pk_fma_f32 v[8:9], v[72:73], v[62:63], v[8:9] op_sel_hi:[1,0,1]
	v_mov_b64_e32 v[72:73], v[108:109]
	v_mov_b64_e32 v[74:75], v[110:111]
	v_mov_b64_e32 v[76:77], v[112:113]
	v_mov_b64_e32 v[78:79], v[114:115]
	v_mov_b32_e32 v89, v68
	v_mov_b32_e32 v68, v35
	v_mov_b32_e32 v88, v34
	v_pk_mul_f32 v[94:95], v[94:95], v[96:97]
	v_pk_fma_f32 v[12:13], v[92:93], v[62:63], v[12:13] op_sel_hi:[1,0,1]
	v_pk_fma_f32 v[14:15], v[94:95], v[62:63], v[14:15] op_sel_hi:[1,0,1]
	v_pk_mul_f32 v[32:33], v[72:73], v[32:33]
	v_pk_mul_f32 v[34:35], v[78:79], v[68:69]
	v_pk_fma_f32 v[16:17], v[32:33], v[62:63], v[16:17] op_sel_hi:[1,0,1]
	v_pk_fma_f32 v[22:23], v[34:35], v[62:63], v[22:23] op_sel_hi:[1,0,1]
	v_pk_mul_f32 v[34:35], v[74:75], v[70:71]
	v_pk_mul_f32 v[76:77], v[76:77], v[88:89]
	v_pk_fma_f32 v[18:19], v[34:35], v[62:63], v[18:19] op_sel_hi:[1,0,1]
	v_mov_b64_e32 v[32:33], v[116:117]
	v_mov_b64_e32 v[34:35], v[118:119]
	v_mov_b64_e32 v[68:69], v[120:121]
	v_mov_b64_e32 v[70:71], v[122:123]
	v_pk_fma_f32 v[20:21], v[76:77], v[62:63], v[20:21] op_sel_hi:[1,0,1]
	v_pk_mul_f32 v[36:37], v[68:69], v[36:37]
	s_nop 0
	v_pk_fma_f32 v[28:29], v[36:37], v[62:63], v[28:29] op_sel_hi:[1,0,1]
	v_mov_b32_e32 v36, v64
	v_mov_b32_e32 v37, v66
	v_mov_b32_e32 v66, v65
	v_pk_mul_f32 v[38:39], v[70:71], v[38:39]
	v_pk_mul_f32 v[32:33], v[32:33], v[36:37]
	v_pk_mul_f32 v[34:35], v[34:35], v[66:67]
	v_pk_fma_f32 v[30:31], v[38:39], v[62:63], v[30:31] op_sel_hi:[1,0,1]
	v_pk_fma_f32 v[26:27], v[34:35], v[62:63], v[26:27] op_sel_hi:[1,0,1]
	v_pk_fma_f32 v[24:25], v[32:33], v[62:63], v[24:25] op_sel_hi:[1,0,1]
	v_mov_b64_e32 v[32:33], v[124:125]
	v_mov_b64_e32 v[34:35], v[126:127]
	v_mov_b64_e32 v[36:37], v[128:129]
	v_mov_b64_e32 v[38:39], v[130:131]
	v_pk_mul_f32 v[32:33], v[32:33], v[56:57]
	v_pk_mul_f32 v[36:37], v[36:37], v[58:59]
	v_pk_mul_f32 v[38:39], v[38:39], v[60:61]
	v_pk_mul_f32 v[34:35], v[34:35], v[54:55]
	v_pk_fma_f32 v[6:7], v[38:39], v[62:63], v[6:7] op_sel_hi:[1,0,1]
	v_pk_fma_f32 v[4:5], v[36:37], v[62:63], v[4:5] op_sel_hi:[1,0,1]
	v_pk_fma_f32 v[2:3], v[34:35], v[62:63], v[2:3] op_sel_hi:[1,0,1]
	v_pk_fma_f32 v[0:1], v[32:33], v[62:63], v[0:1] op_sel_hi:[1,0,1]
	s_cbranch_vccnz .LBB0_291
	v_lshl_add_u64 v[32:33], s[22:23], 0, v[192:193]
	global_store_dwordx4 v[32:33], v[12:15], off
	global_store_dwordx4 v[32:33], v[8:11], off offset:16
	global_store_dwordx4 v[32:33], v[20:23], off offset:2048
	global_store_dwordx4 v[32:33], v[16:19], off offset:2064
	v_add_co_u32_e32 v32, vcc, 0x1000, v32
	s_nop 1
	v_addc_co_u32_e32 v33, vcc, 0, v33, vcc
	global_store_dwordx4 v[32:33], v[28:31], off
	global_store_dwordx4 v[32:33], v[24:27], off offset:16
	global_store_dwordx4 v[32:33], v[4:7], off offset:2048
	global_store_dwordx4 v[32:33], v[0:3], off offset:2064
	s_nop 0
.LBB0_291:
	s_andn2_b64 vcc, exec, s[14:15]
	s_cbranch_vccnz .LBB0_288
	v_mov_b32_e32 v34, v13
	v_mov_b32_e32 v35, v9
	v_mov_b32_e32 v32, v12
	v_mov_b32_e32 v33, v8
	v_pk_mul_f32 v[34:35], v[34:35], v[34:35]
	v_mov_b32_e32 v36, v15
	v_mov_b32_e32 v37, v11
	v_pk_fma_f32 v[32:33], v[32:33], v[32:33], v[34:35]
	v_mov_b32_e32 v34, v14
	v_mov_b32_e32 v35, v10
	v_pk_mul_f32 v[36:37], v[36:37], v[36:37]
	s_mov_b32 s4, 0xf800000
	v_pk_fma_f32 v[34:35], v[34:35], v[34:35], v[36:37]
	v_pk_mul_f32 v[36:37], v[20:21], v[20:21]
	v_pk_add_f32 v[32:33], v[32:33], v[34:35]
	v_pk_mul_f32 v[34:35], v[22:23], v[22:23]
	v_pk_add_f32 v[32:33], v[32:33], v[32:33] op_sel_hi:[0,1]
	v_pk_mov_b32 v[38:39], v[36:37], v[34:35] op_sel:[1,0]
	v_mov_b32_e32 v37, v35
	v_mul_f32_e32 v32, v16, v16
	v_pk_add_f32 v[34:35], v[38:39], v[36:37]
	v_pk_fma_f32 v[36:37], v[16:17], v[16:17], v[32:33] op_sel_hi:[1,1,0]
	v_mul_f32_e32 v32, v18, v18
	v_pk_add_f32 v[34:35], v[34:35], v[34:35] op_sel_hi:[0,1]
	v_pk_fma_f32 v[38:39], v[18:19], v[18:19], v[32:33] op_sel_hi:[1,1,0]
	v_mul_f32_e32 v36, v28, v28
	v_mul_f32_e32 v38, v29, v29
	v_mul_f32_e32 v34, v30, v30
	v_mul_f32_e32 v32, v31, v31
	v_pk_add_f32 v[36:37], v[36:37], v[38:39]
	v_pk_add_f32 v[32:33], v[34:35], v[32:33]
	v_pk_mul_f32 v[34:35], v[26:27], v[26:27]
	v_pk_add_f32 v[32:33], v[36:37], v[32:33]
	v_pk_mul_f32 v[36:37], v[24:25], v[24:25]
	v_pk_add_f32 v[32:33], v[32:33], v[32:33] op_sel_hi:[0,1]
	v_pk_mov_b32 v[38:39], v[36:37], v[34:35] op_sel:[1,0]
	v_mov_b32_e32 v37, v35
	v_mul_f32_e32 v32, v4, v4
	v_pk_add_f32 v[34:35], v[38:39], v[36:37]
	v_pk_fma_f32 v[36:37], v[4:5], v[4:5], v[32:33] op_sel_hi:[1,1,0]
	v_mul_f32_e32 v32, v6, v6
	v_pk_add_f32 v[34:35], v[34:35], v[34:35] op_sel_hi:[0,1]
	v_pk_fma_f32 v[38:39], v[6:7], v[6:7], v[32:33] op_sel_hi:[1,1,0]
	v_mul_f32_e32 v36, v0, v0
	v_mul_f32_e32 v38, v1, v1
	v_mul_f32_e32 v34, v2, v2
	v_mul_f32_e32 v32, v3, v3
	v_pk_add_f32 v[36:37], v[36:37], v[38:39]
	v_pk_add_f32 v[32:33], v[34:35], v[32:33]
	v_lshl_add_u64 v[38:39], s[18:19], 0, v[52:53]
	v_pk_add_f32 v[32:33], v[36:37], v[32:33]
	s_nop 0
	v_add_f32_e32 v32, v32, v33
	ds_bpermute_b32 v33, v63, v32
	s_waitcnt lgkmcnt(0)
	v_add_f32_e32 v32, v32, v33
	ds_bpermute_b32 v33, v80, v32
	s_waitcnt lgkmcnt(0)
	v_add_f32_e32 v32, v32, v33
	ds_bpermute_b32 v33, v81, v32
	s_waitcnt lgkmcnt(0)
	v_add_f32_e32 v32, v32, v33
	ds_bpermute_b32 v33, v82, v32
	s_waitcnt lgkmcnt(0)
	v_add_f32_e32 v32, v32, v33
	ds_bpermute_b32 v33, v83, v32
	s_waitcnt lgkmcnt(0)
	v_add_f32_e32 v32, v32, v33
	ds_bpermute_b32 v33, v84, v32
	s_waitcnt lgkmcnt(0)
	v_add_f32_e32 v32, v32, v33
	v_fmamk_f32 v32, v32, 0x3a000000, v219
	v_cmp_gt_f32_e32 vcc, s4, v32
	v_mul_f32_e32 v33, 0x4f800000, v32
	s_nop 0
	v_cndmask_b32_e32 v32, v32, v33, vcc
	v_sqrt_f32_e32 v33, v32
	s_nop 0
	v_add_u32_e32 v34, -1, v33
	v_fma_f32 v35, -v34, v33, v32
	v_cmp_ge_f32_e64 s[6:7], 0, v35
	v_add_u32_e32 v35, 1, v33
	s_nop 0
	v_cndmask_b32_e64 v34, v33, v34, s[6:7]
	v_fma_f32 v33, -v35, v33, v32
	v_cmp_lt_f32_e64 s[6:7], 0, v33
	s_nop 1
	v_cndmask_b32_e64 v33, v34, v35, s[6:7]
	v_mul_f32_e32 v34, 0x37800000, v33
	v_cndmask_b32_e32 v33, v33, v34, vcc
	v_cmp_class_f32_e32 vcc, v32, v220
	s_nop 1
	v_cndmask_b32_e32 v32, v33, v32, vcc
	v_div_scale_f32 v33, s[4:5], v32, v32, 1.0
	v_rcp_f32_e32 v34, v33
	s_mov_b32 s4, 0xffff0000
	s_mov_b32 s5, 0x14200000
	v_fma_f32 v35, -v33, v34, 1.0
	v_fmac_f32_e32 v34, v35, v34
	v_div_scale_f32 v35, vcc, 1.0, v32, 1.0
	v_mul_f32_e32 v36, v35, v34
	v_fma_f32 v37, -v33, v36, v35
	v_fmac_f32_e32 v36, v37, v34
	v_fma_f32 v33, -v33, v36, v35
	v_div_fmas_f32 v33, v33, v34, v36
	v_div_fixup_f32 v36, v33, v32, 1.0
	v_mov_b64_e32 v[32:33], v[132:133]
	v_mov_b64_e32 v[34:35], v[134:135]
	v_mov_b64_e32 v[54:55], v[136:137]
	v_mov_b64_e32 v[56:57], v[138:139]
	v_pk_mul_f32 v[10:11], v[10:11], v[34:35]
	v_pk_mul_f32 v[12:13], v[12:13], v[54:55]
	v_pk_mul_f32 v[8:9], v[8:9], v[32:33]
	v_pk_mul_f32 v[12:13], v[12:13], v[36:37] op_sel_hi:[1,0]
	v_pk_mul_f32 v[32:33], v[10:11], v[36:37] op_sel_hi:[1,0]
	v_bfe_u32 v10, v12, 16, 1
	v_pk_mul_f32 v[14:15], v[14:15], v[56:57]
	v_add3_u32 v10, v12, v10, s77
	v_bfe_u32 v11, v13, 16, 1
	v_pk_mul_f32 v[14:15], v[14:15], v[36:37] op_sel_hi:[1,0]
	v_lshrrev_b32_e32 v10, 16, v10
	v_add3_u32 v11, v13, v11, s77
	v_and_or_b32 v10, v11, s4, v10
	v_bfe_u32 v11, v14, 16, 1
	v_add3_u32 v11, v14, v11, s77
	v_bfe_u32 v12, v15, 16, 1
	v_pk_mul_f32 v[8:9], v[8:9], v[36:37] op_sel_hi:[1,0]
	v_lshrrev_b32_e32 v11, 16, v11
	v_add3_u32 v12, v15, v12, s77
	v_and_or_b32 v11, v12, s4, v11
	v_bfe_u32 v12, v8, 16, 1
	v_add3_u32 v8, v8, v12, s77
	v_bfe_u32 v12, v9, 16, 1
	v_lshrrev_b32_e32 v8, 16, v8
	v_add3_u32 v9, v9, v12, s77
	v_and_or_b32 v12, v9, s4, v8
	v_bfe_u32 v8, v32, 16, 1
	v_add3_u32 v8, v32, v8, s77
	v_bfe_u32 v9, v33, 16, 1
	v_lshrrev_b32_e32 v8, 16, v8
	v_add3_u32 v9, v33, v9, s77
	v_and_or_b32 v13, v9, s4, v8
	v_add_co_u32_e32 v8, vcc, s5, v38
	s_nop 1
	v_addc_co_u32_e32 v9, vcc, 0, v39, vcc
	global_store_dwordx4 v[8:9], v[10:13], off
	s_nop 1
	v_mov_b64_e32 v[10:11], v[140:141]
	v_mov_b64_e32 v[12:13], v[142:143]
	s_nop 0
	v_mov_b64_e32 v[32:33], v[144:145]
	v_mov_b64_e32 v[34:35], v[146:147]
	v_pk_mul_f32 v[12:13], v[18:19], v[12:13]
	v_pk_mul_f32 v[20:21], v[20:21], v[32:33]
	v_pk_mul_f32 v[10:11], v[16:17], v[10:11]
	v_pk_mul_f32 v[20:21], v[20:21], v[36:37] op_sel_hi:[1,0]
	v_pk_mul_f32 v[16:17], v[12:13], v[36:37] op_sel_hi:[1,0]
	v_pk_mul_f32 v[12:13], v[10:11], v[36:37] op_sel_hi:[1,0]
	v_bfe_u32 v10, v20, 16, 1
	v_pk_mul_f32 v[14:15], v[22:23], v[34:35]
	v_add3_u32 v10, v20, v10, s77
	v_bfe_u32 v11, v21, 16, 1
	v_pk_mul_f32 v[14:15], v[14:15], v[36:37] op_sel_hi:[1,0]
	v_lshrrev_b32_e32 v10, 16, v10
	v_add3_u32 v11, v21, v11, s77
	v_and_or_b32 v10, v11, s4, v10
	v_bfe_u32 v11, v14, 16, 1
	v_add3_u32 v11, v14, v11, s77
	v_bfe_u32 v14, v15, 16, 1
	v_lshrrev_b32_e32 v11, 16, v11
	v_add3_u32 v14, v15, v14, s77
	v_and_or_b32 v11, v14, s4, v11
	v_bfe_u32 v14, v12, 16, 1
	v_add3_u32 v12, v12, v14, s77
	v_bfe_u32 v14, v13, 16, 1
	v_lshrrev_b32_e32 v12, 16, v12
	v_add3_u32 v13, v13, v14, s77
	v_and_or_b32 v12, v13, s4, v12
	v_bfe_u32 v13, v16, 16, 1
	v_add3_u32 v13, v16, v13, s77
	v_bfe_u32 v14, v17, 16, 1
	v_lshrrev_b32_e32 v13, 16, v13
	v_add3_u32 v14, v17, v14, s77
	v_and_or_b32 v13, v14, s4, v13
	global_store_dwordx4 v[8:9], v[10:13], off offset:1024
	s_nop 1
	v_mov_b64_e32 v[10:11], v[148:149]
	v_mov_b64_e32 v[12:13], v[150:151]
	s_nop 0
	v_mov_b64_e32 v[14:15], v[152:153]
	v_mov_b64_e32 v[16:17], v[154:155]
	v_pk_mul_f32 v[12:13], v[26:27], v[12:13]
	v_pk_mul_f32 v[14:15], v[28:29], v[14:15]
	v_pk_mul_f32 v[10:11], v[24:25], v[10:11]
	v_pk_mul_f32 v[14:15], v[36:37], v[14:15] op_sel_hi:[0,1]
	v_pk_mul_f32 v[18:19], v[36:37], v[12:13] op_sel_hi:[0,1]
	v_pk_mul_f32 v[12:13], v[36:37], v[10:11] op_sel_hi:[0,1]
	v_bfe_u32 v10, v14, 16, 1
	v_pk_mul_f32 v[16:17], v[30:31], v[16:17]
	v_add3_u32 v10, v14, v10, s77
	v_bfe_u32 v11, v15, 16, 1
	v_pk_mul_f32 v[16:17], v[36:37], v[16:17] op_sel_hi:[0,1]
	v_lshrrev_b32_e32 v10, 16, v10
	v_add3_u32 v11, v15, v11, s77
	v_and_or_b32 v10, v11, s4, v10
	v_bfe_u32 v11, v16, 16, 1
	v_add3_u32 v11, v16, v11, s77
	v_bfe_u32 v14, v17, 16, 1
	v_lshrrev_b32_e32 v11, 16, v11
	v_add3_u32 v14, v17, v14, s77
	v_and_or_b32 v11, v14, s4, v11
	v_bfe_u32 v14, v12, 16, 1
	v_add3_u32 v12, v12, v14, s77
	v_bfe_u32 v14, v13, 16, 1
	v_lshrrev_b32_e32 v12, 16, v12
	v_add3_u32 v13, v13, v14, s77
	v_and_or_b32 v12, v13, s4, v12
	v_bfe_u32 v13, v18, 16, 1
	v_add3_u32 v13, v18, v13, s77
	v_bfe_u32 v14, v19, 16, 1
	v_lshrrev_b32_e32 v13, 16, v13
	v_add3_u32 v14, v19, v14, s77
	v_and_or_b32 v13, v14, s4, v13
	global_store_dwordx4 v[8:9], v[10:13], off offset:2048
	s_nop 1
	v_mov_b64_e32 v[10:11], v[156:157]
	v_mov_b64_e32 v[12:13], v[158:159]
	s_nop 0
	v_mov_b64_e32 v[14:15], v[160:161]
	v_mov_b64_e32 v[16:17], v[162:163]
	v_pk_mul_f32 v[2:3], v[2:3], v[12:13]
	v_pk_mul_f32 v[4:5], v[4:5], v[14:15]
	v_pk_mul_f32 v[0:1], v[0:1], v[10:11]
	v_pk_mul_f32 v[4:5], v[36:37], v[4:5] op_sel_hi:[0,1]
	v_pk_mul_f32 v[10:11], v[36:37], v[2:3] op_sel_hi:[0,1]
	v_pk_mul_f32 v[2:3], v[36:37], v[0:1] op_sel_hi:[0,1]
	v_bfe_u32 v0, v4, 16, 1
	v_pk_mul_f32 v[6:7], v[6:7], v[16:17]
	v_add3_u32 v0, v4, v0, s77
	v_bfe_u32 v1, v5, 16, 1
	v_pk_mul_f32 v[6:7], v[36:37], v[6:7] op_sel_hi:[0,1]
	v_lshrrev_b32_e32 v0, 16, v0
	v_add3_u32 v1, v5, v1, s77
	v_and_or_b32 v0, v1, s4, v0
	v_bfe_u32 v1, v6, 16, 1
	v_add3_u32 v1, v6, v1, s77
	v_bfe_u32 v4, v7, 16, 1
	v_lshrrev_b32_e32 v1, 16, v1
	v_add3_u32 v4, v7, v4, s77
	v_and_or_b32 v1, v4, s4, v1
	v_bfe_u32 v4, v2, 16, 1
	v_add3_u32 v2, v2, v4, s77
	v_bfe_u32 v4, v3, 16, 1
	v_lshrrev_b32_e32 v2, 16, v2
	v_add3_u32 v3, v3, v4, s77
	v_and_or_b32 v2, v3, s4, v2
	v_bfe_u32 v3, v10, 16, 1
	v_add3_u32 v3, v10, v3, s77
	v_bfe_u32 v4, v11, 16, 1
	v_lshrrev_b32_e32 v3, 16, v3
	v_add3_u32 v4, v11, v4, s77
	v_and_or_b32 v3, v4, s4, v3
	global_store_dwordx4 v[8:9], v[0:3], off offset:3072
	s_branch .LBB0_288
	s_nop 0

.Lslot_w_done:
	s_mov_b64 s[8:9], s[0:1]
	s_getreg_b32 s4, hwreg(HW_REG_XCC_ID, 0, 4)
	s_waitcnt vmcnt(0)
	s_waitcnt vmcnt(0)
	s_barrier
	s_and_saveexec_b64 s[6:7], s[46:47]
	s_cbranch_execz .LBB0_414
	v_readlane_b32 s5, v254, 27
	s_load_dwordx2 s[8:9], s[8:9], 0x100
	s_waitcnt vmcnt(0) expcnt(0) lgkmcnt(0)
	v_mov_b32_e32 v0, s5
	ds_read_b32 v2, v0
	v_readlane_b32 s5, v254, 28
	s_and_b32 s4, s4, 15
	s_waitcnt lgkmcnt(0)
	v_cmp_ne_u32_e32 vcc, 0, v2
	v_mov_b32_e32 v0, s5
	ds_read_b32 v0, v0
	s_cbranch_vccnz .LBB0_378
	s_add_u32 s10, s8, 0x1200
	s_addc_u32 s11, s9, 0
	s_add_u32 s12, s8, 0x1400
	s_addc_u32 s13, s9, 0
	s_add_u32 s14, s8, 0x1500
	s_addc_u32 s15, s9, 0
	s_add_u32 s16, s8, 0x1600
	s_addc_u32 s17, s9, 0
	s_add_u32 s18, s8, 0x1700
	s_addc_u32 s19, s9, 0
	s_add_u32 s20, s8, 0x1800
	s_addc_u32 s21, s9, 0
	s_add_u32 s22, s8, 0x1900
	s_addc_u32 s23, s9, 0
	s_add_u32 s24, s8, 0x1a00
	s_addc_u32 s25, s9, 0
	s_add_u32 s26, s8, 0x1b00
	s_addc_u32 s27, s9, 0
	s_add_u32 s28, s8, 0x1c00
	s_addc_u32 s29, s9, 0
	s_add_u32 s30, s8, 0x1d00
	s_addc_u32 s31, s9, 0
	s_add_u32 s34, s8, 0x1e00
	s_addc_u32 s35, s9, 0
	s_add_u32 s36, s8, 0x1f00
	s_addc_u32 s37, s9, 0
	s_add_u32 s38, s8, 0x2000
	s_addc_u32 s39, s9, 0
	s_add_u32 s40, s8, 0x2100
	s_addc_u32 s41, s9, 0
	s_add_u32 s42, s8, 0x2200
	s_addc_u32 s43, s9, 0
	s_add_u32 s44, s8, 0x2300
	s_addc_u32 s45, s9, 0
	s_mov_b32 s5, 1
	s_branch .LBB0_366
	s_nop 0

.LBB0_453:
	s_add_u32 s12, s12, 0x1fa00600
	s_addc_u32 s13, s13, 0
	v_lshl_add_u32 v128, s19, 8, v138
	v_lshl_or_b32 v129, s28, 8, v139
	s_add_u32 s14, s10, 0x22a00000
	v_or_b32_e32 v132, s34, v129
	v_ashrrev_i32_e32 v129, 31, v128
	s_addc_u32 s15, s11, 0
	v_lshlrev_b64 v[130:131], 10, v[128:129]
	s_add_u32 s10, s16, s72
	v_lshl_add_u64 v[130:131], s[14:15], 0, v[130:131]
	v_lshlrev_b32_e32 v192, 1, v132
	s_addc_u32 s11, s17, s73
	v_lshl_add_u64 v[130:131], v[130:131], 0, v[192:193]
	v_lshlrev_b32_e32 v132, 2, v132
	v_mov_b64_e32 v[248:249], v[130:131]
	global_load_dwordx4 v[200:203], v132, s[10:11] offset:16
	global_load_dwordx4 v[204:207], v132, s[10:11]
	global_load_dwordx4 v[208:211], v132, s[10:11] offset:528
	global_load_dwordx4 v[240:243], v132, s[10:11] offset:512
	global_load_dwordx4 v[152:155], v[248:249], off
	global_load_dwordx4 v[156:159], v[248:249], off offset:256
	s_mov_b64 s[98:99], 0x4000
	v_lshl_add_u64 v[250:251], v[248:249], 0, s[98:99]
	global_load_dwordx4 v[160:163], v[250:251], off
	s_mov_b64 s[98:99], 0x4000
	v_lshl_add_u64 v[250:251], v[248:249], 0, s[98:99]
	global_load_dwordx4 v[164:167], v[250:251], off offset:256
	s_mov_b64 s[98:99], 0x8000
	v_lshl_add_u64 v[250:251], v[248:249], 0, s[98:99]
	global_load_dwordx4 v[168:171], v[250:251], off
	s_mov_b64 s[98:99], 0x8000
	v_lshl_add_u64 v[250:251], v[248:249], 0, s[98:99]
	global_load_dwordx4 v[172:175], v[250:251], off offset:256
	s_mov_b64 s[98:99], 0xc000
	v_lshl_add_u64 v[250:251], v[248:249], 0, s[98:99]
	global_load_dwordx4 v[176:179], v[250:251], off
	s_mov_b64 s[98:99], 0xc000
	v_lshl_add_u64 v[250:251], v[248:249], 0, s[98:99]
	global_load_dwordx4 v[180:183], v[250:251], off offset:256
	s_nop 1
	s_waitcnt vmcnt(7)
	v_mov_b64_e32 v[134:135], v[152:153]
	v_mov_b64_e32 v[136:137], v[154:155]
	v_mov_b64_e32 v[138:139], v[200:201]
	v_mov_b64_e32 v[140:141], v[202:203]
	v_mov_b64_e32 v[142:143], v[204:205]
	v_mov_b64_e32 v[144:145], v[206:207]
	v_add_f32_e32 v120, v120, v138
	v_add_f32_e32 v124, v124, v142
	v_add_f32_e32 v121, v121, v139
	v_add_f32_e32 v122, v122, v140
	v_mul_f32_e32 v124, 0xbfb8aa3b, v124
	v_mul_f32_e32 v120, 0xbfb8aa3b, v120
	v_mul_f32_e32 v121, 0xbfb8aa3b, v121
	v_mul_f32_e32 v122, 0xbfb8aa3b, v122
	v_exp_f32_e32 v124, v124
	v_exp_f32_e32 v120, v120
	v_exp_f32_e32 v121, v121
	v_exp_f32_e32 v122, v122
	v_add_f32_e32 v124, 1.0, v124
	v_add_f32_e32 v120, 1.0, v120
	v_add_f32_e32 v121, 1.0, v121
	v_add_f32_e32 v122, 1.0, v122
	v_rcp_f32_e32 v124, v124
	v_rcp_f32_e32 v120, v120
	v_rcp_f32_e32 v121, v121
	v_rcp_f32_e32 v122, v122
	v_lshlrev_b32_e32 v133, 16, v134
	v_lshlrev_b32_e32 v147, 16, v136
	v_and_b32_e32 v136, 0xffff0000, v136
	v_lshlrev_b32_e32 v148, 16, v137
	v_mul_f32_e32 v124, v124, v133
	v_mul_f32_e32 v133, v120, v147
	v_add_f32_e32 v120, v125, v143
	v_mul_f32_e32 v125, v121, v136
	v_add_f32_e32 v121, v126, v144
	v_mul_f32_e32 v126, v122, v148
	v_add_f32_e32 v122, v127, v145
	v_mul_f32_e32 v120, 0xbfb8aa3b, v120
	v_mul_f32_e32 v121, 0xbfb8aa3b, v121
	v_mul_f32_e32 v122, 0xbfb8aa3b, v122
	v_exp_f32_e32 v120, v120
	v_exp_f32_e32 v121, v121
	v_exp_f32_e32 v122, v122
	v_add_f32_e32 v123, v123, v141
	v_mul_f32_e32 v123, 0xbfb8aa3b, v123
	v_exp_f32_e32 v123, v123
	v_add_f32_e32 v120, 1.0, v120
	v_add_f32_e32 v121, 1.0, v121
	v_add_f32_e32 v122, 1.0, v122
	v_rcp_f32_e32 v120, v120
	v_rcp_f32_e32 v121, v121
	v_rcp_f32_e32 v122, v122
	v_add_f32_e32 v123, 1.0, v123
	v_and_b32_e32 v134, 0xffff0000, v134
	v_lshlrev_b32_e32 v146, 16, v135
	v_and_b32_e32 v135, 0xffff0000, v135
	v_rcp_f32_e32 v123, v123
	v_mul_f32_e32 v120, v120, v134
	v_mul_f32_e32 v121, v121, v146
	v_mul_f32_e32 v122, v122, v135
	v_cvt_pk_bf16_f32 v120, v124, v120
	v_cvt_pk_bf16_f32 v121, v121, v122
	v_cvt_pk_bf16_f32 v122, v133, v125
	v_lshlrev_b64 v[124:125], 12, v[128:129]
	v_and_b32_e32 v137, 0xffff0000, v137
	v_lshl_add_u64 v[124:125], s[12:13], 0, v[124:125]
	v_mul_f32_e32 v123, v123, v137
	v_lshl_add_u64 v[124:125], v[124:125], 0, v[192:193]
	v_cvt_pk_bf16_f32 v123, v126, v123
	global_store_dwordx4 v[124:125], v[120:123], off
	s_mov_b64 s[98:99], 0x20000
	v_lshl_add_u64 v[250:251], v[248:249], 0, s[98:99]
	global_load_dwordx4 v[152:155], v[250:251], off
	s_nop 1
	s_waitcnt vmcnt(8)
	v_mov_b64_e32 v[120:121], v[156:157]
	v_mov_b64_e32 v[122:123], v[158:159]
	s_nop 0
	v_mov_b64_e32 v[134:135], v[208:209]
	v_mov_b64_e32 v[136:137], v[210:211]
	v_mov_b64_e32 v[138:139], v[240:241]
	v_mov_b64_e32 v[140:141], v[242:243]
	v_lshlrev_b32_e32 v126, 16, v120
	v_add_f32_e32 v112, v112, v134
	v_add_f32_e32 v116, v116, v138
	v_add_f32_e32 v113, v113, v135
	v_add_f32_e32 v114, v114, v136
	v_mul_f32_e32 v116, 0xbfb8aa3b, v116
	v_mul_f32_e32 v112, 0xbfb8aa3b, v112
	v_mul_f32_e32 v113, 0xbfb8aa3b, v113
	v_mul_f32_e32 v114, 0xbfb8aa3b, v114
	v_exp_f32_e32 v116, v116
	v_exp_f32_e32 v112, v112
	v_exp_f32_e32 v113, v113
	v_exp_f32_e32 v114, v114
	v_add_f32_e32 v116, 1.0, v116
	v_add_f32_e32 v112, 1.0, v112
	v_add_f32_e32 v113, 1.0, v113
	v_add_f32_e32 v114, 1.0, v114
	v_rcp_f32_e32 v116, v116
	v_rcp_f32_e32 v112, v112
	v_rcp_f32_e32 v113, v113
	v_rcp_f32_e32 v114, v114
	v_lshlrev_b32_e32 v129, 16, v122
	v_and_b32_e32 v122, 0xffff0000, v122
	v_lshlrev_b32_e32 v130, 16, v123
	v_mul_f32_e32 v116, v116, v126
	v_mul_f32_e32 v126, v112, v129
	v_add_f32_e32 v112, v117, v139
	v_mul_f32_e32 v117, v113, v122
	v_add_f32_e32 v113, v118, v140
	v_mul_f32_e32 v118, v114, v130
	v_add_f32_e32 v114, v119, v141
	v_mul_f32_e32 v112, 0xbfb8aa3b, v112
	v_mul_f32_e32 v113, 0xbfb8aa3b, v113
	v_add_f32_e32 v115, v115, v137
	v_mul_f32_e32 v114, 0xbfb8aa3b, v114
	v_exp_f32_e32 v112, v112
	v_exp_f32_e32 v113, v113
	v_exp_f32_e32 v114, v114
	v_mul_f32_e32 v115, 0xbfb8aa3b, v115
	v_exp_f32_e32 v115, v115
	v_add_f32_e32 v112, 1.0, v112
	v_add_f32_e32 v113, 1.0, v113
	v_add_f32_e32 v114, 1.0, v114
	v_rcp_f32_e32 v112, v112
	v_rcp_f32_e32 v113, v113
	v_rcp_f32_e32 v114, v114
	v_add_f32_e32 v115, 1.0, v115
	v_rcp_f32_e32 v115, v115
	v_and_b32_e32 v120, 0xffff0000, v120
	v_lshlrev_b32_e32 v127, 16, v121
	v_and_b32_e32 v121, 0xffff0000, v121
	v_and_b32_e32 v123, 0xffff0000, v123
	v_mul_f32_e32 v112, v112, v120
	v_mul_f32_e32 v113, v113, v127
	v_mul_f32_e32 v114, v114, v121
	v_mul_f32_e32 v115, v115, v123
	v_cvt_pk_bf16_f32 v112, v116, v112
	v_cvt_pk_bf16_f32 v113, v113, v114
	v_cvt_pk_bf16_f32 v114, v126, v117
	v_cvt_pk_bf16_f32 v115, v118, v115
	global_store_dwordx4 v[124:125], v[112:115], off offset:256
	s_mov_b64 s[98:99], 0x20000
	v_lshl_add_u64 v[250:251], v[248:249], 0, s[98:99]
	global_load_dwordx4 v[156:159], v[250:251], off offset:256
	s_nop 1
	v_or_b32_e32 v114, 16, v128
	v_ashrrev_i32_e32 v115, 31, v114
	v_lshlrev_b64 v[112:113], 10, v[114:115]
	v_lshl_add_u64 v[112:113], s[14:15], 0, v[112:113]
	v_lshl_add_u64 v[112:113], v[112:113], 0, v[192:193]
	s_nop 1
	s_waitcnt vmcnt(9)
	v_mov_b64_e32 v[116:117], v[160:161]
	v_mov_b64_e32 v[118:119], v[162:163]
	v_mov_b64_e32 v[120:121], v[200:201]
	v_mov_b64_e32 v[122:123], v[202:203]
	v_mov_b64_e32 v[124:125], v[204:205]
	v_mov_b64_e32 v[126:127], v[206:207]
	v_lshlrev_b32_e32 v131, 16, v118
	v_add_f32_e32 v104, v104, v120
	v_add_f32_e32 v105, v105, v121
	v_add_f32_e32 v106, v106, v122
	v_mul_f32_e32 v104, 0xbfb8aa3b, v104
	v_mul_f32_e32 v105, 0xbfb8aa3b, v105
	v_mul_f32_e32 v106, 0xbfb8aa3b, v106
	v_exp_f32_e32 v104, v104
	v_exp_f32_e32 v105, v105
	v_exp_f32_e32 v106, v106
	v_and_b32_e32 v118, 0xffff0000, v118
	v_add_f32_e32 v104, 1.0, v104
	v_add_f32_e32 v105, 1.0, v105
	v_add_f32_e32 v106, 1.0, v106
	v_rcp_f32_e32 v104, v104
	v_rcp_f32_e32 v105, v105
	v_rcp_f32_e32 v106, v106
	v_lshlrev_b32_e32 v133, 16, v119
	v_add_f32_e32 v108, v108, v124
	v_mul_f32_e32 v120, v104, v131
	v_add_f32_e32 v104, v109, v125
	v_mul_f32_e32 v109, v105, v118
	v_add_f32_e32 v105, v110, v126
	v_mul_f32_e32 v110, v106, v133
	v_add_f32_e32 v106, v111, v127
	v_mul_f32_e32 v108, 0xbfb8aa3b, v108
	v_mul_f32_e32 v104, 0xbfb8aa3b, v104
	v_mul_f32_e32 v105, 0xbfb8aa3b, v105
	v_mul_f32_e32 v106, 0xbfb8aa3b, v106
	v_exp_f32_e32 v108, v108
	v_exp_f32_e32 v104, v104
	v_exp_f32_e32 v105, v105
	v_exp_f32_e32 v106, v106
	v_add_f32_e32 v107, v107, v123
	v_mul_f32_e32 v107, 0xbfb8aa3b, v107
	v_exp_f32_e32 v107, v107
	v_add_f32_e32 v108, 1.0, v108
	v_add_f32_e32 v104, 1.0, v104
	v_add_f32_e32 v105, 1.0, v105
	v_add_f32_e32 v106, 1.0, v106
	v_rcp_f32_e32 v108, v108
	v_rcp_f32_e32 v104, v104
	v_rcp_f32_e32 v105, v105
	v_rcp_f32_e32 v106, v106
	v_add_f32_e32 v107, 1.0, v107
	v_lshlrev_b32_e32 v129, 16, v116
	v_and_b32_e32 v116, 0xffff0000, v116
	v_lshlrev_b32_e32 v130, 16, v117
	v_and_b32_e32 v117, 0xffff0000, v117
	v_rcp_f32_e32 v107, v107
	v_mul_f32_e32 v108, v108, v129
	v_mul_f32_e32 v104, v104, v116
	v_mul_f32_e32 v105, v105, v130
	v_mul_f32_e32 v106, v106, v117
	v_cvt_pk_bf16_f32 v104, v108, v104
	v_cvt_pk_bf16_f32 v105, v105, v106
	v_cvt_pk_bf16_f32 v106, v120, v109
	v_lshlrev_b64 v[108:109], 12, v[114:115]
	v_and_b32_e32 v119, 0xffff0000, v119
	v_lshl_add_u64 v[108:109], s[12:13], 0, v[108:109]
	v_mul_f32_e32 v107, v107, v119
	v_lshl_add_u64 v[108:109], v[108:109], 0, v[192:193]
	v_cvt_pk_bf16_f32 v107, v110, v107
	global_store_dwordx4 v[108:109], v[104:107], off
	s_mov_b64 s[98:99], 0x24000
	v_lshl_add_u64 v[250:251], v[248:249], 0, s[98:99]
	global_load_dwordx4 v[160:163], v[250:251], off
	s_nop 1
	s_waitcnt vmcnt(10)
	v_mov_b64_e32 v[104:105], v[164:165]
	v_mov_b64_e32 v[106:107], v[166:167]
	s_nop 0
	v_mov_b64_e32 v[110:111], v[208:209]
	v_mov_b64_e32 v[112:113], v[210:211]
	v_mov_b64_e32 v[114:115], v[240:241]
	v_mov_b64_e32 v[116:117], v[242:243]
	v_lshlrev_b32_e32 v120, 16, v106
	v_add_f32_e32 v96, v96, v110
	v_add_f32_e32 v97, v97, v111
	v_add_f32_e32 v98, v98, v112
	v_mul_f32_e32 v96, 0xbfb8aa3b, v96
	v_mul_f32_e32 v97, 0xbfb8aa3b, v97
	v_mul_f32_e32 v98, 0xbfb8aa3b, v98
	v_exp_f32_e32 v96, v96
	v_exp_f32_e32 v97, v97
	v_exp_f32_e32 v98, v98
	v_and_b32_e32 v106, 0xffff0000, v106
	v_add_f32_e32 v96, 1.0, v96
	v_add_f32_e32 v97, 1.0, v97
	v_add_f32_e32 v98, 1.0, v98
	v_rcp_f32_e32 v96, v96
	v_rcp_f32_e32 v97, v97
	v_rcp_f32_e32 v98, v98
	v_lshlrev_b32_e32 v121, 16, v107
	v_mul_f32_e32 v110, v96, v120
	v_add_f32_e32 v96, v101, v115
	v_mul_f32_e32 v101, v97, v106
	v_add_f32_e32 v97, v102, v116
	v_mul_f32_e32 v102, v98, v121
	v_add_f32_e32 v98, v103, v117
	v_add_f32_e32 v100, v100, v114
	v_mul_f32_e32 v96, 0xbfb8aa3b, v96
	v_mul_f32_e32 v97, 0xbfb8aa3b, v97
	v_add_f32_e32 v99, v99, v113
	v_mul_f32_e32 v98, 0xbfb8aa3b, v98
	v_mul_f32_e32 v100, 0xbfb8aa3b, v100
	v_exp_f32_e32 v96, v96
	v_exp_f32_e32 v97, v97
	v_exp_f32_e32 v98, v98
	v_mul_f32_e32 v99, 0xbfb8aa3b, v99
	v_exp_f32_e32 v100, v100
	v_exp_f32_e32 v99, v99
	v_add_f32_e32 v96, 1.0, v96
	v_add_f32_e32 v97, 1.0, v97
	v_add_f32_e32 v98, 1.0, v98
	v_add_f32_e32 v100, 1.0, v100
	v_rcp_f32_e32 v96, v96
	v_rcp_f32_e32 v97, v97
	v_rcp_f32_e32 v98, v98
	v_add_f32_e32 v99, 1.0, v99
	v_rcp_f32_e32 v100, v100
	v_rcp_f32_e32 v99, v99
	v_lshlrev_b32_e32 v118, 16, v104
	v_and_b32_e32 v104, 0xffff0000, v104
	v_lshlrev_b32_e32 v119, 16, v105
	v_and_b32_e32 v105, 0xffff0000, v105
	v_and_b32_e32 v107, 0xffff0000, v107
	v_mul_f32_e32 v96, v96, v104
	v_mul_f32_e32 v97, v97, v119
	v_mul_f32_e32 v98, v98, v105
	v_mul_f32_e32 v100, v100, v118
	v_mul_f32_e32 v99, v99, v107
	v_cvt_pk_bf16_f32 v96, v100, v96
	v_cvt_pk_bf16_f32 v97, v97, v98
	v_cvt_pk_bf16_f32 v98, v110, v101
	v_cvt_pk_bf16_f32 v99, v102, v99
	global_store_dwordx4 v[108:109], v[96:99], off offset:256
	s_mov_b64 s[98:99], 0x24000
	v_lshl_add_u64 v[250:251], v[248:249], 0, s[98:99]
	global_load_dwordx4 v[164:167], v[250:251], off offset:256
	s_nop 1
	v_or_b32_e32 v98, 32, v128
	v_ashrrev_i32_e32 v99, 31, v98
	v_lshlrev_b64 v[96:97], 10, v[98:99]
	v_lshl_add_u64 v[96:97], s[14:15], 0, v[96:97]
	v_lshl_add_u64 v[96:97], v[96:97], 0, v[192:193]
	s_nop 1
	s_waitcnt vmcnt(11)
	v_mov_b64_e32 v[100:101], v[168:169]
	v_mov_b64_e32 v[102:103], v[170:171]
	v_mov_b64_e32 v[104:105], v[200:201]
	v_mov_b64_e32 v[106:107], v[202:203]
	v_mov_b64_e32 v[108:109], v[204:205]
	v_mov_b64_e32 v[110:111], v[206:207]
	v_lshlrev_b32_e32 v114, 16, v102
	v_add_f32_e32 v88, v88, v104
	v_add_f32_e32 v89, v89, v105
	v_add_f32_e32 v90, v90, v106
	v_mul_f32_e32 v88, 0xbfb8aa3b, v88
	v_mul_f32_e32 v89, 0xbfb8aa3b, v89
	v_mul_f32_e32 v90, 0xbfb8aa3b, v90
	v_exp_f32_e32 v88, v88
	v_exp_f32_e32 v89, v89
	v_exp_f32_e32 v90, v90
	v_and_b32_e32 v102, 0xffff0000, v102
	v_add_f32_e32 v88, 1.0, v88
	v_add_f32_e32 v89, 1.0, v89
	v_add_f32_e32 v90, 1.0, v90
	v_rcp_f32_e32 v88, v88
	v_rcp_f32_e32 v89, v89
	v_rcp_f32_e32 v90, v90
	v_lshlrev_b32_e32 v115, 16, v103
	v_add_f32_e32 v92, v92, v108
	v_mul_f32_e32 v104, v88, v114
	v_add_f32_e32 v88, v93, v109
	v_mul_f32_e32 v93, v89, v102
	v_add_f32_e32 v89, v94, v110
	v_mul_f32_e32 v94, v90, v115
	v_add_f32_e32 v90, v95, v111
	v_mul_f32_e32 v92, 0xbfb8aa3b, v92
	v_mul_f32_e32 v88, 0xbfb8aa3b, v88
	v_mul_f32_e32 v89, 0xbfb8aa3b, v89
	v_mul_f32_e32 v90, 0xbfb8aa3b, v90
	v_exp_f32_e32 v92, v92
	v_exp_f32_e32 v88, v88
	v_exp_f32_e32 v89, v89
	v_exp_f32_e32 v90, v90
	v_add_f32_e32 v91, v91, v107
	v_mul_f32_e32 v91, 0xbfb8aa3b, v91
	v_exp_f32_e32 v91, v91
	v_add_f32_e32 v92, 1.0, v92
	v_add_f32_e32 v88, 1.0, v88
	v_add_f32_e32 v89, 1.0, v89
	v_add_f32_e32 v90, 1.0, v90
	v_rcp_f32_e32 v92, v92
	v_rcp_f32_e32 v88, v88
	v_rcp_f32_e32 v89, v89
	v_rcp_f32_e32 v90, v90
	v_add_f32_e32 v91, 1.0, v91
	v_lshlrev_b32_e32 v112, 16, v100
	v_and_b32_e32 v100, 0xffff0000, v100
	v_lshlrev_b32_e32 v113, 16, v101
	v_and_b32_e32 v101, 0xffff0000, v101
	v_rcp_f32_e32 v91, v91
	v_mul_f32_e32 v92, v92, v112
	v_mul_f32_e32 v88, v88, v100
	v_mul_f32_e32 v89, v89, v113
	v_mul_f32_e32 v90, v90, v101
	v_cvt_pk_bf16_f32 v88, v92, v88
	v_cvt_pk_bf16_f32 v89, v89, v90
	v_cvt_pk_bf16_f32 v90, v104, v93
	v_lshlrev_b64 v[92:93], 12, v[98:99]
	v_and_b32_e32 v103, 0xffff0000, v103
	v_lshl_add_u64 v[92:93], s[12:13], 0, v[92:93]
	v_mul_f32_e32 v91, v91, v103
	v_lshl_add_u64 v[92:93], v[92:93], 0, v[192:193]
	v_cvt_pk_bf16_f32 v91, v94, v91
	global_store_dwordx4 v[92:93], v[88:91], off
	s_mov_b64 s[98:99], 0x28000
	v_lshl_add_u64 v[250:251], v[248:249], 0, s[98:99]
	global_load_dwordx4 v[168:171], v[250:251], off
	s_nop 1
	s_waitcnt vmcnt(12)
	v_mov_b64_e32 v[88:89], v[172:173]
	v_mov_b64_e32 v[90:91], v[174:175]
	s_nop 0
	v_mov_b64_e32 v[94:95], v[208:209]
	v_mov_b64_e32 v[96:97], v[210:211]
	v_mov_b64_e32 v[98:99], v[240:241]
	v_mov_b64_e32 v[100:101], v[242:243]
	v_lshlrev_b32_e32 v104, 16, v90
	v_add_f32_e32 v80, v80, v94
	v_add_f32_e32 v81, v81, v95
	v_add_f32_e32 v82, v82, v96
	v_mul_f32_e32 v80, 0xbfb8aa3b, v80
	v_mul_f32_e32 v81, 0xbfb8aa3b, v81
	v_mul_f32_e32 v82, 0xbfb8aa3b, v82
	v_exp_f32_e32 v80, v80
	v_exp_f32_e32 v81, v81
	v_exp_f32_e32 v82, v82
	v_and_b32_e32 v90, 0xffff0000, v90
	v_add_f32_e32 v80, 1.0, v80
	v_add_f32_e32 v81, 1.0, v81
	v_add_f32_e32 v82, 1.0, v82
	v_rcp_f32_e32 v80, v80
	v_rcp_f32_e32 v81, v81
	v_rcp_f32_e32 v82, v82
	v_lshlrev_b32_e32 v105, 16, v91
	v_mul_f32_e32 v94, v80, v104
	v_add_f32_e32 v80, v85, v99
	v_mul_f32_e32 v85, v81, v90
	v_add_f32_e32 v81, v86, v100
	v_mul_f32_e32 v86, v82, v105
	v_add_f32_e32 v82, v87, v101
	v_add_f32_e32 v84, v84, v98
	v_mul_f32_e32 v80, 0xbfb8aa3b, v80
	v_mul_f32_e32 v81, 0xbfb8aa3b, v81
	v_add_f32_e32 v83, v83, v97
	v_mul_f32_e32 v82, 0xbfb8aa3b, v82
	v_mul_f32_e32 v84, 0xbfb8aa3b, v84
	v_exp_f32_e32 v80, v80
	v_exp_f32_e32 v81, v81
	v_exp_f32_e32 v82, v82
	v_mul_f32_e32 v83, 0xbfb8aa3b, v83
	v_exp_f32_e32 v84, v84
	v_exp_f32_e32 v83, v83
	v_add_f32_e32 v80, 1.0, v80
	v_add_f32_e32 v81, 1.0, v81
	v_add_f32_e32 v82, 1.0, v82
	v_add_f32_e32 v84, 1.0, v84
	v_rcp_f32_e32 v80, v80
	v_rcp_f32_e32 v81, v81
	v_rcp_f32_e32 v82, v82
	v_add_f32_e32 v83, 1.0, v83
	v_rcp_f32_e32 v84, v84
	v_rcp_f32_e32 v83, v83
	v_lshlrev_b32_e32 v102, 16, v88
	v_and_b32_e32 v88, 0xffff0000, v88
	v_lshlrev_b32_e32 v103, 16, v89
	v_and_b32_e32 v89, 0xffff0000, v89
	v_and_b32_e32 v91, 0xffff0000, v91
	v_mul_f32_e32 v80, v80, v88
	v_mul_f32_e32 v81, v81, v103
	v_mul_f32_e32 v82, v82, v89
	v_mul_f32_e32 v84, v84, v102
	v_mul_f32_e32 v83, v83, v91
	v_cvt_pk_bf16_f32 v80, v84, v80
	v_cvt_pk_bf16_f32 v81, v81, v82
	v_cvt_pk_bf16_f32 v82, v94, v85
	v_cvt_pk_bf16_f32 v83, v86, v83
	global_store_dwordx4 v[92:93], v[80:83], off offset:256
	s_mov_b64 s[98:99], 0x28000
	v_lshl_add_u64 v[250:251], v[248:249], 0, s[98:99]
	global_load_dwordx4 v[172:175], v[250:251], off offset:256
	s_nop 1
	v_or_b32_e32 v82, 48, v128
	v_ashrrev_i32_e32 v83, 31, v82
	v_lshlrev_b64 v[80:81], 10, v[82:83]
	v_lshl_add_u64 v[80:81], s[14:15], 0, v[80:81]
	v_lshl_add_u64 v[80:81], v[80:81], 0, v[192:193]
	s_nop 1
	s_waitcnt vmcnt(13)
	v_mov_b64_e32 v[84:85], v[176:177]
	v_mov_b64_e32 v[86:87], v[178:179]
	v_mov_b64_e32 v[88:89], v[200:201]
	v_mov_b64_e32 v[90:91], v[202:203]
	v_mov_b64_e32 v[92:93], v[204:205]
	v_mov_b64_e32 v[94:95], v[206:207]
	v_lshlrev_b32_e32 v98, 16, v86
	v_add_f32_e32 v72, v72, v88
	v_add_f32_e32 v73, v73, v89
	v_add_f32_e32 v74, v74, v90
	v_mul_f32_e32 v72, 0xbfb8aa3b, v72
	v_mul_f32_e32 v73, 0xbfb8aa3b, v73
	v_mul_f32_e32 v74, 0xbfb8aa3b, v74
	v_exp_f32_e32 v72, v72
	v_exp_f32_e32 v73, v73
	v_exp_f32_e32 v74, v74
	v_and_b32_e32 v86, 0xffff0000, v86
	v_add_f32_e32 v72, 1.0, v72
	v_add_f32_e32 v73, 1.0, v73
	v_add_f32_e32 v74, 1.0, v74
	v_rcp_f32_e32 v72, v72
	v_rcp_f32_e32 v73, v73
	v_rcp_f32_e32 v74, v74
	v_lshlrev_b32_e32 v99, 16, v87
	v_add_f32_e32 v76, v76, v92
	v_mul_f32_e32 v88, v72, v98
	v_add_f32_e32 v72, v77, v93
	v_mul_f32_e32 v77, v73, v86
	v_add_f32_e32 v73, v78, v94
	v_mul_f32_e32 v78, v74, v99
	v_add_f32_e32 v74, v79, v95
	v_mul_f32_e32 v76, 0xbfb8aa3b, v76
	v_mul_f32_e32 v72, 0xbfb8aa3b, v72
	v_mul_f32_e32 v73, 0xbfb8aa3b, v73
	v_mul_f32_e32 v74, 0xbfb8aa3b, v74
	v_exp_f32_e32 v76, v76
	v_exp_f32_e32 v72, v72
	v_exp_f32_e32 v73, v73
	v_exp_f32_e32 v74, v74
	v_add_f32_e32 v75, v75, v91
	v_mul_f32_e32 v75, 0xbfb8aa3b, v75
	v_exp_f32_e32 v75, v75
	v_add_f32_e32 v76, 1.0, v76
	v_add_f32_e32 v72, 1.0, v72
	v_add_f32_e32 v73, 1.0, v73
	v_add_f32_e32 v74, 1.0, v74
	v_rcp_f32_e32 v76, v76
	v_rcp_f32_e32 v72, v72
	v_rcp_f32_e32 v73, v73
	v_rcp_f32_e32 v74, v74
	v_add_f32_e32 v75, 1.0, v75
	v_lshlrev_b32_e32 v96, 16, v84
	v_and_b32_e32 v84, 0xffff0000, v84
	v_lshlrev_b32_e32 v97, 16, v85
	v_and_b32_e32 v85, 0xffff0000, v85
	v_rcp_f32_e32 v75, v75
	v_mul_f32_e32 v76, v76, v96
	v_mul_f32_e32 v72, v72, v84
	v_mul_f32_e32 v73, v73, v97
	v_mul_f32_e32 v74, v74, v85
	v_cvt_pk_bf16_f32 v72, v76, v72
	v_cvt_pk_bf16_f32 v73, v73, v74
	v_cvt_pk_bf16_f32 v74, v88, v77
	v_lshlrev_b64 v[76:77], 12, v[82:83]
	v_and_b32_e32 v87, 0xffff0000, v87
	v_lshl_add_u64 v[76:77], s[12:13], 0, v[76:77]
	v_mul_f32_e32 v75, v75, v87
	v_lshl_add_u64 v[76:77], v[76:77], 0, v[192:193]
	v_cvt_pk_bf16_f32 v75, v78, v75
	global_store_dwordx4 v[76:77], v[72:75], off
	s_mov_b64 s[98:99], 0x2c000
	v_lshl_add_u64 v[250:251], v[248:249], 0, s[98:99]
	global_load_dwordx4 v[176:179], v[250:251], off
	s_nop 1
	s_waitcnt vmcnt(14)
	v_mov_b64_e32 v[72:73], v[180:181]
	v_mov_b64_e32 v[74:75], v[182:183]
	s_nop 0
	v_mov_b64_e32 v[78:79], v[208:209]
	v_mov_b64_e32 v[80:81], v[210:211]
	v_mov_b64_e32 v[82:83], v[240:241]
	v_mov_b64_e32 v[84:85], v[242:243]
	v_lshlrev_b32_e32 v88, 16, v74
	v_add_f32_e32 v64, v64, v78
	v_add_f32_e32 v65, v65, v79
	v_add_f32_e32 v66, v66, v80
	v_mul_f32_e32 v64, 0xbfb8aa3b, v64
	v_mul_f32_e32 v65, 0xbfb8aa3b, v65
	v_mul_f32_e32 v66, 0xbfb8aa3b, v66
	v_exp_f32_e32 v64, v64
	v_exp_f32_e32 v65, v65
	v_exp_f32_e32 v66, v66
	v_and_b32_e32 v74, 0xffff0000, v74
	v_add_f32_e32 v64, 1.0, v64
	v_add_f32_e32 v65, 1.0, v65
	v_add_f32_e32 v66, 1.0, v66
	v_rcp_f32_e32 v64, v64
	v_rcp_f32_e32 v65, v65
	v_rcp_f32_e32 v66, v66
	v_lshlrev_b32_e32 v89, 16, v75
	v_mul_f32_e32 v78, v64, v88
	v_add_f32_e32 v64, v69, v83
	v_mul_f32_e32 v69, v65, v74
	v_add_f32_e32 v65, v70, v84
	v_mul_f32_e32 v70, v66, v89
	v_add_f32_e32 v66, v71, v85
	v_add_f32_e32 v68, v68, v82
	v_mul_f32_e32 v64, 0xbfb8aa3b, v64
	v_mul_f32_e32 v65, 0xbfb8aa3b, v65
	v_add_f32_e32 v67, v67, v81
	v_mul_f32_e32 v66, 0xbfb8aa3b, v66
	v_mul_f32_e32 v68, 0xbfb8aa3b, v68
	v_exp_f32_e32 v64, v64
	v_exp_f32_e32 v65, v65
	v_exp_f32_e32 v66, v66
	v_mul_f32_e32 v67, 0xbfb8aa3b, v67
	v_exp_f32_e32 v68, v68
	v_exp_f32_e32 v67, v67
	v_add_f32_e32 v64, 1.0, v64
	v_add_f32_e32 v65, 1.0, v65
	v_add_f32_e32 v66, 1.0, v66
	v_add_f32_e32 v68, 1.0, v68
	v_rcp_f32_e32 v64, v64
	v_rcp_f32_e32 v65, v65
	v_rcp_f32_e32 v66, v66
	v_add_f32_e32 v67, 1.0, v67
	v_rcp_f32_e32 v68, v68
	v_rcp_f32_e32 v67, v67
	v_lshlrev_b32_e32 v86, 16, v72
	v_and_b32_e32 v72, 0xffff0000, v72
	v_lshlrev_b32_e32 v87, 16, v73
	v_and_b32_e32 v73, 0xffff0000, v73
	v_and_b32_e32 v75, 0xffff0000, v75
	v_mul_f32_e32 v64, v64, v72
	v_mul_f32_e32 v65, v65, v87
	v_mul_f32_e32 v66, v66, v73
	v_mul_f32_e32 v68, v68, v86
	v_mul_f32_e32 v67, v67, v75
	v_cvt_pk_bf16_f32 v64, v68, v64
	v_cvt_pk_bf16_f32 v65, v65, v66
	v_cvt_pk_bf16_f32 v66, v78, v69
	v_cvt_pk_bf16_f32 v67, v70, v67
	global_store_dwordx4 v[76:77], v[64:67], off offset:256
	s_mov_b64 s[98:99], 0x2c000
	v_lshl_add_u64 v[250:251], v[248:249], 0, s[98:99]
	global_load_dwordx4 v[180:183], v[250:251], off offset:256
	s_nop 1
	v_add_u32_e32 v66, 0x80, v128
	v_ashrrev_i32_e32 v67, 31, v66
	v_lshlrev_b64 v[64:65], 10, v[66:67]
	v_lshl_add_u64 v[64:65], s[14:15], 0, v[64:65]
	v_lshl_add_u64 v[64:65], v[64:65], 0, v[192:193]
	s_nop 1
	s_waitcnt vmcnt(14)
	v_mov_b64_e32 v[68:69], v[152:153]
	v_mov_b64_e32 v[70:71], v[154:155]
	v_mov_b64_e32 v[72:73], v[200:201]
	v_mov_b64_e32 v[74:75], v[202:203]
	v_mov_b64_e32 v[76:77], v[204:205]
	v_mov_b64_e32 v[78:79], v[206:207]
	v_lshlrev_b32_e32 v82, 16, v70
	v_add_f32_e32 v56, v56, v72
	v_add_f32_e32 v57, v57, v73
	v_add_f32_e32 v58, v58, v74
	v_mul_f32_e32 v56, 0xbfb8aa3b, v56
	v_mul_f32_e32 v57, 0xbfb8aa3b, v57
	v_mul_f32_e32 v58, 0xbfb8aa3b, v58
	v_exp_f32_e32 v56, v56
	v_exp_f32_e32 v57, v57
	v_exp_f32_e32 v58, v58
	v_and_b32_e32 v70, 0xffff0000, v70
	v_add_f32_e32 v56, 1.0, v56
	v_add_f32_e32 v57, 1.0, v57
	v_add_f32_e32 v58, 1.0, v58
	v_rcp_f32_e32 v56, v56
	v_rcp_f32_e32 v57, v57
	v_rcp_f32_e32 v58, v58
	v_lshlrev_b32_e32 v83, 16, v71
	v_add_f32_e32 v60, v60, v76
	v_mul_f32_e32 v72, v56, v82
	v_add_f32_e32 v56, v61, v77
	v_mul_f32_e32 v61, v57, v70
	v_add_f32_e32 v57, v62, v78
	v_mul_f32_e32 v62, v58, v83
	v_add_f32_e32 v58, v63, v79
	v_mul_f32_e32 v60, 0xbfb8aa3b, v60
	v_mul_f32_e32 v56, 0xbfb8aa3b, v56
	v_mul_f32_e32 v57, 0xbfb8aa3b, v57
	v_mul_f32_e32 v58, 0xbfb8aa3b, v58
	v_exp_f32_e32 v60, v60
	v_exp_f32_e32 v56, v56
	v_exp_f32_e32 v57, v57
	v_exp_f32_e32 v58, v58
	v_add_f32_e32 v59, v59, v75
	v_mul_f32_e32 v59, 0xbfb8aa3b, v59
	v_exp_f32_e32 v59, v59
	v_add_f32_e32 v60, 1.0, v60
	v_add_f32_e32 v56, 1.0, v56
	v_add_f32_e32 v57, 1.0, v57
	v_add_f32_e32 v58, 1.0, v58
	v_rcp_f32_e32 v60, v60
	v_rcp_f32_e32 v56, v56
	v_rcp_f32_e32 v57, v57
	v_rcp_f32_e32 v58, v58
	v_add_f32_e32 v59, 1.0, v59
	v_lshlrev_b32_e32 v80, 16, v68
	v_and_b32_e32 v68, 0xffff0000, v68
	v_lshlrev_b32_e32 v81, 16, v69
	v_and_b32_e32 v69, 0xffff0000, v69
	v_rcp_f32_e32 v59, v59
	v_mul_f32_e32 v60, v60, v80
	v_mul_f32_e32 v56, v56, v68
	v_mul_f32_e32 v57, v57, v81
	v_mul_f32_e32 v58, v58, v69
	v_cvt_pk_bf16_f32 v56, v60, v56
	v_cvt_pk_bf16_f32 v57, v57, v58
	v_cvt_pk_bf16_f32 v58, v72, v61
	v_lshlrev_b64 v[60:61], 12, v[66:67]
	v_and_b32_e32 v71, 0xffff0000, v71
	v_lshl_add_u64 v[60:61], s[12:13], 0, v[60:61]
	v_mul_f32_e32 v59, v59, v71
	v_lshl_add_u64 v[60:61], v[60:61], 0, v[192:193]
	v_cvt_pk_bf16_f32 v59, v62, v59
	global_store_dwordx4 v[60:61], v[56:59], off
	s_nop 1
	s_waitcnt vmcnt(13)
	v_mov_b64_e32 v[56:57], v[156:157]
	v_mov_b64_e32 v[58:59], v[158:159]
	s_nop 0
	v_mov_b64_e32 v[62:63], v[208:209]
	v_mov_b64_e32 v[64:65], v[210:211]
	v_mov_b64_e32 v[66:67], v[240:241]
	v_mov_b64_e32 v[68:69], v[242:243]
	v_lshlrev_b32_e32 v72, 16, v58
	v_add_f32_e32 v48, v48, v62
	v_add_f32_e32 v49, v49, v63
	v_add_f32_e32 v50, v50, v64
	v_mul_f32_e32 v48, 0xbfb8aa3b, v48
	v_mul_f32_e32 v49, 0xbfb8aa3b, v49
	v_mul_f32_e32 v50, 0xbfb8aa3b, v50
	v_exp_f32_e32 v48, v48
	v_exp_f32_e32 v49, v49
	v_exp_f32_e32 v50, v50
	v_and_b32_e32 v58, 0xffff0000, v58
	v_add_f32_e32 v48, 1.0, v48
	v_add_f32_e32 v49, 1.0, v49
	v_add_f32_e32 v50, 1.0, v50
	v_rcp_f32_e32 v48, v48
	v_rcp_f32_e32 v49, v49
	v_rcp_f32_e32 v50, v50
	v_lshlrev_b32_e32 v73, 16, v59
	v_mul_f32_e32 v62, v48, v72
	v_add_f32_e32 v48, v53, v67
	v_mul_f32_e32 v53, v49, v58
	v_add_f32_e32 v49, v54, v68
	v_mul_f32_e32 v54, v50, v73
	v_add_f32_e32 v50, v55, v69
	v_add_f32_e32 v52, v52, v66
	v_mul_f32_e32 v48, 0xbfb8aa3b, v48
	v_mul_f32_e32 v49, 0xbfb8aa3b, v49
	v_add_f32_e32 v51, v51, v65
	v_mul_f32_e32 v50, 0xbfb8aa3b, v50
	v_mul_f32_e32 v52, 0xbfb8aa3b, v52
	v_exp_f32_e32 v48, v48
	v_exp_f32_e32 v49, v49
	v_exp_f32_e32 v50, v50
	v_mul_f32_e32 v51, 0xbfb8aa3b, v51
	v_exp_f32_e32 v52, v52
	v_exp_f32_e32 v51, v51
	v_add_f32_e32 v48, 1.0, v48
	v_add_f32_e32 v49, 1.0, v49
	v_add_f32_e32 v50, 1.0, v50
	v_add_f32_e32 v52, 1.0, v52
	v_rcp_f32_e32 v48, v48
	v_rcp_f32_e32 v49, v49
	v_rcp_f32_e32 v50, v50
	v_add_f32_e32 v51, 1.0, v51
	v_rcp_f32_e32 v52, v52
	v_rcp_f32_e32 v51, v51
	v_lshlrev_b32_e32 v70, 16, v56
	v_and_b32_e32 v56, 0xffff0000, v56
	v_lshlrev_b32_e32 v71, 16, v57
	v_and_b32_e32 v57, 0xffff0000, v57
	v_and_b32_e32 v59, 0xffff0000, v59
	v_mul_f32_e32 v48, v48, v56
	v_mul_f32_e32 v49, v49, v71
	v_mul_f32_e32 v50, v50, v57
	v_mul_f32_e32 v52, v52, v70
	v_mul_f32_e32 v51, v51, v59
	v_cvt_pk_bf16_f32 v48, v52, v48
	v_cvt_pk_bf16_f32 v49, v49, v50
	v_cvt_pk_bf16_f32 v50, v62, v53
	v_cvt_pk_bf16_f32 v51, v54, v51
	global_store_dwordx4 v[60:61], v[48:51], off offset:256
	s_nop 1
	v_add_u32_e32 v50, 0x90, v128
	v_ashrrev_i32_e32 v51, 31, v50
	v_lshlrev_b64 v[48:49], 10, v[50:51]
	v_lshl_add_u64 v[48:49], s[14:15], 0, v[48:49]
	v_lshl_add_u64 v[48:49], v[48:49], 0, v[192:193]
	s_nop 1
	s_waitcnt vmcnt(12)
	v_mov_b64_e32 v[52:53], v[160:161]
	v_mov_b64_e32 v[54:55], v[162:163]
	v_mov_b64_e32 v[56:57], v[200:201]
	v_mov_b64_e32 v[58:59], v[202:203]
	v_mov_b64_e32 v[60:61], v[204:205]
	v_mov_b64_e32 v[62:63], v[206:207]
	v_lshlrev_b32_e32 v66, 16, v54
	v_add_f32_e32 v40, v40, v56
	v_add_f32_e32 v41, v41, v57
	v_add_f32_e32 v42, v42, v58
	v_mul_f32_e32 v40, 0xbfb8aa3b, v40
	v_mul_f32_e32 v41, 0xbfb8aa3b, v41
	v_mul_f32_e32 v42, 0xbfb8aa3b, v42
	v_exp_f32_e32 v40, v40
	v_exp_f32_e32 v41, v41
	v_exp_f32_e32 v42, v42
	v_and_b32_e32 v54, 0xffff0000, v54
	v_add_f32_e32 v40, 1.0, v40
	v_add_f32_e32 v41, 1.0, v41
	v_add_f32_e32 v42, 1.0, v42
	v_rcp_f32_e32 v40, v40
	v_rcp_f32_e32 v41, v41
	v_rcp_f32_e32 v42, v42
	v_lshlrev_b32_e32 v67, 16, v55
	v_add_f32_e32 v44, v44, v60
	v_mul_f32_e32 v56, v40, v66
	v_add_f32_e32 v40, v45, v61
	v_mul_f32_e32 v45, v41, v54
	v_add_f32_e32 v41, v46, v62
	v_mul_f32_e32 v46, v42, v67
	v_add_f32_e32 v42, v47, v63
	v_mul_f32_e32 v44, 0xbfb8aa3b, v44
	v_mul_f32_e32 v40, 0xbfb8aa3b, v40
	v_mul_f32_e32 v41, 0xbfb8aa3b, v41
	v_mul_f32_e32 v42, 0xbfb8aa3b, v42
	v_exp_f32_e32 v44, v44
	v_exp_f32_e32 v40, v40
	v_exp_f32_e32 v41, v41
	v_exp_f32_e32 v42, v42
	v_add_f32_e32 v43, v43, v59
	v_mul_f32_e32 v43, 0xbfb8aa3b, v43
	v_exp_f32_e32 v43, v43
	v_add_f32_e32 v44, 1.0, v44
	v_add_f32_e32 v40, 1.0, v40
	v_add_f32_e32 v41, 1.0, v41
	v_add_f32_e32 v42, 1.0, v42
	v_rcp_f32_e32 v44, v44
	v_rcp_f32_e32 v40, v40
	v_rcp_f32_e32 v41, v41
	v_rcp_f32_e32 v42, v42
	v_add_f32_e32 v43, 1.0, v43
	v_lshlrev_b32_e32 v64, 16, v52
	v_and_b32_e32 v52, 0xffff0000, v52
	v_lshlrev_b32_e32 v65, 16, v53
	v_and_b32_e32 v53, 0xffff0000, v53
	v_rcp_f32_e32 v43, v43
	v_mul_f32_e32 v44, v44, v64
	v_mul_f32_e32 v40, v40, v52
	v_mul_f32_e32 v41, v41, v65
	v_mul_f32_e32 v42, v42, v53
	v_cvt_pk_bf16_f32 v40, v44, v40
	v_cvt_pk_bf16_f32 v41, v41, v42
	v_cvt_pk_bf16_f32 v42, v56, v45
	v_lshlrev_b64 v[44:45], 12, v[50:51]
	v_and_b32_e32 v55, 0xffff0000, v55
	v_lshl_add_u64 v[44:45], s[12:13], 0, v[44:45]
	v_mul_f32_e32 v43, v43, v55
	v_lshl_add_u64 v[44:45], v[44:45], 0, v[192:193]
	v_cvt_pk_bf16_f32 v43, v46, v43
	global_store_dwordx4 v[44:45], v[40:43], off
	s_nop 1
	s_waitcnt vmcnt(11)
	v_mov_b64_e32 v[40:41], v[164:165]
	v_mov_b64_e32 v[42:43], v[166:167]
	s_nop 0
	v_mov_b64_e32 v[46:47], v[208:209]
	v_mov_b64_e32 v[48:49], v[210:211]
	v_mov_b64_e32 v[50:51], v[240:241]
	v_mov_b64_e32 v[52:53], v[242:243]
	v_lshlrev_b32_e32 v56, 16, v42
	v_add_f32_e32 v32, v32, v46
	v_add_f32_e32 v33, v33, v47
	v_add_f32_e32 v34, v34, v48
	v_mul_f32_e32 v32, 0xbfb8aa3b, v32
	v_mul_f32_e32 v33, 0xbfb8aa3b, v33
	v_mul_f32_e32 v34, 0xbfb8aa3b, v34
	v_exp_f32_e32 v32, v32
	v_exp_f32_e32 v33, v33
	v_exp_f32_e32 v34, v34
	v_and_b32_e32 v42, 0xffff0000, v42
	v_add_f32_e32 v32, 1.0, v32
	v_add_f32_e32 v33, 1.0, v33
	v_add_f32_e32 v34, 1.0, v34
	v_rcp_f32_e32 v32, v32
	v_rcp_f32_e32 v33, v33
	v_rcp_f32_e32 v34, v34
	v_lshlrev_b32_e32 v57, 16, v43
	v_mul_f32_e32 v46, v32, v56
	v_add_f32_e32 v32, v37, v51
	v_mul_f32_e32 v37, v33, v42
	v_add_f32_e32 v33, v38, v52
	v_mul_f32_e32 v38, v34, v57
	v_add_f32_e32 v34, v39, v53
	v_add_f32_e32 v36, v36, v50
	v_mul_f32_e32 v32, 0xbfb8aa3b, v32
	v_mul_f32_e32 v33, 0xbfb8aa3b, v33
	v_add_f32_e32 v35, v35, v49
	v_mul_f32_e32 v34, 0xbfb8aa3b, v34
	v_mul_f32_e32 v36, 0xbfb8aa3b, v36
	v_exp_f32_e32 v32, v32
	v_exp_f32_e32 v33, v33
	v_exp_f32_e32 v34, v34
	v_mul_f32_e32 v35, 0xbfb8aa3b, v35
	v_exp_f32_e32 v36, v36
	v_exp_f32_e32 v35, v35
	v_add_f32_e32 v32, 1.0, v32
	v_add_f32_e32 v33, 1.0, v33
	v_add_f32_e32 v34, 1.0, v34
	v_add_f32_e32 v36, 1.0, v36
	v_rcp_f32_e32 v32, v32
	v_rcp_f32_e32 v33, v33
	v_rcp_f32_e32 v34, v34
	v_add_f32_e32 v35, 1.0, v35
	v_rcp_f32_e32 v36, v36
	v_rcp_f32_e32 v35, v35
	v_lshlrev_b32_e32 v54, 16, v40
	v_and_b32_e32 v40, 0xffff0000, v40
	v_lshlrev_b32_e32 v55, 16, v41
	v_and_b32_e32 v41, 0xffff0000, v41
	v_and_b32_e32 v43, 0xffff0000, v43
	v_mul_f32_e32 v32, v32, v40
	v_mul_f32_e32 v33, v33, v55
	v_mul_f32_e32 v34, v34, v41
	v_mul_f32_e32 v36, v36, v54
	v_mul_f32_e32 v35, v35, v43
	v_cvt_pk_bf16_f32 v32, v36, v32
	v_cvt_pk_bf16_f32 v33, v33, v34
	v_cvt_pk_bf16_f32 v34, v46, v37
	v_cvt_pk_bf16_f32 v35, v38, v35
	global_store_dwordx4 v[44:45], v[32:35], off offset:256
	s_nop 1
	v_add_u32_e32 v34, 0xa0, v128
	v_ashrrev_i32_e32 v35, 31, v34
	v_lshlrev_b64 v[32:33], 10, v[34:35]
	v_lshl_add_u64 v[32:33], s[14:15], 0, v[32:33]
	v_lshl_add_u64 v[32:33], v[32:33], 0, v[192:193]
	s_nop 1
	s_waitcnt vmcnt(10)
	v_mov_b64_e32 v[36:37], v[168:169]
	v_mov_b64_e32 v[38:39], v[170:171]
	v_mov_b64_e32 v[40:41], v[200:201]
	v_mov_b64_e32 v[42:43], v[202:203]
	v_mov_b64_e32 v[44:45], v[204:205]
	v_mov_b64_e32 v[46:47], v[206:207]
	v_lshlrev_b32_e32 v50, 16, v38
	v_add_f32_e32 v24, v24, v40
	v_add_f32_e32 v25, v25, v41
	v_add_f32_e32 v26, v26, v42
	v_mul_f32_e32 v24, 0xbfb8aa3b, v24
	v_mul_f32_e32 v25, 0xbfb8aa3b, v25
	v_mul_f32_e32 v26, 0xbfb8aa3b, v26
	v_exp_f32_e32 v24, v24
	v_exp_f32_e32 v25, v25
	v_exp_f32_e32 v26, v26
	v_and_b32_e32 v38, 0xffff0000, v38
	v_add_f32_e32 v24, 1.0, v24
	v_add_f32_e32 v25, 1.0, v25
	v_add_f32_e32 v26, 1.0, v26
	v_rcp_f32_e32 v24, v24
	v_rcp_f32_e32 v25, v25
	v_rcp_f32_e32 v26, v26
	v_lshlrev_b32_e32 v51, 16, v39
	v_add_f32_e32 v28, v28, v44
	v_mul_f32_e32 v40, v24, v50
	v_add_f32_e32 v24, v29, v45
	v_mul_f32_e32 v29, v25, v38
	v_add_f32_e32 v25, v30, v46
	v_mul_f32_e32 v30, v26, v51
	v_add_f32_e32 v26, v31, v47
	v_mul_f32_e32 v28, 0xbfb8aa3b, v28
	v_mul_f32_e32 v24, 0xbfb8aa3b, v24
	v_mul_f32_e32 v25, 0xbfb8aa3b, v25
	v_mul_f32_e32 v26, 0xbfb8aa3b, v26
	v_exp_f32_e32 v28, v28
	v_exp_f32_e32 v24, v24
	v_exp_f32_e32 v25, v25
	v_exp_f32_e32 v26, v26
	v_add_f32_e32 v27, v27, v43
	v_mul_f32_e32 v27, 0xbfb8aa3b, v27
	v_exp_f32_e32 v27, v27
	v_add_f32_e32 v28, 1.0, v28
	v_add_f32_e32 v24, 1.0, v24
	v_add_f32_e32 v25, 1.0, v25
	v_add_f32_e32 v26, 1.0, v26
	v_rcp_f32_e32 v28, v28
	v_rcp_f32_e32 v24, v24
	v_rcp_f32_e32 v25, v25
	v_rcp_f32_e32 v26, v26
	v_add_f32_e32 v27, 1.0, v27
	v_lshlrev_b32_e32 v48, 16, v36
	v_and_b32_e32 v36, 0xffff0000, v36
	v_lshlrev_b32_e32 v49, 16, v37
	v_and_b32_e32 v37, 0xffff0000, v37
	v_rcp_f32_e32 v27, v27
	v_mul_f32_e32 v28, v28, v48
	v_mul_f32_e32 v24, v24, v36
	v_mul_f32_e32 v25, v25, v49
	v_mul_f32_e32 v26, v26, v37
	v_cvt_pk_bf16_f32 v24, v28, v24
	v_cvt_pk_bf16_f32 v25, v25, v26
	v_cvt_pk_bf16_f32 v26, v40, v29
	v_lshlrev_b64 v[28:29], 12, v[34:35]
	v_and_b32_e32 v39, 0xffff0000, v39
	v_lshl_add_u64 v[28:29], s[12:13], 0, v[28:29]
	v_mul_f32_e32 v27, v27, v39
	v_lshl_add_u64 v[28:29], v[28:29], 0, v[192:193]
	v_cvt_pk_bf16_f32 v27, v30, v27
	global_store_dwordx4 v[28:29], v[24:27], off
	s_nop 1
	s_waitcnt vmcnt(9)
	v_mov_b64_e32 v[24:25], v[172:173]
	v_mov_b64_e32 v[26:27], v[174:175]
	s_nop 0
	v_mov_b64_e32 v[30:31], v[208:209]
	v_mov_b64_e32 v[32:33], v[210:211]
	v_mov_b64_e32 v[34:35], v[240:241]
	v_mov_b64_e32 v[36:37], v[242:243]
	v_lshlrev_b32_e32 v40, 16, v26
	v_add_f32_e32 v16, v16, v30
	v_add_f32_e32 v17, v17, v31
	v_add_f32_e32 v18, v18, v32
	v_mul_f32_e32 v16, 0xbfb8aa3b, v16
	v_mul_f32_e32 v17, 0xbfb8aa3b, v17
	v_mul_f32_e32 v18, 0xbfb8aa3b, v18
	v_exp_f32_e32 v16, v16
	v_exp_f32_e32 v17, v17
	v_exp_f32_e32 v18, v18
	v_and_b32_e32 v26, 0xffff0000, v26
	v_add_f32_e32 v16, 1.0, v16
	v_add_f32_e32 v17, 1.0, v17
	v_add_f32_e32 v18, 1.0, v18
	v_rcp_f32_e32 v16, v16
	v_rcp_f32_e32 v17, v17
	v_rcp_f32_e32 v18, v18
	v_lshlrev_b32_e32 v41, 16, v27
	v_mul_f32_e32 v30, v16, v40
	v_add_f32_e32 v16, v21, v35
	v_mul_f32_e32 v21, v17, v26
	v_add_f32_e32 v17, v22, v36
	v_mul_f32_e32 v22, v18, v41
	v_add_f32_e32 v18, v23, v37
	v_add_f32_e32 v20, v20, v34
	v_mul_f32_e32 v16, 0xbfb8aa3b, v16
	v_mul_f32_e32 v17, 0xbfb8aa3b, v17
	v_add_f32_e32 v19, v19, v33
	v_mul_f32_e32 v18, 0xbfb8aa3b, v18
	v_mul_f32_e32 v20, 0xbfb8aa3b, v20
	v_exp_f32_e32 v16, v16
	v_exp_f32_e32 v17, v17
	v_exp_f32_e32 v18, v18
	v_mul_f32_e32 v19, 0xbfb8aa3b, v19
	v_exp_f32_e32 v20, v20
	v_exp_f32_e32 v19, v19
	v_add_f32_e32 v16, 1.0, v16
	v_add_f32_e32 v17, 1.0, v17
	v_add_f32_e32 v18, 1.0, v18
	v_add_f32_e32 v20, 1.0, v20
	v_rcp_f32_e32 v16, v16
	v_rcp_f32_e32 v17, v17
	v_rcp_f32_e32 v18, v18
	v_add_f32_e32 v19, 1.0, v19
	v_rcp_f32_e32 v20, v20
	v_rcp_f32_e32 v19, v19
	v_lshlrev_b32_e32 v38, 16, v24
	v_and_b32_e32 v24, 0xffff0000, v24
	v_lshlrev_b32_e32 v39, 16, v25
	v_and_b32_e32 v25, 0xffff0000, v25
	v_and_b32_e32 v27, 0xffff0000, v27
	v_mul_f32_e32 v16, v16, v24
	v_mul_f32_e32 v17, v17, v39
	v_mul_f32_e32 v18, v18, v25
	v_mul_f32_e32 v20, v20, v38
	v_mul_f32_e32 v19, v19, v27
	v_cvt_pk_bf16_f32 v16, v20, v16
	v_cvt_pk_bf16_f32 v17, v17, v18
	v_cvt_pk_bf16_f32 v18, v30, v21
	v_cvt_pk_bf16_f32 v19, v22, v19
	global_store_dwordx4 v[28:29], v[16:19], off offset:256
	s_nop 1
	v_add_u32_e32 v18, 0xb0, v128
	v_ashrrev_i32_e32 v19, 31, v18
	v_lshlrev_b64 v[16:17], 10, v[18:19]
	v_lshl_add_u64 v[16:17], s[14:15], 0, v[16:17]
	v_lshl_add_u64 v[16:17], v[16:17], 0, v[192:193]
	s_nop 1
	s_waitcnt vmcnt(8)
	v_mov_b64_e32 v[20:21], v[176:177]
	v_mov_b64_e32 v[22:23], v[178:179]
	v_mov_b64_e32 v[24:25], v[200:201]
	v_mov_b64_e32 v[26:27], v[202:203]
	v_mov_b64_e32 v[28:29], v[204:205]
	v_mov_b64_e32 v[30:31], v[206:207]
	v_lshlrev_b32_e32 v34, 16, v22
	v_add_f32_e32 v8, v8, v24
	v_add_f32_e32 v9, v9, v25
	v_add_f32_e32 v10, v10, v26
	v_mul_f32_e32 v8, 0xbfb8aa3b, v8
	v_mul_f32_e32 v9, 0xbfb8aa3b, v9
	v_mul_f32_e32 v10, 0xbfb8aa3b, v10
	v_exp_f32_e32 v8, v8
	v_exp_f32_e32 v9, v9
	v_exp_f32_e32 v10, v10
	v_and_b32_e32 v22, 0xffff0000, v22
	v_add_f32_e32 v8, 1.0, v8
	v_add_f32_e32 v9, 1.0, v9
	v_add_f32_e32 v10, 1.0, v10
	v_rcp_f32_e32 v8, v8
	v_rcp_f32_e32 v9, v9
	v_rcp_f32_e32 v10, v10
	v_lshlrev_b32_e32 v35, 16, v23
	v_add_f32_e32 v12, v12, v28
	v_mul_f32_e32 v24, v8, v34
	v_add_f32_e32 v8, v13, v29
	v_mul_f32_e32 v13, v9, v22
	v_add_f32_e32 v9, v14, v30
	v_mul_f32_e32 v14, v10, v35
	v_add_f32_e32 v10, v15, v31
	v_mul_f32_e32 v12, 0xbfb8aa3b, v12
	v_mul_f32_e32 v8, 0xbfb8aa3b, v8
	v_mul_f32_e32 v9, 0xbfb8aa3b, v9
	v_mul_f32_e32 v10, 0xbfb8aa3b, v10
	v_exp_f32_e32 v12, v12
	v_exp_f32_e32 v8, v8
	v_exp_f32_e32 v9, v9
	v_exp_f32_e32 v10, v10
	v_add_f32_e32 v11, v11, v27
	v_mul_f32_e32 v11, 0xbfb8aa3b, v11
	v_exp_f32_e32 v11, v11
	v_add_f32_e32 v12, 1.0, v12
	v_add_f32_e32 v8, 1.0, v8
	v_add_f32_e32 v9, 1.0, v9
	v_add_f32_e32 v10, 1.0, v10
	v_rcp_f32_e32 v12, v12
	v_rcp_f32_e32 v8, v8
	v_rcp_f32_e32 v9, v9
	v_rcp_f32_e32 v10, v10
	v_add_f32_e32 v11, 1.0, v11
	v_lshlrev_b32_e32 v32, 16, v20
	v_and_b32_e32 v20, 0xffff0000, v20
	v_lshlrev_b32_e32 v33, 16, v21
	v_and_b32_e32 v21, 0xffff0000, v21
	v_rcp_f32_e32 v11, v11
	v_mul_f32_e32 v12, v12, v32
	v_mul_f32_e32 v8, v8, v20
	v_mul_f32_e32 v9, v9, v33
	v_mul_f32_e32 v10, v10, v21
	v_cvt_pk_bf16_f32 v8, v12, v8
	v_cvt_pk_bf16_f32 v9, v9, v10
	v_cvt_pk_bf16_f32 v10, v24, v13
	v_lshlrev_b64 v[12:13], 12, v[18:19]
	v_and_b32_e32 v23, 0xffff0000, v23
	v_lshl_add_u64 v[12:13], s[12:13], 0, v[12:13]
	v_mul_f32_e32 v11, v11, v23
	v_lshl_add_u64 v[12:13], v[12:13], 0, v[192:193]
	v_cvt_pk_bf16_f32 v11, v14, v11
	global_store_dwordx4 v[12:13], v[8:11], off
	s_nop 1
	s_waitcnt vmcnt(7)
	v_mov_b64_e32 v[8:9], v[180:181]
	v_mov_b64_e32 v[10:11], v[182:183]
	s_nop 0
	v_mov_b64_e32 v[14:15], v[208:209]
	v_mov_b64_e32 v[16:17], v[210:211]
	v_mov_b64_e32 v[18:19], v[240:241]
	v_mov_b64_e32 v[20:21], v[242:243]
	s_mov_b64 s[10:11], 0
	v_lshlrev_b32_e32 v24, 16, v10
	v_add_f32_e32 v0, v0, v14
	v_add_f32_e32 v1, v1, v15
	v_add_f32_e32 v2, v2, v16
	v_mul_f32_e32 v0, 0xbfb8aa3b, v0
	v_mul_f32_e32 v1, 0xbfb8aa3b, v1
	v_mul_f32_e32 v2, 0xbfb8aa3b, v2
	v_exp_f32_e32 v0, v0
	v_exp_f32_e32 v1, v1
	v_exp_f32_e32 v2, v2
	v_and_b32_e32 v10, 0xffff0000, v10
	v_add_f32_e32 v0, 1.0, v0
	v_add_f32_e32 v1, 1.0, v1
	v_add_f32_e32 v2, 1.0, v2
	v_rcp_f32_e32 v0, v0
	v_rcp_f32_e32 v1, v1
	v_rcp_f32_e32 v2, v2
	v_lshlrev_b32_e32 v25, 16, v11
	v_mul_f32_e32 v14, v0, v24
	v_add_f32_e32 v0, v5, v19
	v_mul_f32_e32 v5, v1, v10
	v_add_f32_e32 v1, v6, v20
	v_mul_f32_e32 v6, v2, v25
	v_add_f32_e32 v2, v7, v21
	v_add_f32_e32 v3, v3, v17
	v_add_f32_e32 v4, v4, v18
	v_mul_f32_e32 v0, 0xbfb8aa3b, v0
	v_mul_f32_e32 v1, 0xbfb8aa3b, v1
	v_mul_f32_e32 v2, 0xbfb8aa3b, v2
	v_mul_f32_e32 v3, 0xbfb8aa3b, v3
	v_mul_f32_e32 v4, 0xbfb8aa3b, v4
	v_exp_f32_e32 v0, v0
	v_exp_f32_e32 v1, v1
	v_exp_f32_e32 v2, v2
	v_exp_f32_e32 v3, v3
	v_exp_f32_e32 v4, v4
	v_add_f32_e32 v0, 1.0, v0
	v_add_f32_e32 v1, 1.0, v1
	v_add_f32_e32 v2, 1.0, v2
	v_add_f32_e32 v3, 1.0, v3
	v_add_f32_e32 v4, 1.0, v4
	v_rcp_f32_e32 v0, v0
	v_rcp_f32_e32 v1, v1
	v_rcp_f32_e32 v2, v2
	v_rcp_f32_e32 v3, v3
	v_rcp_f32_e32 v4, v4
	v_lshlrev_b32_e32 v22, 16, v8
	v_and_b32_e32 v8, 0xffff0000, v8
	v_lshlrev_b32_e32 v23, 16, v9
	v_and_b32_e32 v9, 0xffff0000, v9
	v_and_b32_e32 v11, 0xffff0000, v11
	v_mul_f32_e32 v0, v0, v8
	v_mul_f32_e32 v1, v1, v23
	v_mul_f32_e32 v2, v2, v9
	v_mul_f32_e32 v3, v3, v11
	v_mul_f32_e32 v4, v4, v22
	v_cvt_pk_bf16_f32 v0, v4, v0
	v_cvt_pk_bf16_f32 v1, v1, v2
	v_cvt_pk_bf16_f32 v2, v14, v5
	v_cvt_pk_bf16_f32 v3, v6, v3
	global_store_dwordx4 v[12:13], v[0:3], off offset:256
	s_waitcnt vmcnt(0)
	s_barrier
	s_barrier
	s_nop 0

.LBB0_460:
	s_and_b32 s69, s89, 1
	s_mul_i32 s16, s69, 0x4400
	s_add_i32 s18, s16, 0
	s_mul_i32 s16, s69, 0xc00
	s_add_i32 s22, s18, s16
	v_add_u32_e32 v64, s18, v158
	v_add_u32_e32 v65, v64, v159
	v_add_u32_e32 v64, v64, v201
	s_cmp_eq_u32 s89, 0
	s_waitcnt vmcnt(0)
	ds_write_b128 v65, v[126:129]
	ds_write_b128 v64, v[122:125]
	v_add_u32_e32 v64, s22, v158
	s_cselect_b64 s[16:17], -1, 0
	v_add_u32_e32 v65, v64, v202
	v_add_u32_e32 v64, v64, v203
	s_and_b64 vcc, exec, s[16:17]
	ds_write_b128 v65, v[118:121] offset:34816
	ds_write_b128 v64, v[114:117] offset:34816
	s_waitcnt lgkmcnt(0)
	s_barrier
	s_cbranch_vccnz .LBB0_462
	s_and_b32 s16, s87, 8
	s_xor_b32 s17, s16, 8
	s_lshl_b32 s17, s17, 2
	s_add_i32 s17, s17, 0x12c00
	v_mov_b32_e32 v72, s17
	ds_read_b128 v[64:67], v72
	ds_read_b128 v[68:71], v72 offset:16
	s_waitcnt lgkmcnt(0)
	v_and_b32_e32 v64, v64, v65
	v_and_b32_e32 v66, v66, v67
	v_and_b32_e32 v68, v68, v69
	v_and_b32_e32 v70, v70, v71
	v_and_b32_e32 v64, v64, v66
	v_and_b32_e32 v68, v68, v70
	v_and_b32_e32 v64, v64, v68
	v_and_b32_e32 v64, 1, v64
	v_cmp_eq_u32_e64 s[16:17], 0, v64
	s_nop 0

.Lsb_near:
	v_add3_u32 v130, s18, v192, v205
	ds_read_b128 v[64:67], v130 offset:8704
	ds_read_b128 v[132:135], v130 offset:8736
	v_or_b32_e32 v163, s23, v200
	v_add3_u32 v207, s22, v204, v206
	s_waitcnt lgkmcnt(1)
	v_mfma_f32_32x32x16_bf16 v[66:81], v[64:67], v[82:85], 0
	s_waitcnt lgkmcnt(0)
	v_mfma_f32_32x32x16_bf16 v[66:81], v[132:135], v[86:89], v[66:81]
	ds_read_b128 v[132:135], v130 offset:8768
	ds_read_b128 v[136:139], v130 offset:8800
	s_waitcnt lgkmcnt(1)
	v_mfma_f32_32x32x16_bf16 v[66:81], v[132:135], v[90:93], v[66:81]
	s_waitcnt lgkmcnt(0)
	v_mfma_f32_32x32x16_bf16 v[66:81], v[136:139], v[94:97], v[66:81]
	ds_read_b128 v[132:135], v130 offset:8832
	ds_read_b128 v[136:139], v130 offset:8864
	s_waitcnt lgkmcnt(1)
	v_mfma_f32_32x32x16_bf16 v[66:81], v[132:135], v[98:101], v[66:81]
	s_waitcnt lgkmcnt(0)
	v_mfma_f32_32x32x16_bf16 v[66:81], v[136:139], v[102:105], v[66:81]
	ds_read_b128 v[132:135], v130 offset:8896
	ds_read_b128 v[136:139], v130 offset:8928
	ds_read_b128 v[208:211], v130 offset:224
	s_waitcnt lgkmcnt(2)
	v_mfma_f32_32x32x16_bf16 v[66:81], v[132:135], v[106:109], v[66:81]
	s_waitcnt lgkmcnt(1)
	v_mfma_f32_32x32x16_bf16 v[66:81], v[136:139], v[110:113], v[66:81]
	s_nop 11
	v_mov_b32_e32 v64, v66
	v_mov_b32_e32 v65, v68
	v_mov_b32_e32 v68, v67
	v_mul_f32_e32 v132, s68, v64
	v_mul_f32_e32 v133, s68, v65
	v_mov_b32_e32 v66, v70
	v_mul_f32_e32 v134, s68, v68
	v_mul_f32_e32 v135, s68, v69
	v_mul_f32_e64 v70, |v132|, s54
	v_mov_b32_e32 v67, v72
	v_mul_f32_e64 v72, |v134|, s54
	v_exp_f32_e32 v70, v70
	v_mul_f32_e64 v131, |v133|, s54
	v_exp_f32_e32 v72, v72
	v_mul_f32_e64 v138, |v135|, s54
	v_exp_f32_e32 v131, v131
	v_mul_f32_e32 v136, s68, v66
	v_mul_f32_e32 v137, s68, v67
	v_exp_f32_e32 v138, v138
	v_mul_f32_e64 v139, |v136|, s54
	v_add_f32_e32 v70, 1.0, v70
	v_exp_f32_e32 v139, v139
	v_add_f32_e32 v72, 1.0, v72
	v_add_f32_e32 v131, 1.0, v131
	v_add_f32_e32 v138, 1.0, v138
	v_log_f32_e32 v70, v70
	v_add_f32_e32 v139, 1.0, v139
	v_log_f32_e32 v72, v72
	v_log_f32_e32 v131, v131
	v_log_f32_e32 v138, v138
	v_mov_b32_e32 v142, v139
	v_mul_f32_e32 v139, 0x3f317217, v70
	v_mul_f32_e32 v140, 0x3f317217, v72
	v_fma_f32 v139, v70, s86, -v139
	v_mul_f32_e32 v141, 0x3f317217, v131
	v_fma_f32 v140, v72, s86, -v140
	v_fmac_f32_e32 v139, 0x3377d1cf, v70
	v_mul_f32_e32 v143, 0x3f317217, v138
	v_fma_f32 v141, v131, s86, -v141
	v_fmac_f32_e32 v140, 0x3377d1cf, v72
	v_fmac_f32_e32 v139, 0x3f317217, v70
	v_fma_f32 v143, v138, s86, -v143
	v_fmac_f32_e32 v141, 0x3377d1cf, v131
	v_fmac_f32_e32 v140, 0x3f317217, v72
	v_fmac_f32_e32 v143, 0x3377d1cf, v138
	v_fmac_f32_e32 v141, 0x3f317217, v131
	v_fmac_f32_e32 v143, 0x3f317217, v138
	v_min_f32_e32 v132, 0, v132
	v_min_f32_e32 v133, 0, v133
	v_sub_f32_e32 v166, v132, v139
	v_sub_f32_e32 v167, v133, v141
	v_fma_f32 v174, -v64, s68, v166
	v_fma_f32 v175, -v65, s68, v167
	v_log_f32_e32 v65, v142
	v_min_f32_e32 v134, 0, v134
	v_min_f32_e32 v135, 0, v135
	v_sub_f32_e32 v164, v134, v140
	v_sub_f32_e32 v165, v135, v143
	v_mov_b32_e32 v72, v71
	v_fma_f32 v172, -v68, s68, v164
	v_fma_f32 v173, -v69, s68, v165
	v_mul_f32_e32 v68, 0x3f317217, v65
	v_fma_f32 v70, v65, s86, -v68
	v_mul_f32_e32 v68, s68, v72
	v_mul_f32_e32 v69, s68, v73
	v_fmac_f32_e32 v70, 0x3377d1cf, v65
	v_mul_f32_e64 v71, |v68|, s54
	v_exp_f32_e32 v71, v71
	v_fmac_f32_e32 v70, 0x3f317217, v65
	v_mul_f32_e64 v131, |v137|, s54
	v_exp_f32_e32 v131, v131
	v_mov_b32_e32 v65, v70
	v_add_f32_e32 v70, 1.0, v71
	v_mul_f32_e64 v133, |v69|, s54
	v_exp_f32_e32 v133, v133
	v_log_f32_e32 v71, v70
	v_mov_b32_e32 v70, v65
	v_min_f32_e32 v64, 0, v136
	v_mul_f32_e32 v65, 0x3f317217, v71
	v_fma_f32 v65, v71, s86, -v65
	v_fmac_f32_e32 v65, 0x3377d1cf, v71
	v_fmac_f32_e32 v65, 0x3f317217, v71
	v_min_f32_e32 v68, 0, v68
	v_min_f32_e32 v69, 0, v69
	v_add_f32_e32 v71, 1.0, v131
	v_mov_b32_e32 v140, v78
	v_mov_b32_e32 v141, v80
	v_log_f32_e32 v71, v71
	v_mov_b32_e32 v132, v65
	v_min_f32_e32 v65, 0, v137
	v_mul_f32_e32 v131, 0x3f317217, v71
	v_fma_f32 v131, v71, s86, -v131
	v_fmac_f32_e32 v131, 0x3377d1cf, v71
	v_fmac_f32_e32 v131, 0x3f317217, v71
	v_mul_f32_e32 v142, s68, v140
	v_mul_f32_e32 v143, s68, v141
	v_mov_b32_e32 v80, v79
	v_mov_b32_e32 v71, v131
	v_add_f32_e32 v131, 1.0, v133
	v_sub_f32_e32 v168, v64, v70
	v_sub_f32_e32 v169, v65, v71
	v_log_f32_e32 v131, v131
	v_fma_f32 v176, -v66, s68, v168
	v_fma_f32 v177, -v67, s68, v169
	v_mul_f32_e32 v144, s68, v80
	v_mul_f32_e32 v145, s68, v81
	v_mul_f32_e32 v64, 0x3f317217, v131
	v_fma_f32 v70, v131, s86, -v64
	v_mov_b32_e32 v64, v74
	v_mul_f32_e32 v66, s68, v64
	v_mul_f32_e32 v67, s68, v76
	v_fmac_f32_e32 v70, 0x3377d1cf, v131
	v_mul_f32_e64 v71, |v66|, s54
	v_exp_f32_e32 v71, v71
	v_fmac_f32_e32 v70, 0x3f317217, v131
	v_min_f32_e32 v66, 0, v66
	v_mov_b32_e32 v133, v70
	v_add_f32_e32 v70, 1.0, v71
	v_sub_f32_e32 v170, v68, v132
	v_sub_f32_e32 v171, v69, v133
	ds_read_b128 v[132:135], v130 offset:32
	v_log_f32_e32 v70, v70
	v_fma_f32 v178, -v72, s68, v170
	v_fma_f32 v179, -v73, s68, v171
	v_mul_f32_e64 v73, |v67|, s54
	v_exp_f32_e32 v73, v73
	v_mul_f32_e32 v68, 0x3f317217, v70
	v_fma_f32 v71, v70, s86, -v68
	v_mul_f32_e32 v68, s68, v75
	v_mul_f32_e32 v69, s68, v77
	v_fmac_f32_e32 v71, 0x3377d1cf, v70
	v_mul_f32_e64 v72, |v68|, s54
	v_exp_f32_e32 v72, v72
	v_fmac_f32_e32 v71, 0x3f317217, v70
	v_mul_f32_e64 v74, |v69|, s54
	v_exp_f32_e32 v74, v74
	v_mov_b32_e32 v70, v71
	v_add_f32_e32 v71, 1.0, v72
	v_min_f32_e32 v67, 0, v67
	v_min_f32_e32 v68, 0, v68
	v_log_f32_e32 v71, v71
	v_mov_b32_e32 v70, v70
	v_min_f32_e32 v69, 0, v69
	v_mul_f32_e32 v72, 0x3f317217, v71
	v_fma_f32 v72, v71, s86, -v72
	v_fmac_f32_e32 v72, 0x3377d1cf, v71
	v_fmac_f32_e32 v72, 0x3f317217, v71
	s_nop 1
	v_mov_b32_e32 v71, v72
	v_add_f32_e32 v72, 1.0, v73
	s_nop 1
	v_log_f32_e32 v73, v72
	v_mov_b32_e32 v72, v71
	v_mul_f32_e32 v71, 0x3f317217, v73
	v_fma_f32 v71, v73, s86, -v71
	v_fmac_f32_e32 v71, 0x3377d1cf, v73
	v_fmac_f32_e32 v71, 0x3f317217, v73
	s_nop 1
	v_add_f32_e32 v73, 1.0, v74
	v_sub_f32_e32 v180, v66, v70
	v_sub_f32_e32 v181, v67, v71
	v_mul_f32_e64 v70, |v143|, s54
	v_log_f32_e32 v73, v73
	v_fma_f32 v184, -v64, s68, v180
	v_fma_f32 v185, -v76, s68, v181
	v_mul_f32_e64 v65, |v142|, s54
	v_exp_f32_e32 v65, v65
	v_mul_f32_e32 v64, 0x3f317217, v73
	v_fma_f32 v64, v73, s86, -v64
	v_fmac_f32_e32 v64, 0x3377d1cf, v73
	v_fmac_f32_e32 v64, 0x3f317217, v73
	v_exp_f32_e32 v131, v70
	v_mov_b32_e32 v73, v64
	v_add_f32_e32 v64, 1.0, v65
	v_mul_f32_e64 v66, |v144|, s54
	v_exp_f32_e32 v66, v66
	v_log_f32_e32 v64, v64
	v_sub_f32_e32 v182, v68, v72
	v_sub_f32_e32 v183, v69, v73
	v_add_f32_e32 v131, 1.0, v131
	v_fma_f32 v186, -v75, s68, v182
	v_fma_f32 v187, -v77, s68, v183
	v_mul_f32_e32 v65, 0x3f317217, v64
	v_fma_f32 v65, v64, s86, -v65
	v_fmac_f32_e32 v65, 0x3377d1cf, v64
	v_fmac_f32_e32 v65, 0x3f317217, v64
	v_min_f32_e32 v142, 0, v142
	v_min_f32_e32 v143, 0, v143
	v_mov_b32_e32 v64, v65
	v_add_f32_e32 v65, 1.0, v66
	v_min_f32_e32 v144, 0, v144
	v_log_f32_e32 v68, v65
	v_mov_b32_e32 v146, v64
	ds_read_b128 v[64:67], v130
	v_mul_f32_e32 v69, 0x3f317217, v68
	v_fma_f32 v69, v68, s86, -v69
	v_fmac_f32_e32 v69, 0x3377d1cf, v68
	v_fmac_f32_e32 v69, 0x3f317217, v68
	s_nop 0
	v_mov_b32_e32 v147, v69
	s_waitcnt lgkmcnt(0)
	v_mfma_f32_32x32x16_bf16 v[64:79], v[64:67], v[82:85], 0
	v_mov_b32_e32 v148, v147
	s_nop 0
	ds_read_b128 v[136:139], v130 offset:64
	v_log_f32_e32 v131, v131
	v_mfma_f32_32x32x16_bf16 v[64:79], v[132:135], v[86:89], v[64:79]
	v_mul_f32_e32 v132, 0x3f317217, v131
	v_fma_f32 v147, v131, s86, -v132
	ds_read_b128 v[132:135], v130 offset:96
	v_fmac_f32_e32 v147, 0x3377d1cf, v131
	v_fmac_f32_e32 v147, 0x3f317217, v131
	s_waitcnt lgkmcnt(1)
	v_mfma_f32_32x32x16_bf16 v[64:79], v[136:139], v[90:93], v[64:79]
	v_mul_f32_e64 v137, |v145|, s54
	v_exp_f32_e32 v149, v137
	ds_read_b128 v[136:139], v130 offset:128
	s_waitcnt lgkmcnt(1)
	v_mfma_f32_32x32x16_bf16 v[64:79], v[132:135], v[94:97], v[64:79]
	v_add_f32_e32 v131, 1.0, v149
	v_add_f32_e64 v188, v142, -v146
	v_add_f32_e64 v189, v143, -v147
	v_min_f32_e32 v145, 0, v145
	ds_read_b128 v[132:135], v130 offset:160
	s_waitcnt lgkmcnt(1)
	v_mfma_f32_32x32x16_bf16 v[64:79], v[136:139], v[98:101], v[64:79]
	v_log_f32_e32 v131, v131
	v_fma_f32 v212, -v140, s68, v188
	v_fma_f32 v213, -v141, s68, v189
	v_mul_f32_e32 v136, 0x3f317217, v131
	v_fma_f32 v140, v131, s86, -v136
	ds_read_b128 v[136:139], v130 offset:192
	s_waitcnt lgkmcnt(1)
	v_mfma_f32_32x32x16_bf16 v[64:79], v[132:135], v[102:105], v[64:79]
	v_fmac_f32_e32 v140, 0x3377d1cf, v131
	v_fmac_f32_e32 v140, 0x3f317217, v131
	s_nop 0
	s_waitcnt lgkmcnt(0)
	v_mfma_f32_32x32x16_bf16 v[64:79], v[136:139], v[106:109], v[64:79]
	v_add_f32_e64 v190, v144, -v148
	v_add_f32_e64 v191, v145, -v140
	ds_read_b64_tr_b16 v[146:147], v207 offset:45056
	ds_read_b64_tr_b16 v[142:143], v207 offset:45120
	ds_read_b64_tr_b16 v[138:139], v207 offset:45184
	ds_read_b64_tr_b16 v[134:135], v207 offset:45248
	ds_read_b64_tr_b16 v[148:149], v207 offset:47616
	ds_read_b64_tr_b16 v[144:145], v207 offset:47680
	ds_read_b64_tr_b16 v[140:141], v207 offset:47744
	ds_read_b64_tr_b16 v[136:137], v207 offset:47808
	ds_read_b64_tr_b16 v[130:131], v207 offset:50176
	ds_read_b64_tr_b16 v[132:133], v207 offset:52736
	v_fma_f32 v216, -v80, s68, v190
	v_fma_f32 v217, -v81, s68, v191
	v_or_b32_e32 v80, 34, v163
	v_cmp_lt_i32_e64 s[26:27], v80, v153
	v_mfma_f32_32x32x16_bf16 v[64:79], v[208:211], v[110:113], v[64:79]
	v_or_b32_e32 v208, 32, v163
	v_cmp_lt_i32_e64 s[30:31], v208, v152
	v_or_b32_e32 v208, 33, v163
	v_cmp_lt_i32_e64 s[40:41], v208, v152
	v_cndmask_b32_e64 v80, 0, v174, s[30:31]
	v_or_b32_e32 v174, 35, v163
	v_cmp_lt_i32_e64 s[38:39], v174, v153
	v_cndmask_b32_e64 v81, 0, v175, s[26:27]
	v_cndmask_b32_e64 v174, 0, v172, s[40:41]
	v_cndmask_b32_e64 v175, 0, v173, s[38:39]
	v_add_f32_e32 v80, v80, v174
	v_add_f32_e32 v81, v81, v175
	v_or_b32_e32 v208, 40, v163
	v_add_f32_e32 v172, v80, v81
	v_add_f32_e32 v173, v81, v80
	v_cmp_lt_i32_e64 s[22:23], v208, v152
	v_or_b32_e32 v173, 42, v163
	v_cmp_lt_i32_e64 s[18:19], v173, v153
	v_or_b32_e32 v173, 43, v163
	v_or_b32_e32 v208, 41, v163
	v_cmp_lt_i32_e64 s[28:29], v173, v153
	v_or_b32_e32 v173, 50, v163
	v_cmp_lt_i32_e64 s[34:35], v208, v152
	v_or_b32_e32 v208, 48, v163
	v_cmp_lt_i32_e32 vcc, v173, v153
	v_or_b32_e32 v173, 51, v163
	v_cmp_lt_i32_e64 s[42:43], v208, v152
	v_or_b32_e32 v208, 49, v163
	v_cmp_lt_i32_e64 s[16:17], v173, v153
	v_or_b32_e32 v173, 58, v163
	v_cmp_lt_i32_e64 s[44:45], v208, v152
	v_or_b32_e32 v208, 56, v163
	v_cmp_lt_i32_e64 s[14:15], v173, v153
	v_or_b32_e32 v173, 59, v163
	v_or_b32_e32 v210, 57, v163
	v_cmp_lt_i32_e64 s[36:37], v208, v152
	v_cmp_lt_i32_e64 s[20:21], v173, v153
	v_cmp_lt_i32_e64 s[24:25], v210, v152
	v_cndmask_b32_e32 v185, 0, v185, vcc
	v_cndmask_b32_e64 v184, 0, v184, s[42:43]
	v_cndmask_b32_e64 v187, 0, v187, s[16:17]
	v_cndmask_b32_e64 v186, 0, v186, s[44:45]
	v_cndmask_b32_e64 v209, 0, v213, s[14:15]
	v_cndmask_b32_e64 v208, 0, v212, s[36:37]
	v_cndmask_b32_e64 v211, 0, v217, s[20:21]
	v_cndmask_b32_e64 v210, 0, v216, s[24:25]
	v_add_f32_e32 v184, v184, v186
	v_add_f32_e32 v185, v185, v187
	v_add_f32_e32 v208, v208, v210
	v_add_f32_e32 v209, v209, v211
	v_add_f32_e32 v240, v184, v185
	v_add_f32_e32 v241, v185, v184
	v_add_f32_e32 v212, v208, v209
	v_add_f32_e32 v213, v209, v208
	ds_bpermute_b32 v216, v235, v212
	ds_bpermute_b32 v184, v235, v240
	v_cndmask_b32_e64 v177, 0, v177, s[18:19]
	s_waitcnt lgkmcnt(1)
	v_add_f32_e32 v208, v212, v216
	s_waitcnt lgkmcnt(0)
	v_cndmask_b32_e64 v213, 0, v184, s[10:11]
	v_add_f32_e32 v208, v213, v208
	v_add_f32_e32 v245, v162, v208
	v_add_f32_e32 v246, v186, v185
	v_add_f32_e32 v247, v180, v245
	v_add_f32_e32 v182, v182, v245
	v_add_f32_e32 v180, v246, v247
	v_mul_f32_e32 v180, 0x3fb8aa3b, v180
	v_exp_f32_e32 v180, v180
	v_add_f32_e32 v182, v185, v182
	v_mul_f32_e32 v182, 0x3fb8aa3b, v182
	v_cndmask_b32_e64 v176, 0, v176, s[22:23]
	v_cndmask_b32_e64 v179, 0, v179, s[28:29]
	v_cndmask_b32_e64 v178, 0, v178, s[34:35]
	v_exp_f32_e32 v182, v182
	v_add_f32_e32 v176, v176, v178
	v_add_f32_e32 v177, v177, v179
	v_cndmask_b32_e64 v213, 0, v180, s[42:43]
	v_add_f32_e32 v180, v181, v245
	v_add_f32_e32 v242, v176, v177
	v_add_f32_e32 v243, v177, v176
	v_add_f32_e32 v180, v187, v180
	ds_bpermute_b32 v80, v235, v172
	ds_bpermute_b32 v176, v235, v242
	v_mul_f32_e32 v180, 0x3fb8aa3b, v180
	v_cndmask_b32_e64 v215, 0, v182, s[44:45]
	v_exp_f32_e32 v239, v180
	v_add_f32_e32 v180, v183, v245
	v_add_f32_e32 v182, v184, v216
	v_add_f32_e32 v183, v240, v212
	v_add_f32_e32 v180, 0, v180
	v_add_f32_e32 v181, v242, v183
	v_add_f32_e32 v181, v181, v216
	v_add_f32_e32 v181, v181, v184
	v_cndmask_b32_e64 v173, 0, v216, s[10:11]
	s_waitcnt lgkmcnt(1)
	v_cndmask_b32_e64 v208, 0, v80, s[10:11]
	v_mul_f32_e32 v180, 0x3fb8aa3b, v180
	s_waitcnt lgkmcnt(0)
	v_add_f32_e32 v181, v181, v176
	v_exp_f32_e32 v241, v180
	v_add_f32_e32 v180, v162, v173
	v_add_f32_e32 v173, v183, v216
	v_add_f32_e32 v181, v208, v181
	v_cndmask_b32_e64 v186, 0, v176, s[10:11]
	v_add_f32_e32 v173, v173, v184
	v_add_f32_e32 v185, v162, v181
	v_add_f32_e32 v173, v186, v173
	v_add_f32_e32 v164, v164, v185
	v_add_f32_e32 v186, v174, v81
	v_add_f32_e32 v187, v166, v185
	v_add_f32_e32 v81, v81, v164
	v_add_f32_e32 v164, v167, v185
	v_add_f32_e32 v165, v165, v185
	v_add_f32_e32 v166, v186, v187
	v_add_f32_e32 v164, v175, v164
	v_add_f32_e32 v165, 0, v165
	v_mul_f32_e32 v166, 0x3fb8aa3b, v166
	v_mul_f32_e32 v164, 0x3fb8aa3b, v164
	v_mul_f32_e32 v165, 0x3fb8aa3b, v165
	v_exp_f32_e32 v166, v166
	v_exp_f32_e32 v164, v164
	v_exp_f32_e32 v165, v165
	v_cndmask_b32_e64 v174, 0, v166, s[30:31]
	v_cndmask_b32_e64 v175, 0, v164, s[26:27]
	v_cndmask_b32_e64 v181, 0, v165, s[38:39]
	v_add_f32_e32 v165, v162, v173
	v_add_f32_e32 v166, v178, v177
	v_add_f32_e32 v167, v168, v165
	v_mul_f32_e32 v81, 0x3fb8aa3b, v81
	v_add_f32_e32 v164, v166, v167
	v_add_f32_e32 v166, v170, v165
	v_add_f32_e32 v167, v169, v165
	v_add_f32_e32 v165, v171, v165
	v_add_f32_e32 v166, v177, v166
	v_add_f32_e32 v167, v179, v167
	v_add_f32_e32 v165, 0, v165
	v_mul_f32_e32 v164, 0x3fb8aa3b, v164
	v_mul_f32_e32 v166, 0x3fb8aa3b, v166
	v_mul_f32_e32 v167, 0x3fb8aa3b, v167
	v_mul_f32_e32 v165, 0x3fb8aa3b, v165
	v_exp_f32_e32 v81, v81
	v_exp_f32_e32 v164, v164
	v_exp_f32_e32 v166, v166
	v_exp_f32_e32 v167, v167
	v_exp_f32_e32 v165, v165
	v_cndmask_b32_e64 v81, 0, v81, s[40:41]
	v_cndmask_b32_e64 v168, 0, v164, s[22:23]
	v_cndmask_b32_e64 v166, 0, v166, s[34:35]
	v_cndmask_b32_e64 v167, 0, v167, s[18:19]
	v_cndmask_b32_e64 v169, 0, v165, s[28:29]
	v_cvt_pk_bf16_f32 v164, v174, v81
	v_cvt_pk_bf16_f32 v165, v175, v181
	v_cvt_pk_bf16_f32 v166, v168, v166
	v_cvt_pk_bf16_f32 v167, v167, v169
	s_nop 0
	s_nop 0
	v_mfma_f32_32x32x16_bf16 v[48:63], v[146:149], v[164:167], v[48:63]
	v_add_f32_e64 v146, v180, v188
	v_add_f32_e64 v147, v210, v209
	v_add_f32_e32 v81, v146, v147
	v_mul_f32_e32 v81, 0x3fb8aa3b, v81
	v_exp_f32_e32 v81, v81
	v_cndmask_b32_e32 v146, 0, v239, vcc
	v_cndmask_b32_e64 v81, 0, v81, s[36:37]
	v_mfma_f32_32x32x16_bf16 v[32:47], v[142:145], v[164:167], v[32:47]
	v_add_f32_e32 v143, v180, v190
	v_add_f32_e32 v144, v180, v189
	v_add_f32_e32 v143, v143, v209
	v_mul_f32_e32 v143, 0x3fb8aa3b, v143
	v_exp_f32_e32 v143, v143
	v_cndmask_b32_e64 v142, 0, v241, s[16:17]
	v_mfma_f32_32x32x16_bf16 v[16:31], v[138:141], v[164:167], v[16:31]
	v_add_f32_e32 v139, v180, v191
	v_add_f32_e32 v138, v144, v211
	v_add_f32_e32 v139, 0, v139
	v_mul_f32_e32 v138, 0x3fb8aa3b, v138
	v_mul_f32_e32 v139, 0x3fb8aa3b, v139
	v_exp_f32_e32 v138, v138
	v_exp_f32_e32 v139, v139
	v_mfma_f32_32x32x16_bf16 v[0:15], v[134:137], v[164:167], v[0:15]
	v_cndmask_b32_e64 v136, 0, v143, s[24:25]
	v_cndmask_b32_e64 v137, 0, v138, s[14:15]
	v_cndmask_b32_e64 v138, 0, v139, s[20:21]
	v_cvt_pk_bf16_f32 v134, v213, v215
	v_cvt_pk_bf16_f32 v135, v146, v142
	v_cvt_pk_bf16_f32 v136, v81, v136
	v_cvt_pk_bf16_f32 v137, v137, v138
	ds_read_b64_tr_b16 v[138:139], v207 offset:50240
	ds_read_b64_tr_b16 v[142:143], v207 offset:50304
	ds_read_b64_tr_b16 v[146:147], v207 offset:50368
	ds_read_b64_tr_b16 v[140:141], v207 offset:52800
	ds_read_b64_tr_b16 v[144:145], v207 offset:52864
	ds_read_b64_tr_b16 v[148:149], v207 offset:52928
	v_mfma_f32_32x32x16_bf16 v[48:63], v[130:133], v[134:137], v[48:63]
	v_mov_b32_e32 v130, v64
	v_mov_b32_e32 v131, v68
	v_mul_f32_e64 v132, v130, s68
	v_mul_f32_e64 v133, v131, s68
	v_mul_f32_e64 v64, |v132|, s54
	v_exp_f32_e32 v64, v64
	v_add_f32_e32 v80, v80, v176
	v_add_f32_e32 v81, v172, v242
	s_waitcnt lgkmcnt(2)
	v_mfma_f32_32x32x16_bf16 v[32:47], v[138:141], v[134:137], v[32:47]
	v_add_f32_e64 v80, v80, v182
	v_add_f32_e64 v81, v81, v183
	v_add_f32_e32 v64, 1.0, v64
	s_nop 1
	v_log_f32_e32 v138, v64
	v_min_f32_e32 v64, 0, v132
	s_waitcnt lgkmcnt(1)
	v_mfma_f32_32x32x16_bf16 v[16:31], v[142:145], v[134:137], v[16:31]
	v_mul_f32_e64 v143, |v133|, s54
	v_mul_f32_e32 v68, 0x3f317217, v138
	v_fma_f32 v132, v138, s86, -v68
	v_mov_b32_e32 v68, v65
	v_fmac_f32_e32 v132, 0x3377d1cf, v138
	v_fmac_f32_e32 v132, 0x3f317217, v138
	s_waitcnt lgkmcnt(0)
	v_mfma_f32_32x32x16_bf16 v[0:15], v[146:149], v[134:137], v[0:15]
	v_mul_f32_e64 v134, v68, s68
	v_mul_f32_e64 v135, v69, s68
	v_mul_f32_e64 v65, |v134|, s54
	v_exp_f32_e32 v65, v65
	v_mov_b32_e32 v137, v70
	v_exp_f32_e32 v143, v143
	v_min_f32_e32 v134, 0, v134
	v_add_f32_e32 v65, 1.0, v65
	v_add_f32_e32 v143, 1.0, v143
	s_nop 0
	v_log_f32_e32 v65, v65
	s_nop 0
	v_mul_f32_e32 v136, 0x3f317217, v65
	v_fma_f32 v140, v65, s86, -v136
	v_mov_b32_e32 v136, v66
	v_mul_f32_e32 v138, s68, v136
	v_mul_f32_e32 v139, s68, v137
	v_fmac_f32_e32 v140, 0x3377d1cf, v65
	v_mul_f32_e64 v66, |v138|, s54
	v_exp_f32_e32 v66, v66
	v_fmac_f32_e32 v140, 0x3f317217, v65
	v_min_f32_e32 v138, 0, v138
	v_add_f32_e32 v66, 1.0, v66
	v_mov_b32_e32 v65, v140
	s_nop 1
	v_log_f32_e32 v142, v66
	v_mov_b32_e32 v70, v67
	v_mul_f32_e32 v140, s68, v70
	v_mul_f32_e32 v141, s68, v71
	v_mul_f32_e64 v67, |v140|, s54
	v_exp_f32_e32 v67, v67
	v_mov_b32_e32 v66, v65
	v_mul_f32_e32 v65, 0x3f317217, v142
	v_fma_f32 v65, v142, s86, -v65
	v_fmac_f32_e32 v65, 0x3377d1cf, v142
	v_fmac_f32_e32 v65, 0x3f317217, v142
	v_add_f32_e32 v67, 1.0, v67
	v_min_f32_e32 v140, 0, v140
	s_nop 1
	v_log_f32_e32 v67, v67
	v_mov_b32_e32 v142, v65
	v_mul_f32_e32 v65, 0x3f317217, v67
	v_fma_f32 v65, v67, s86, -v65
	v_fmac_f32_e32 v65, 0x3377d1cf, v67
	v_fmac_f32_e32 v65, 0x3f317217, v67
	s_nop 1
	s_nop 0
	v_log_f32_e32 v143, v143
	v_mov_b32_e32 v144, v65
	v_min_f32_e32 v65, 0, v133
	v_or_b32_e32 v67, 8, v163
	v_mul_f32_e32 v133, 0x3f317217, v143
	v_fma_f32 v133, v143, s86, -v133
	v_fmac_f32_e32 v133, 0x3377d1cf, v143
	v_fmac_f32_e32 v133, 0x3f317217, v143
	s_nop 1
	v_sub_f32_e32 v64, v64, v132
	v_sub_f32_e32 v65, v65, v133
	v_mul_f32_e64 v132, |v135|, s54
	v_exp_f32_e32 v132, v132
	v_cmp_lt_i32_e32 vcc, v67, v153
	v_fma_f32 v130, -v130, s68, v64
	v_fma_f32 v131, -v131, s68, v65
	v_cmp_lt_i32_e64 s[14:15], v163, v152
	v_add_f32_e32 v67, 1.0, v132
	s_nop 0
	v_cndmask_b32_e64 v146, 0, v130, s[14:15]
	v_min_f32_e32 v135, 0, v135
	v_log_f32_e32 v67, v67
	v_cndmask_b32_e32 v147, 0, v131, vcc
	v_or_b32_e32 v131, 1, v163
	v_or_b32_e32 v130, 9, v163
	v_mul_f32_e32 v132, 0x3f317217, v67
	v_fma_f32 v132, v67, s86, -v132
	v_fmac_f32_e32 v132, 0x3377d1cf, v67
	v_fmac_f32_e32 v132, 0x3f317217, v67
	s_nop 1
	v_mov_b32_e32 v67, v132
	v_mul_f32_e64 v132, |v139|, s54
	v_sub_f32_e32 v66, v134, v66
	v_sub_f32_e32 v67, v135, v67
	v_exp_f32_e32 v134, v132
	v_fma_f32 v68, -v68, s68, v66
	v_fma_f32 v69, -v69, s68, v67
	v_cmp_lt_i32_e64 s[18:19], v131, v152
	v_cmp_lt_i32_e64 s[16:17], v130, v153
	v_min_f32_e32 v139, 0, v139
	v_cndmask_b32_e64 v132, 0, v68, s[18:19]
	v_add_f32_e32 v68, 1.0, v134
	v_cndmask_b32_e64 v133, 0, v69, s[16:17]
	v_or_b32_e32 v135, 2, v163
	v_log_f32_e32 v68, v68
	v_cmp_lt_i32_e64 s[24:25], v135, v152
	v_or_b32_e32 v134, 10, v163
	v_mul_f32_e32 v69, 0x3f317217, v68
	v_fma_f32 v69, v68, s86, -v69
	v_fmac_f32_e32 v69, 0x3377d1cf, v68
	v_fmac_f32_e32 v69, 0x3f317217, v68
	s_nop 1
	v_sub_f32_e32 v68, v138, v142
	v_sub_f32_e32 v69, v139, v69
	v_cmp_lt_i32_e64 s[22:23], v134, v153
	v_fma_f32 v130, -v136, s68, v68
	v_fma_f32 v131, -v137, s68, v69
	v_mul_f32_e64 v136, |v141|, s54
	v_exp_f32_e32 v136, v136
	v_cndmask_b32_e64 v142, 0, v130, s[24:25]
	v_cndmask_b32_e64 v143, 0, v131, s[22:23]
	v_mul_f32_e32 v134, s68, v72
	v_mul_f32_e32 v135, s68, v73
	v_add_f32_e32 v130, 1.0, v136
	v_mul_f32_e64 v138, |v134|, s54
	v_exp_f32_e32 v138, v138
	v_log_f32_e32 v130, v130
	v_or_b32_e32 v136, 11, v163
	v_or_b32_e32 v137, 3, v163
	v_cmp_lt_i32_e64 s[34:35], v137, v152
	v_mul_f32_e32 v131, 0x3f317217, v130
	v_fma_f32 v131, v130, s86, -v131
	v_fmac_f32_e32 v131, 0x3377d1cf, v130
	v_fmac_f32_e32 v131, 0x3f317217, v130
	v_min_f32_e32 v134, 0, v134
	v_min_f32_e32 v141, 0, v141
	v_cmp_lt_i32_e64 s[26:27], v136, v153
	v_add_f32_e32 v136, 1.0, v138
	v_sub_f32_e32 v130, v140, v144
	v_sub_f32_e32 v131, v141, v131
	v_log_f32_e32 v136, v136
	v_mul_f32_e64 v138, |v135|, s54
	v_exp_f32_e32 v138, v138
	v_min_f32_e32 v135, 0, v135
	v_mul_f32_e32 v137, 0x3f317217, v136
	v_fma_f32 v137, v136, s86, -v137
	v_fmac_f32_e32 v137, 0x3377d1cf, v136
	v_fmac_f32_e32 v137, 0x3f317217, v136
	v_or_b32_e32 v140, 16, v163
	v_cmp_lt_i32_e64 s[36:37], v140, v152
	v_mov_b32_e32 v136, v137
	v_add_f32_e32 v137, 1.0, v138
	v_fma_f32 v70, -v70, s68, v130
	v_fma_f32 v71, -v71, s68, v131
	s_nop 0
	v_log_f32_e32 v137, v137
	v_mov_b32_e32 v136, v136
	v_cndmask_b32_e64 v71, 0, v71, s[26:27]
	v_mul_f32_e32 v138, 0x3f317217, v137
	v_fma_f32 v138, v137, s86, -v138
	v_fmac_f32_e32 v138, 0x3377d1cf, v137
	v_fmac_f32_e32 v138, 0x3f317217, v137
	v_cndmask_b32_e64 v70, 0, v70, s[34:35]
	s_nop 0
	v_sub_f32_e32 v134, v134, v136
	v_sub_f32_e32 v135, v135, v138
	v_mul_f32_e32 v136, s68, v74
	v_mul_f32_e32 v137, s68, v75
	v_or_b32_e32 v138, 17, v163
	v_mul_f32_e64 v139, |v136|, s54
	v_exp_f32_e32 v139, v139
	v_cmp_lt_i32_e64 s[20:21], v138, v153
	v_mul_f32_e64 v140, |v137|, s54
	v_exp_f32_e32 v140, v140
	v_add_f32_e32 v138, 1.0, v139
	v_min_f32_e32 v136, 0, v136
	v_min_f32_e32 v137, 0, v137
	v_log_f32_e32 v138, v138
	v_fma_f32 v72, -v72, s68, v134
	v_fma_f32 v73, -v73, s68, v135
	v_mul_f32_e32 v139, 0x3f317217, v138
	v_fma_f32 v139, v138, s86, -v139
	v_fmac_f32_e32 v139, 0x3377d1cf, v138
	v_fmac_f32_e32 v139, 0x3f317217, v138
	v_cndmask_b32_e64 v73, 0, v73, s[20:21]
	v_cndmask_b32_e64 v72, 0, v72, s[36:37]
	v_mov_b32_e32 v138, v139
	v_add_f32_e32 v139, 1.0, v140
	s_nop 1
	v_log_f32_e32 v139, v139
	v_mov_b32_e32 v138, v138
	v_mul_f32_e32 v140, 0x3f317217, v139
	v_fma_f32 v140, v139, s86, -v140
	v_fmac_f32_e32 v140, 0x3377d1cf, v139
	v_fmac_f32_e32 v140, 0x3f317217, v139
	s_nop 1
	v_mov_b32_e32 v139, v140
	v_or_b32_e32 v140, 18, v163
	v_cmp_lt_i32_e64 s[30:31], v140, v152
	v_add_f32_e32 v140, v142, v70
	v_add_f32_e32 v141, v143, v71
	v_mov_b32_e32 v142, v76
	v_mov_b32_e32 v143, v78
	v_mul_f32_e32 v144, s68, v142
	v_mul_f32_e32 v145, s68, v143
	v_sub_f32_e32 v136, v136, v138
	v_sub_f32_e32 v137, v137, v139
	v_mul_f32_e64 v76, |v144|, s54
	v_exp_f32_e32 v78, v76
	v_or_b32_e32 v138, 19, v163
	v_fma_f32 v74, -v74, s68, v136
	v_fma_f32 v75, -v75, s68, v137
	v_cmp_lt_i32_e64 s[28:29], v138, v153
	v_cndmask_b32_e64 v138, 0, v74, s[30:31]
	v_mul_f32_e64 v149, |v145|, s54
	v_cndmask_b32_e64 v139, 0, v75, s[28:29]
	v_add_f32_e32 v74, v146, v132
	v_add_f32_e32 v75, v147, v133
	v_exp_f32_e32 v149, v149
	v_add_f32_e32 v146, v74, v140
	v_add_f32_e32 v147, v75, v141
	v_add_f32_e32 v74, 1.0, v78
	ds_bpermute_b32 v148, v235, v147
	ds_bpermute_b32 v76, v235, v146
	v_log_f32_e32 v75, v74
	s_nop 0
	v_mul_f32_e32 v78, 0x3f317217, v75
	v_add_f32_e32 v164, v72, v73
	v_add_f32_e32 v165, v73, v75
	v_min_f32_e32 v74, 0, v144
	v_fma_f32 v144, v75, s86, -v78
	v_mov_b32_e32 v78, v77
	v_mul_f32_e32 v166, s68, v78
	v_mul_f32_e32 v167, s68, v79
	v_fmac_f32_e32 v144, 0x3377d1cf, v75
	v_mul_f32_e64 v77, |v166|, s54
	v_exp_f32_e32 v77, v77
	v_fmac_f32_e32 v144, 0x3f317217, v75
	v_min_f32_e32 v166, 0, v166
	v_add_f32_e32 v77, 1.0, v77
	v_or_b32_e32 v165, 24, v163
	v_cmp_lt_i32_e64 s[42:43], v165, v152
	v_log_f32_e32 v77, v77
	v_mov_b32_e32 v144, v144
	v_mul_f32_e32 v75, 0x3f317217, v77
	v_fma_f32 v75, v77, s86, -v75
	v_fmac_f32_e32 v75, 0x3377d1cf, v77
	v_fmac_f32_e32 v75, 0x3f317217, v77
	s_nop 1
	v_mov_b32_e32 v168, v75
	v_add_f32_e32 v75, 1.0, v149
	v_or_b32_e32 v149, 26, v163
	s_nop 0
	v_log_f32_e32 v77, v75
	v_min_f32_e32 v75, 0, v145
	v_mul_f32_e32 v145, 0x3f317217, v77
	v_fma_f32 v145, v77, s86, -v145
	v_fmac_f32_e32 v145, 0x3377d1cf, v77
	v_fmac_f32_e32 v145, 0x3f317217, v77
	s_nop 1
	v_mov_b32_e32 v145, v145
	v_mul_f32_e64 v77, |v167|, s54
	v_exp_f32_e32 v77, v77
	v_sub_f32_e32 v74, v74, v144
	v_sub_f32_e32 v75, v75, v145
	v_min_f32_e32 v167, 0, v167
	v_cmp_lt_i32_e64 s[38:39], v149, v153
	v_add_f32_e32 v77, 1.0, v77
	v_or_b32_e32 v149, 27, v163
	v_or_b32_e32 v163, 25, v163
	v_log_f32_e32 v77, v77
	v_fma_f32 v142, -v142, s68, v74
	v_fma_f32 v143, -v143, s68, v75
	v_mul_f32_e32 v144, 0x3f317217, v77
	v_fma_f32 v144, v77, s86, -v144
	v_fmac_f32_e32 v144, 0x3377d1cf, v77
	v_fmac_f32_e32 v144, 0x3f317217, v77
	v_cndmask_b32_e64 v143, 0, v143, s[38:39]
	v_cndmask_b32_e64 v142, 0, v142, s[42:43]
	v_mov_b32_e32 v169, v144
	v_sub_f32_e32 v144, v166, v168
	v_sub_f32_e32 v145, v167, v169
	v_cmp_lt_i32_e64 s[40:41], v149, v153
	v_fma_f32 v78, -v78, s68, v144
	v_fma_f32 v79, -v79, s68, v145
	v_cmp_lt_i32_e64 s[44:45], v163, v152
	v_cndmask_b32_e64 v167, 0, v79, s[40:41]
	v_mov_b32_e32 v168, v132
	v_cndmask_b32_e64 v166, 0, v78, s[44:45]
	v_add_f32_e32 v142, v142, v166
	v_add_f32_e32 v143, v143, v167
	v_add_f32_e32 v170, v138, v139
	v_add_f32_e32 v171, v139, v133
	v_add_f32_e32 v164, v164, v170
	v_add_f32_e32 v165, v142, v143
	ds_bpermute_b32 v149, v235, v165
	ds_bpermute_b32 v77, v235, v164
	v_add_f32_e32 v78, v146, v146
	v_add_f32_e32 v79, v146, v147
	v_mov_b32_e32 v169, v64
	v_mov_b32_e32 v64, v133
	v_add_f32_e32 v132, v164, v165
	v_add_f32_e32 v133, v165, v164
	s_waitcnt lgkmcnt(1)
	v_add_f32_e32 v142, v165, v149
	s_waitcnt lgkmcnt(0)
	v_cndmask_b32_e64 v146, 0, v77, s[10:11]
	v_add_f32_e32 v142, v146, v142
	v_add_f32_e32 v146, v132, v149
	v_add_f32_e32 v147, v147, v132
	v_add_f32_e32 v146, v146, v77
	v_cndmask_b32_e64 v163, 0, v148, s[10:11]
	v_add_f32_e32 v147, v147, v149
	v_add_f32_e32 v146, v163, v146
	v_add_f32_e32 v147, v147, v77
	v_cndmask_b32_e64 v163, 0, v76, s[10:11]
	v_add_f32_e32 v76, v76, v148
	v_add_f32_e32 v77, v77, v149
	v_mov_b32_e32 v78, v80
	v_add_f32_e32 v147, v147, v148
	v_add_f32_e32 v77, v76, v77
	v_add_f32_e32 v76, v76, v76
	v_pk_mov_b32 v[80:81], v[80:81], v[132:133] op_sel:[1,0]
	v_add_f32_e32 v147, v163, v147
	v_add_f32_e32 v78, v78, v80
	v_add_f32_e32 v79, v79, v81
	v_mov_b32_e32 v163, v77
	v_add_f32_e32 v80, v162, v78
	v_add_f32_e32 v81, v163, v79
	v_add_f32_e32 v77, v80, v147
	v_add_f32_e32 v78, v168, v140
	v_add_f32_e32 v79, v169, v77
	v_add_f32_e32 v68, v68, v77
	v_add_f32_e32 v76, v78, v79
	v_mul_f32_e32 v76, 0x3fb8aa3b, v76
	v_exp_f32_e32 v76, v76
	v_add_f32_e32 v66, v66, v77
	v_add_f32_e32 v68, v70, v68
	v_add_f32_e32 v70, v130, v77
	v_cndmask_b32_e64 v78, 0, v76, s[14:15]
	v_add_f32_e32 v77, v80, v146
	v_add_f32_e32 v66, v140, v66
	v_add_f32_e32 v64, v64, v141
	v_add_f32_e32 v65, v65, v77
	v_mul_f32_e32 v66, 0x3fb8aa3b, v66
	v_add_f32_e32 v64, v64, v65
	v_add_f32_e32 v65, v67, v77
	v_exp_f32_e32 v66, v66
	v_add_f32_e32 v65, v141, v65
	v_mul_f32_e32 v64, 0x3fb8aa3b, v64
	v_mul_f32_e32 v65, 0x3fb8aa3b, v65
	v_exp_f32_e32 v64, v64
	v_exp_f32_e32 v65, v65
	v_cndmask_b32_e64 v79, 0, v66, s[18:19]
	v_add_f32_e32 v66, v69, v77
	v_add_f32_e32 v66, v71, v66
	v_mul_f32_e32 v66, 0x3fb8aa3b, v66
	v_cndmask_b32_e32 v71, 0, v64, vcc
	v_cndmask_b32_e64 v76, 0, v65, s[16:17]
	v_add_f32_e32 v171, v80, v142
	v_pk_mov_b32 v[64:65], v[72:73], v[134:135] op_sel:[1,0]
	v_exp_f32_e32 v66, v66
	v_add_f32_e32 v67, v131, v77
	v_add_f32_e32 v64, v64, v170
	v_add_f32_e32 v65, v65, v171
	v_add_f32_e32 v67, 0, v67
	v_add_f32_e32 v64, v64, v65
	v_add_f32_e32 v65, v135, v171
	v_mul_f32_e32 v67, 0x3fb8aa3b, v67
	v_mul_f32_e32 v64, 0x3fb8aa3b, v64
	v_add_f32_e32 v65, v170, v65
	v_exp_f32_e32 v67, v67
	v_exp_f32_e32 v64, v64
	v_mul_f32_e32 v65, 0x3fb8aa3b, v65
	v_add_f32_e32 v70, 0, v70
	v_cndmask_b32_e64 v77, 0, v66, s[22:23]
	v_exp_f32_e32 v140, v65
	v_add_f32_e32 v65, v136, v171
	v_add_f32_e32 v66, v137, v171
	v_mul_f32_e32 v68, 0x3fb8aa3b, v68
	v_mul_f32_e32 v70, 0x3fb8aa3b, v70
	v_add_f32_e32 v65, v139, v65
	v_add_f32_e32 v66, 0, v66
	v_exp_f32_e32 v68, v68
	v_exp_f32_e32 v70, v70
	v_mul_f32_e32 v65, 0x3fb8aa3b, v65
	v_mul_f32_e32 v66, 0x3fb8aa3b, v66
	v_cndmask_b32_e64 v131, 0, v67, s[26:27]
	v_exp_f32_e32 v139, v66
	v_exp_f32_e32 v141, v65
	v_cndmask_b32_e64 v146, 0, v64, s[36:37]
	ds_read_b64_tr_b16 v[64:65], v207 offset:34816
	ds_read_b64_tr_b16 v[66:67], v207 offset:37376
	v_cndmask_b32_e64 v138, 0, v149, s[10:11]
	v_add_f32_e32 v72, v80, v138
	v_mov_b32_e32 v142, v74
	v_cndmask_b32_e64 v130, 0, v68, s[24:25]
	v_cndmask_b32_e64 v70, 0, v70, s[34:35]
	v_add_f32_e32 v68, v72, v142
	v_add_f32_e32 v69, v166, v143
	v_cndmask_b32_e64 v74, 0, v139, s[28:29]
	v_add_f32_e32 v73, v68, v69
	v_cvt_pk_bf16_f32 v68, v78, v79
	v_cvt_pk_bf16_f32 v69, v130, v70
	v_cvt_pk_bf16_f32 v70, v71, v76
	v_cvt_pk_bf16_f32 v71, v77, v131
	ds_read_b64_tr_b16 v[76:77], v207 offset:34880
	ds_read_b64_tr_b16 v[130:131], v207 offset:34944
	ds_read_b64_tr_b16 v[134:135], v207 offset:35008
	ds_read_b64_tr_b16 v[78:79], v207 offset:37440
	ds_read_b64_tr_b16 v[132:133], v207 offset:37504
	ds_read_b64_tr_b16 v[136:137], v207 offset:37568
	s_waitcnt lgkmcnt(6)
	v_mfma_f32_32x32x16_bf16 v[48:63], v[64:67], v[68:71], v[48:63]
	v_mul_f32_e32 v64, 0x3fb8aa3b, v73
	v_exp_f32_e32 v64, v64
	v_add_f32_e32 v65, v72, v75
	v_add_f32_e32 v65, v65, v167
	v_mul_f32_e32 v65, 0x3fb8aa3b, v65
	v_cndmask_b32_e64 v139, 0, v64, s[42:43]
	v_add_f32_e32 v64, v72, v144
	v_exp_f32_e32 v75, v65
	v_add_f32_e32 v65, v72, v145
	v_add_f32_e32 v64, v64, v143
	v_add_f32_e32 v65, 0, v65
	v_mul_f32_e32 v64, 0x3fb8aa3b, v64
	v_mul_f32_e32 v65, 0x3fb8aa3b, v65
	v_exp_f32_e32 v64, v64
	v_exp_f32_e32 v72, v65
	s_waitcnt lgkmcnt(2)
	v_mfma_f32_32x32x16_bf16 v[32:47], v[76:79], v[68:71], v[32:47]
	v_cndmask_b32_e64 v73, 0, v140, s[20:21]
	v_cndmask_b32_e64 v138, 0, v141, s[30:31]
	v_cndmask_b32_e64 v76, 0, v64, s[44:45]
	v_cndmask_b32_e64 v72, 0, v72, s[40:41]
	ds_read_b64_tr_b16 v[64:65], v207 offset:39936
	ds_read_b64_tr_b16 v[66:67], v207 offset:42496
	v_add_f32_e32 v162, v80, v81
	s_mov_b32 s14, 0xc2480000
	s_waitcnt lgkmcnt(3)
	v_mfma_f32_32x32x16_bf16 v[16:31], v[130:133], v[68:71], v[16:31]
	v_cmp_gt_f32_e32 vcc, s14, v162
	s_cmp_eq_u64 vcc, exec
	s_cselect_b64 s[14:15], -1, 0
	s_waitcnt lgkmcnt(2)
	v_mfma_f32_32x32x16_bf16 v[0:15], v[134:137], v[68:71], v[0:15]
	v_cndmask_b32_e64 v71, 0, v75, s[38:39]
	v_cvt_pk_bf16_f32 v68, v146, v73
	v_cvt_pk_bf16_f32 v69, v138, v74
	v_cvt_pk_bf16_f32 v70, v139, v76
	v_cvt_pk_bf16_f32 v71, v71, v72
	ds_read_b64_tr_b16 v[72:73], v207 offset:40000
	ds_read_b64_tr_b16 v[76:77], v207 offset:40064
	ds_read_b64_tr_b16 v[130:131], v207 offset:40128
	ds_read_b64_tr_b16 v[74:75], v207 offset:42560
	ds_read_b64_tr_b16 v[78:79], v207 offset:42624
	ds_read_b64_tr_b16 v[132:133], v207 offset:42688
	s_waitcnt lgkmcnt(6)
	v_mfma_f32_32x32x16_bf16 v[48:63], v[64:67], v[68:71], v[48:63]
	s_waitcnt lgkmcnt(2)
	v_mfma_f32_32x32x16_bf16 v[32:47], v[72:75], v[68:71], v[32:47]
	s_waitcnt lgkmcnt(1)
	v_mfma_f32_32x32x16_bf16 v[16:31], v[76:79], v[68:71], v[16:31]
	s_waitcnt lgkmcnt(0)
	v_mfma_f32_32x32x16_bf16 v[0:15], v[130:133], v[68:71], v[0:15]
	s_nop 0

.LBB0_530:
	s_add_i32 s10, s25, s28
	s_cmp_gt_i32 s10, s26
	s_cbranch_scc1 .LBB0_527
	v_mov_b32_e32 v128, s67
	v_add3_u32 v216, s20, v246, v192
	ds_read_b32 v251, v128
	ds_read_b128 v[160:163], v216
	ds_read_b128 v[164:167], v240
	ds_read_b128 v[168:171], v216 offset:32
	ds_read_b128 v[172:175], v240 offset:32
	ds_read_b128 v[128:131], v216 offset:64
	ds_read_b128 v[132:135], v240 offset:64
	ds_read_b128 v[136:139], v216 offset:96
	ds_read_b128 v[140:143], v240 offset:96
	s_cmpk_gt_i32 s27, 0x7f
	s_cselect_b64 s[10:11], -1, 0
	s_cmpk_lt_i32 s27, 0x80
	v_add_u32_e32 v252, s27, v249
	s_cselect_b64 s[18:19], -1, 0
	s_and_b64 vcc, exec, s[10:11]
	v_add_u32_e32 v253, 63, v252
	s_waitcnt lgkmcnt(6)
	v_mfma_f32_32x32x16_bf16 v[144:159], v[160:163], v[164:167], 0
	ds_read_b128 v[160:163], v216 offset:128
	ds_read_b128 v[164:167], v240 offset:128
	s_waitcnt lgkmcnt(6)
	v_mfma_f32_32x32x16_bf16 v[144:159], v[168:171], v[172:175], v[144:159]
	ds_read_b128 v[168:171], v216 offset:160
	ds_read_b128 v[172:175], v240 offset:160
	s_waitcnt lgkmcnt(6)
	v_mfma_f32_32x32x16_bf16 v[144:159], v[128:131], v[132:135], v[144:159]
	s_waitcnt lgkmcnt(4)
	v_mfma_f32_32x32x16_bf16 v[144:159], v[136:139], v[140:143], v[144:159]
	s_waitcnt lgkmcnt(2)
	v_mfma_f32_32x32x16_bf16 v[128:143], v[160:163], v[164:167], 0
	ds_read_b128 v[160:163], v216 offset:192
	ds_read_b128 v[164:167], v240 offset:192
	s_waitcnt lgkmcnt(2)
	v_mfma_f32_32x32x16_bf16 v[128:143], v[168:171], v[172:175], v[128:143]
	ds_read_b128 v[168:171], v216 offset:224
	ds_read_b128 v[172:175], v240 offset:224
	s_waitcnt lgkmcnt(2)
	v_mfma_f32_32x32x16_bf16 v[128:143], v[160:163], v[164:167], v[128:143]
	s_waitcnt lgkmcnt(0)
	v_mfma_f32_32x32x16_bf16 v[128:143], v[168:171], v[172:175], v[128:143]
	s_nop 1
	s_cbranch_vccnz .LBB0_565
	s_mov_b32 s99, 0x12800
	v_mov_b32_e32 v217, 0xff800000
	v_max_i32_e32 v160, 0, v253
	v_min_u32_e32 v160, 0x80, v160
	v_lshl_add_u32 v160, v160, 2, s99
	ds_read_b32 v160, v160
	v_add_u32_e32 v161, 62, v252
	v_max_i32_e32 v161, 0, v161
	v_min_u32_e32 v161, 0x80, v161
	v_lshl_add_u32 v161, v161, 2, s99
	ds_read_b32 v161, v161
	v_add_u32_e32 v162, 61, v252
	v_max_i32_e32 v162, 0, v162
	v_min_u32_e32 v162, 0x80, v162
	v_lshl_add_u32 v162, v162, 2, s99
	ds_read_b32 v162, v162
	v_add_u32_e32 v163, 60, v252
	v_max_i32_e32 v163, 0, v163
	v_min_u32_e32 v163, 0x80, v163
	v_lshl_add_u32 v163, v163, 2, s99
	ds_read_b32 v163, v163
	v_add_u32_e32 v164, 55, v252
	v_max_i32_e32 v164, 0, v164
	v_min_u32_e32 v164, 0x80, v164
	v_lshl_add_u32 v164, v164, 2, s99
	ds_read_b32 v164, v164
	v_add_u32_e32 v165, 54, v252
	v_max_i32_e32 v165, 0, v165
	v_min_u32_e32 v165, 0x80, v165
	v_lshl_add_u32 v165, v165, 2, s99
	ds_read_b32 v165, v165
	v_add_u32_e32 v166, 53, v252
	v_max_i32_e32 v166, 0, v166
	v_min_u32_e32 v166, 0x80, v166
	v_lshl_add_u32 v166, v166, 2, s99
	ds_read_b32 v166, v166
	v_add_u32_e32 v167, 52, v252
	v_max_i32_e32 v167, 0, v167
	v_min_u32_e32 v167, 0x80, v167
	v_lshl_add_u32 v167, v167, 2, s99
	ds_read_b32 v167, v167
	s_waitcnt lgkmcnt(7)
	v_fmac_f32_e32 v160, 0x3e38aa3b, v144
	v_cmp_le_i32_e32 vcc, 0xffffffc1, v252
	s_nop 1
	v_cndmask_b32_e32 v144, v217, v160, vcc
	s_waitcnt lgkmcnt(6)
	v_fmac_f32_e32 v161, 0x3e38aa3b, v145
	v_cmp_le_i32_e32 vcc, 0xffffffc2, v252
	s_nop 1
	v_cndmask_b32_e32 v145, v217, v161, vcc
	s_waitcnt lgkmcnt(5)
	v_fmac_f32_e32 v162, 0x3e38aa3b, v146
	v_cmp_le_i32_e32 vcc, 0xffffffc3, v252
	s_nop 1
	v_cndmask_b32_e32 v146, v217, v162, vcc
	s_waitcnt lgkmcnt(4)
	v_fmac_f32_e32 v163, 0x3e38aa3b, v147
	v_cmp_le_i32_e32 vcc, 0xffffffc4, v252
	s_nop 1
	v_cndmask_b32_e32 v147, v217, v163, vcc
	s_waitcnt lgkmcnt(3)
	v_fmac_f32_e32 v164, 0x3e38aa3b, v148
	v_cmp_le_i32_e32 vcc, 0xffffffc9, v252
	s_nop 1
	v_cndmask_b32_e32 v148, v217, v164, vcc
	s_waitcnt lgkmcnt(2)
	v_fmac_f32_e32 v165, 0x3e38aa3b, v149
	v_cmp_le_i32_e32 vcc, 0xffffffca, v252
	s_nop 1
	v_cndmask_b32_e32 v149, v217, v165, vcc
	s_waitcnt lgkmcnt(1)
	v_fmac_f32_e32 v166, 0x3e38aa3b, v150
	v_cmp_le_i32_e32 vcc, 0xffffffcb, v252
	s_nop 1
	v_cndmask_b32_e32 v150, v217, v166, vcc
	s_waitcnt lgkmcnt(0)
	v_fmac_f32_e32 v167, 0x3e38aa3b, v151
	v_cmp_le_i32_e32 vcc, 0xffffffcc, v252
	s_nop 1
	v_cndmask_b32_e32 v151, v217, v167, vcc
	v_add_u32_e32 v168, 47, v252
	v_max_i32_e32 v168, 0, v168
	v_min_u32_e32 v168, 0x80, v168
	v_lshl_add_u32 v168, v168, 2, s99
	ds_read_b32 v168, v168
	v_add_u32_e32 v169, 46, v252
	v_max_i32_e32 v169, 0, v169
	v_min_u32_e32 v169, 0x80, v169
	v_lshl_add_u32 v169, v169, 2, s99
	ds_read_b32 v169, v169
	v_add_u32_e32 v170, 45, v252
	v_max_i32_e32 v170, 0, v170
	v_min_u32_e32 v170, 0x80, v170
	v_lshl_add_u32 v170, v170, 2, s99
	ds_read_b32 v170, v170
	v_add_u32_e32 v171, 44, v252
	v_max_i32_e32 v171, 0, v171
	v_min_u32_e32 v171, 0x80, v171
	v_lshl_add_u32 v171, v171, 2, s99
	ds_read_b32 v171, v171
	v_add_u32_e32 v172, 39, v252
	v_max_i32_e32 v172, 0, v172
	v_min_u32_e32 v172, 0x80, v172
	v_lshl_add_u32 v172, v172, 2, s99
	ds_read_b32 v172, v172
	v_add_u32_e32 v173, 38, v252
	v_max_i32_e32 v173, 0, v173
	v_min_u32_e32 v173, 0x80, v173
	v_lshl_add_u32 v173, v173, 2, s99
	ds_read_b32 v173, v173
	v_add_u32_e32 v174, 37, v252
	v_max_i32_e32 v174, 0, v174
	v_min_u32_e32 v174, 0x80, v174
	v_lshl_add_u32 v174, v174, 2, s99
	ds_read_b32 v174, v174
	v_add_u32_e32 v175, 36, v252
	v_max_i32_e32 v175, 0, v175
	v_min_u32_e32 v175, 0x80, v175
	v_lshl_add_u32 v175, v175, 2, s99
	ds_read_b32 v175, v175
	s_waitcnt lgkmcnt(7)
	v_fmac_f32_e32 v168, 0x3e38aa3b, v152
	v_cmp_le_i32_e32 vcc, 0xffffffd1, v252
	s_nop 1
	v_cndmask_b32_e32 v152, v217, v168, vcc
	s_waitcnt lgkmcnt(6)
	v_fmac_f32_e32 v169, 0x3e38aa3b, v153
	v_cmp_le_i32_e32 vcc, 0xffffffd2, v252
	s_nop 1
	v_cndmask_b32_e32 v153, v217, v169, vcc
	s_waitcnt lgkmcnt(5)
	v_fmac_f32_e32 v170, 0x3e38aa3b, v154
	v_cmp_le_i32_e32 vcc, 0xffffffd3, v252
	s_nop 1
	v_cndmask_b32_e32 v154, v217, v170, vcc
	s_waitcnt lgkmcnt(4)
	v_fmac_f32_e32 v171, 0x3e38aa3b, v155
	v_cmp_le_i32_e32 vcc, 0xffffffd4, v252
	s_nop 1
	v_cndmask_b32_e32 v155, v217, v171, vcc
	s_waitcnt lgkmcnt(3)
	v_fmac_f32_e32 v172, 0x3e38aa3b, v156
	v_cmp_le_i32_e32 vcc, 0xffffffd9, v252
	s_nop 1
	v_cndmask_b32_e32 v156, v217, v172, vcc
	s_waitcnt lgkmcnt(2)
	v_fmac_f32_e32 v173, 0x3e38aa3b, v157
	v_cmp_le_i32_e32 vcc, 0xffffffda, v252
	s_nop 1
	v_cndmask_b32_e32 v157, v217, v173, vcc
	s_waitcnt lgkmcnt(1)
	v_fmac_f32_e32 v174, 0x3e38aa3b, v158
	v_cmp_le_i32_e32 vcc, 0xffffffdb, v252
	s_nop 1
	v_cndmask_b32_e32 v158, v217, v174, vcc
	s_waitcnt lgkmcnt(0)
	v_fmac_f32_e32 v175, 0x3e38aa3b, v159
	v_cmp_le_i32_e32 vcc, 0xffffffdc, v252
	s_nop 1
	v_cndmask_b32_e32 v159, v217, v175, vcc
	s_nop 0

.LBB0_746:
	v_lshl_add_u64 v[0:1], s[12:13], 0, v[192:193]
	v_add_co_u32_e32 v4, vcc, 0x1000, v0
	v_lshl_add_u64 v[32:33], s[16:17], 0, v[52:53]
	s_nop 0
	v_addc_co_u32_e32 v5, vcc, 0, v1, vcc
	v_add_co_u32_e32 v34, vcc, 0x1ba00000, v32
	global_load_dwordx4 v[8:11], v[0:1], off offset:16
	global_load_dwordx4 v[12:15], v[0:1], off
	global_load_dwordx4 v[16:19], v[0:1], off offset:2064
	global_load_dwordx4 v[20:23], v[0:1], off offset:2048
	v_lshl_add_u64 v[2:3], v[0:1], 0, s[26:27]
	v_lshl_add_u64 v[0:1], v[0:1], 0, s[24:25]
	v_addc_co_u32_e32 v35, vcc, 0, v33, vcc
	global_load_dwordx4 v[28:31], v[4:5], off
	global_load_dwordx4 v[24:27], v[2:3], off offset:16
	s_nop 0
	global_load_dwordx4 v[4:7], v[4:5], off offset:2048
	s_nop 0
	global_load_dwordx4 v[0:3], v[0:1], off offset:16
	s_nop 0
	global_load_dwordx4 v[64:67], v[34:35], off
	global_load_dwordx4 v[68:71], v[34:35], off offset:1024
	global_load_dwordx4 v[58:61], v[34:35], off offset:2048
	global_load_dwordx4 v[82:85], v[34:35], off offset:3072
	s_mov_b32 s4, 0xf800000
	s_waitcnt vmcnt(3)
	v_and_b32_e32 v75, 0xffff0000, v66
	v_and_b32_e32 v74, 0xffff0000, v64
	v_and_b32_e32 v79, 0xffff0000, v67
	v_and_b32_e32 v78, 0xffff0000, v65
	v_lshlrev_b32_e32 v73, 16, v66
	v_lshlrev_b32_e32 v72, 16, v64
	v_lshlrev_b32_e32 v77, 16, v67
	v_lshlrev_b32_e32 v76, 16, v65
	v_pk_mul_f32 v[34:35], v[74:75], v[74:75]
	v_pk_mul_f32 v[64:65], v[78:79], v[78:79]
	v_pk_fma_f32 v[34:35], v[72:73], v[72:73], v[34:35]
	v_pk_fma_f32 v[64:65], v[76:77], v[76:77], v[64:65]
	s_waitcnt vmcnt(2)
	v_lshlrev_b32_e32 v32, 16, v70
	v_pk_add_f32 v[34:35], v[34:35], v[64:65]
	v_and_b32_e32 v33, 0xffff0000, v70
	v_pk_add_f32 v[64:65], v[34:35], v[34:35] op_sel_hi:[0,1]
	v_lshlrev_b32_e32 v35, 16, v69
	v_lshlrev_b32_e32 v34, 16, v68
	v_and_b32_e32 v69, 0xffff0000, v69
	v_and_b32_e32 v68, 0xffff0000, v68
	s_waitcnt vmcnt(1)
	v_lshlrev_b32_e32 v36, 16, v58
	v_pk_mul_f32 v[66:67], v[68:69], v[68:69]
	v_lshlrev_b32_e32 v70, 16, v71
	s_waitcnt vmcnt(0)
	v_lshlrev_b32_e32 v56, 16, v84
	v_and_b32_e32 v63, 0xffff0000, v84
	v_lshlrev_b32_e32 v54, 16, v85
	v_and_b32_e32 v55, 0xffff0000, v85
	v_pk_fma_f32 v[66:67], v[34:35], v[34:35], v[66:67]
	v_mul_f32_e32 v37, v32, v32
	v_mul_f32_e32 v85, v33, v33
	v_and_b32_e32 v71, 0xffff0000, v71
	v_mul_f32_e32 v62, v70, v70
	v_mov_b32_e32 v84, v36
	v_and_b32_e32 v80, 0xffff0000, v58
	v_lshlrev_b32_e32 v38, 16, v59
	v_and_b32_e32 v39, 0xffff0000, v59
	v_pk_add_f32 v[66:67], v[66:67], v[66:67] op_sel_hi:[0,1]
	v_pk_fma_f32 v[86:87], v[70:71], v[70:71], v[62:63] op_sel_hi:[1,1,0]
	v_pk_add_f32 v[84:85], v[36:37], v[84:85]
	v_mul_f32_e32 v86, v80, v80
	v_mul_f32_e32 v64, v38, v38
	v_mul_f32_e32 v66, v39, v39
	v_mul_f32_e32 v88, v36, v36
	v_mov_b32_e32 v89, v85
	v_pk_add_f32 v[84:85], v[88:89], v[86:87]
	v_pk_add_f32 v[64:65], v[64:65], v[66:67]
	v_and_b32_e32 v67, 0xffff0000, v61
	v_pk_add_f32 v[64:65], v[84:85], v[64:65]
	v_and_b32_e32 v66, 0xffff0000, v60
	v_pk_add_f32 v[84:85], v[64:65], v[64:65] op_sel_hi:[0,1]
	v_lshlrev_b32_e32 v65, 16, v61
	v_lshlrev_b32_e32 v64, 16, v60
	v_pk_mul_f32 v[60:61], v[66:67], v[66:67]
	v_lshlrev_b32_e32 v58, 16, v82
	v_pk_fma_f32 v[60:61], v[64:65], v[64:65], v[60:61]
	v_and_b32_e32 v59, 0xffff0000, v82
	v_pk_add_f32 v[86:87], v[60:61], v[60:61] op_sel_hi:[0,1]
	v_lshlrev_b32_e32 v60, 16, v83
	v_mul_f32_e32 v57, v58, v58
	v_mul_f32_e32 v89, v59, v59
	v_and_b32_e32 v61, 0xffff0000, v83
	v_mul_f32_e32 v62, v60, v60
	v_mov_b32_e32 v88, v56
	v_pk_fma_f32 v[82:83], v[60:61], v[60:61], v[62:63] op_sel_hi:[1,1,0]
	v_pk_add_f32 v[88:89], v[56:57], v[88:89]
	v_mul_f32_e32 v82, v63, v63
	v_mul_f32_e32 v86, v54, v54
	v_mul_f32_e32 v84, v55, v55
	v_mul_f32_e32 v90, v56, v56
	v_mov_b32_e32 v91, v89
	v_pk_add_f32 v[82:83], v[90:91], v[82:83]
	v_pk_add_f32 v[84:85], v[86:87], v[84:85]
	v_mov_b32_e32 v90, v72
	v_pk_add_f32 v[82:83], v[82:83], v[84:85]
	v_mov_b32_e32 v91, v74
	v_add_f32_e32 v37, v82, v83
	ds_bpermute_b32 v57, v230, v37
	v_mov_b32_e32 v74, v73
	s_waitcnt lgkmcnt(0)
	v_add_f32_e32 v37, v37, v57
	ds_bpermute_b32 v57, v231, v37
	s_waitcnt lgkmcnt(0)
	v_add_f32_e32 v37, v37, v57
	ds_bpermute_b32 v57, v232, v37
	s_waitcnt lgkmcnt(0)
	v_add_f32_e32 v37, v37, v57
	ds_bpermute_b32 v57, v233, v37
	s_waitcnt lgkmcnt(0)
	v_add_f32_e32 v37, v37, v57
	ds_bpermute_b32 v57, v234, v37
	s_waitcnt lgkmcnt(0)
	v_add_f32_e32 v37, v37, v57
	ds_bpermute_b32 v57, v235, v37
	s_waitcnt lgkmcnt(0)
	v_add_f32_e32 v37, v37, v57
	v_fmamk_f32 v37, v37, 0x3a000000, v219
	v_cmp_gt_f32_e32 vcc, s4, v37
	v_mul_f32_e32 v57, 0x4f800000, v37
	s_nop 0
	v_cndmask_b32_e32 v37, v37, v57, vcc
	v_sqrt_f32_e32 v57, v37
	s_nop 0
	v_add_u32_e32 v62, -1, v57
	v_fma_f32 v81, -v62, v57, v37
	v_cmp_ge_f32_e64 s[4:5], 0, v81
	v_add_u32_e32 v81, 1, v57
	s_nop 0
	v_cndmask_b32_e64 v62, v57, v62, s[4:5]
	v_fma_f32 v57, -v81, v57, v37
	v_cmp_lt_f32_e64 s[4:5], 0, v57
	s_nop 1
	v_cndmask_b32_e64 v57, v62, v81, s[4:5]
	v_mul_f32_e32 v62, 0x37800000, v57
	v_cndmask_b32_e32 v57, v57, v62, vcc
	v_cmp_class_f32_e32 vcc, v37, v220
	s_nop 1
	v_cndmask_b32_e32 v37, v57, v37, vcc
	v_div_scale_f32 v57, s[4:5], v37, v37, 1.0
	v_rcp_f32_e32 v62, v57
	s_nop 0
	v_fma_f32 v81, -v57, v62, 1.0
	v_fmac_f32_e32 v62, v81, v62
	v_div_scale_f32 v81, vcc, 1.0, v37, 1.0
	v_mul_f32_e32 v82, v81, v62
	v_fma_f32 v83, -v57, v82, v81
	v_fmac_f32_e32 v82, v83, v62
	v_fma_f32 v57, -v57, v82, v81
	v_div_fmas_f32 v57, v57, v62, v82
	v_mov_b64_e32 v[82:83], v[100:101]
	v_mov_b64_e32 v[84:85], v[102:103]
	v_mov_b64_e32 v[86:87], v[104:105]
	v_mov_b64_e32 v[88:89], v[106:107]
	v_div_fixup_f32 v62, v57, v37, 1.0
	v_mov_b32_e32 v37, v80
	v_mov_b32_e32 v57, v63
	s_andn2_b64 vcc, exec, s[8:9]
	v_pk_mul_f32 v[72:73], v[82:83], v[74:75]
	v_pk_mul_f32 v[86:87], v[86:87], v[90:91]
	v_mov_b32_e32 v91, v78
	v_mov_b32_e32 v78, v77
	v_pk_mul_f32 v[74:75], v[84:85], v[78:79]
	v_mov_b32_e32 v90, v76
	v_pk_fma_f32 v[10:11], v[74:75], v[62:63], v[10:11] op_sel_hi:[1,0,1]
	v_pk_fma_f32 v[8:9], v[72:73], v[62:63], v[8:9] op_sel_hi:[1,0,1]
	v_mov_b64_e32 v[72:73], v[108:109]
	v_mov_b64_e32 v[74:75], v[110:111]
	v_mov_b64_e32 v[76:77], v[112:113]
	v_mov_b64_e32 v[78:79], v[114:115]
	v_mov_b32_e32 v83, v68
	v_mov_b32_e32 v68, v35
	v_mov_b32_e32 v82, v34
	v_pk_mul_f32 v[88:89], v[88:89], v[90:91]
	v_pk_fma_f32 v[12:13], v[86:87], v[62:63], v[12:13] op_sel_hi:[1,0,1]
	v_pk_fma_f32 v[14:15], v[88:89], v[62:63], v[14:15] op_sel_hi:[1,0,1]
	v_pk_mul_f32 v[32:33], v[72:73], v[32:33]
	v_pk_mul_f32 v[34:35], v[78:79], v[68:69]
	v_pk_fma_f32 v[16:17], v[32:33], v[62:63], v[16:17] op_sel_hi:[1,0,1]
	v_pk_fma_f32 v[22:23], v[34:35], v[62:63], v[22:23] op_sel_hi:[1,0,1]
	v_pk_mul_f32 v[34:35], v[74:75], v[70:71]
	v_pk_mul_f32 v[76:77], v[76:77], v[82:83]
	v_pk_fma_f32 v[18:19], v[34:35], v[62:63], v[18:19] op_sel_hi:[1,0,1]
	v_mov_b64_e32 v[32:33], v[116:117]
	v_mov_b64_e32 v[34:35], v[118:119]
	v_mov_b64_e32 v[68:69], v[120:121]
	v_mov_b64_e32 v[70:71], v[122:123]
	v_pk_fma_f32 v[20:21], v[76:77], v[62:63], v[20:21] op_sel_hi:[1,0,1]
	v_pk_mul_f32 v[36:37], v[68:69], v[36:37]
	s_nop 0
	v_pk_fma_f32 v[28:29], v[36:37], v[62:63], v[28:29] op_sel_hi:[1,0,1]
	v_mov_b32_e32 v36, v64
	v_mov_b32_e32 v37, v66
	v_mov_b32_e32 v66, v65
	v_pk_mul_f32 v[38:39], v[70:71], v[38:39]
	v_pk_mul_f32 v[32:33], v[32:33], v[36:37]
	v_pk_mul_f32 v[34:35], v[34:35], v[66:67]
	v_pk_fma_f32 v[30:31], v[38:39], v[62:63], v[30:31] op_sel_hi:[1,0,1]
	v_pk_fma_f32 v[26:27], v[34:35], v[62:63], v[26:27] op_sel_hi:[1,0,1]
	v_pk_fma_f32 v[24:25], v[32:33], v[62:63], v[24:25] op_sel_hi:[1,0,1]
	v_mov_b64_e32 v[32:33], v[124:125]
	v_mov_b64_e32 v[34:35], v[126:127]
	v_mov_b64_e32 v[36:37], v[128:129]
	v_mov_b64_e32 v[38:39], v[130:131]
	v_pk_mul_f32 v[32:33], v[32:33], v[56:57]
	v_pk_mul_f32 v[36:37], v[36:37], v[58:59]
	v_pk_mul_f32 v[38:39], v[38:39], v[60:61]
	v_pk_mul_f32 v[34:35], v[34:35], v[54:55]
	v_pk_fma_f32 v[6:7], v[38:39], v[62:63], v[6:7] op_sel_hi:[1,0,1]
	v_pk_fma_f32 v[4:5], v[36:37], v[62:63], v[4:5] op_sel_hi:[1,0,1]
	v_pk_fma_f32 v[2:3], v[34:35], v[62:63], v[2:3] op_sel_hi:[1,0,1]
	v_pk_fma_f32 v[0:1], v[32:33], v[62:63], v[0:1] op_sel_hi:[1,0,1]
	s_cbranch_vccnz .LBB0_748
	v_lshl_add_u64 v[32:33], s[18:19], 0, v[192:193]
	global_store_dwordx4 v[32:33], v[12:15], off
	global_store_dwordx4 v[32:33], v[8:11], off offset:16
	global_store_dwordx4 v[32:33], v[20:23], off offset:2048
	global_store_dwordx4 v[32:33], v[16:19], off offset:2064
	v_add_co_u32_e32 v32, vcc, 0x1000, v32
	s_nop 1
	v_addc_co_u32_e32 v33, vcc, 0, v33, vcc
	global_store_dwordx4 v[32:33], v[28:31], off
	global_store_dwordx4 v[32:33], v[24:27], off offset:16
	global_store_dwordx4 v[32:33], v[4:7], off offset:2048
	global_store_dwordx4 v[32:33], v[0:3], off offset:2064
	s_nop 0
.LBB0_748:
	s_andn2_b64 vcc, exec, s[10:11]
	s_cbranch_vccnz .LBB0_745
	v_mov_b32_e32 v34, v13
	v_mov_b32_e32 v35, v9
	v_mov_b32_e32 v32, v12
	v_mov_b32_e32 v33, v8
	v_pk_mul_f32 v[34:35], v[34:35], v[34:35]
	v_mov_b32_e32 v36, v15
	v_mov_b32_e32 v37, v11
	v_pk_fma_f32 v[32:33], v[32:33], v[32:33], v[34:35]
	v_mov_b32_e32 v34, v14
	v_mov_b32_e32 v35, v10
	v_pk_mul_f32 v[36:37], v[36:37], v[36:37]
	s_mov_b32 s4, 0xf800000
	v_pk_fma_f32 v[34:35], v[34:35], v[34:35], v[36:37]
	v_pk_mul_f32 v[36:37], v[20:21], v[20:21]
	v_pk_add_f32 v[32:33], v[32:33], v[34:35]
	v_pk_mul_f32 v[34:35], v[22:23], v[22:23]
	v_pk_add_f32 v[32:33], v[32:33], v[32:33] op_sel_hi:[0,1]
	v_pk_mov_b32 v[38:39], v[36:37], v[34:35] op_sel:[1,0]
	v_mov_b32_e32 v37, v35
	v_mul_f32_e32 v32, v16, v16
	v_pk_add_f32 v[34:35], v[38:39], v[36:37]
	v_pk_fma_f32 v[36:37], v[16:17], v[16:17], v[32:33] op_sel_hi:[1,1,0]
	v_mul_f32_e32 v32, v18, v18
	v_pk_add_f32 v[34:35], v[34:35], v[34:35] op_sel_hi:[0,1]
	v_pk_fma_f32 v[38:39], v[18:19], v[18:19], v[32:33] op_sel_hi:[1,1,0]
	v_mul_f32_e32 v36, v28, v28
	v_mul_f32_e32 v38, v29, v29
	v_mul_f32_e32 v34, v30, v30
	v_mul_f32_e32 v32, v31, v31
	v_pk_add_f32 v[36:37], v[36:37], v[38:39]
	v_pk_add_f32 v[32:33], v[34:35], v[32:33]
	v_pk_mul_f32 v[34:35], v[26:27], v[26:27]
	v_pk_add_f32 v[32:33], v[36:37], v[32:33]
	v_pk_mul_f32 v[36:37], v[24:25], v[24:25]
	v_pk_add_f32 v[32:33], v[32:33], v[32:33] op_sel_hi:[0,1]
	v_pk_mov_b32 v[38:39], v[36:37], v[34:35] op_sel:[1,0]
	v_mov_b32_e32 v37, v35
	v_mul_f32_e32 v32, v4, v4
	v_pk_add_f32 v[34:35], v[38:39], v[36:37]
	v_pk_fma_f32 v[36:37], v[4:5], v[4:5], v[32:33] op_sel_hi:[1,1,0]
	v_mul_f32_e32 v32, v6, v6
	v_pk_add_f32 v[34:35], v[34:35], v[34:35] op_sel_hi:[0,1]
	v_pk_fma_f32 v[38:39], v[6:7], v[6:7], v[32:33] op_sel_hi:[1,1,0]
	v_mul_f32_e32 v36, v0, v0
	v_mul_f32_e32 v38, v1, v1
	v_mul_f32_e32 v34, v2, v2
	v_mul_f32_e32 v32, v3, v3
	v_pk_add_f32 v[36:37], v[36:37], v[38:39]
	v_pk_add_f32 v[32:33], v[34:35], v[32:33]
	v_lshl_add_u64 v[38:39], s[14:15], 0, v[52:53]
	v_pk_add_f32 v[32:33], v[36:37], v[32:33]
	s_nop 0
	v_add_f32_e32 v32, v32, v33
	ds_bpermute_b32 v33, v230, v32
	s_waitcnt lgkmcnt(0)
	v_add_f32_e32 v32, v32, v33
	ds_bpermute_b32 v33, v231, v32
	s_waitcnt lgkmcnt(0)
	v_add_f32_e32 v32, v32, v33
	ds_bpermute_b32 v33, v232, v32
	s_waitcnt lgkmcnt(0)
	v_add_f32_e32 v32, v32, v33
	ds_bpermute_b32 v33, v233, v32
	s_waitcnt lgkmcnt(0)
	v_add_f32_e32 v32, v32, v33
	ds_bpermute_b32 v33, v234, v32
	s_waitcnt lgkmcnt(0)
	v_add_f32_e32 v32, v32, v33
	ds_bpermute_b32 v33, v235, v32
	s_waitcnt lgkmcnt(0)
	v_add_f32_e32 v32, v32, v33
	v_fmamk_f32 v32, v32, 0x3a000000, v219
	v_cmp_gt_f32_e32 vcc, s4, v32
	v_mul_f32_e32 v33, 0x4f800000, v32
	s_nop 0
	v_cndmask_b32_e32 v32, v32, v33, vcc
	v_sqrt_f32_e32 v33, v32
	s_nop 0
	v_add_u32_e32 v34, -1, v33
	v_fma_f32 v35, -v34, v33, v32
	v_cmp_ge_f32_e64 s[4:5], 0, v35
	v_add_u32_e32 v35, 1, v33
	s_nop 0
	v_cndmask_b32_e64 v34, v33, v34, s[4:5]
	v_fma_f32 v33, -v35, v33, v32
	v_cmp_lt_f32_e64 s[4:5], 0, v33
	s_nop 1
	v_cndmask_b32_e64 v33, v34, v35, s[4:5]
	v_mul_f32_e32 v34, 0x37800000, v33
	v_cndmask_b32_e32 v33, v33, v34, vcc
	v_cmp_class_f32_e32 vcc, v32, v220
	s_nop 1
	v_cndmask_b32_e32 v32, v33, v32, vcc
	v_div_scale_f32 v33, s[4:5], v32, v32, 1.0
	v_rcp_f32_e32 v34, v33
	s_mov_b32 s4, 0xffff0000
	s_mov_b32 s5, 0x14200000
	v_fma_f32 v35, -v33, v34, 1.0
	v_fmac_f32_e32 v34, v35, v34
	v_div_scale_f32 v35, vcc, 1.0, v32, 1.0
	v_mul_f32_e32 v36, v35, v34
	v_fma_f32 v37, -v33, v36, v35
	v_fmac_f32_e32 v36, v37, v34
	v_fma_f32 v33, -v33, v36, v35
	v_div_fmas_f32 v33, v33, v34, v36
	v_div_fixup_f32 v36, v33, v32, 1.0
	v_mov_b64_e32 v[32:33], v[132:133]
	v_mov_b64_e32 v[34:35], v[134:135]
	v_mov_b64_e32 v[54:55], v[136:137]
	v_mov_b64_e32 v[56:57], v[138:139]
	v_pk_mul_f32 v[10:11], v[10:11], v[34:35]
	v_pk_mul_f32 v[12:13], v[12:13], v[54:55]
	v_pk_mul_f32 v[8:9], v[8:9], v[32:33]
	v_pk_mul_f32 v[12:13], v[12:13], v[36:37] op_sel_hi:[1,0]
	v_pk_mul_f32 v[32:33], v[10:11], v[36:37] op_sel_hi:[1,0]
	v_bfe_u32 v10, v12, 16, 1
	v_pk_mul_f32 v[14:15], v[14:15], v[56:57]
	v_add3_u32 v10, v12, v10, s77
	v_bfe_u32 v11, v13, 16, 1
	v_pk_mul_f32 v[14:15], v[14:15], v[36:37] op_sel_hi:[1,0]
	v_lshrrev_b32_e32 v10, 16, v10
	v_add3_u32 v11, v13, v11, s77
	v_and_or_b32 v10, v11, s4, v10
	v_bfe_u32 v11, v14, 16, 1
	v_add3_u32 v11, v14, v11, s77
	v_bfe_u32 v12, v15, 16, 1
	v_pk_mul_f32 v[8:9], v[8:9], v[36:37] op_sel_hi:[1,0]
	v_lshrrev_b32_e32 v11, 16, v11
	v_add3_u32 v12, v15, v12, s77
	v_and_or_b32 v11, v12, s4, v11
	v_bfe_u32 v12, v8, 16, 1
	v_add3_u32 v8, v8, v12, s77
	v_bfe_u32 v12, v9, 16, 1
	v_lshrrev_b32_e32 v8, 16, v8
	v_add3_u32 v9, v9, v12, s77
	v_and_or_b32 v12, v9, s4, v8
	v_bfe_u32 v8, v32, 16, 1
	v_add3_u32 v8, v32, v8, s77
	v_bfe_u32 v9, v33, 16, 1
	v_lshrrev_b32_e32 v8, 16, v8
	v_add3_u32 v9, v33, v9, s77
	v_and_or_b32 v13, v9, s4, v8
	v_add_co_u32_e32 v8, vcc, s5, v38
	s_nop 1
	v_addc_co_u32_e32 v9, vcc, 0, v39, vcc
	global_store_dwordx4 v[8:9], v[10:13], off
	s_nop 1
	v_mov_b64_e32 v[10:11], v[140:141]
	v_mov_b64_e32 v[12:13], v[142:143]
	s_nop 0
	v_mov_b64_e32 v[32:33], v[144:145]
	v_mov_b64_e32 v[34:35], v[146:147]
	v_pk_mul_f32 v[12:13], v[18:19], v[12:13]
	v_pk_mul_f32 v[20:21], v[20:21], v[32:33]
	v_pk_mul_f32 v[10:11], v[16:17], v[10:11]
	v_pk_mul_f32 v[20:21], v[20:21], v[36:37] op_sel_hi:[1,0]
	v_pk_mul_f32 v[16:17], v[12:13], v[36:37] op_sel_hi:[1,0]
	v_pk_mul_f32 v[12:13], v[10:11], v[36:37] op_sel_hi:[1,0]
	v_bfe_u32 v10, v20, 16, 1
	v_pk_mul_f32 v[14:15], v[22:23], v[34:35]
	v_add3_u32 v10, v20, v10, s77
	v_bfe_u32 v11, v21, 16, 1
	v_pk_mul_f32 v[14:15], v[14:15], v[36:37] op_sel_hi:[1,0]
	v_lshrrev_b32_e32 v10, 16, v10
	v_add3_u32 v11, v21, v11, s77
	v_and_or_b32 v10, v11, s4, v10
	v_bfe_u32 v11, v14, 16, 1
	v_add3_u32 v11, v14, v11, s77
	v_bfe_u32 v14, v15, 16, 1
	v_lshrrev_b32_e32 v11, 16, v11
	v_add3_u32 v14, v15, v14, s77
	v_and_or_b32 v11, v14, s4, v11
	v_bfe_u32 v14, v12, 16, 1
	v_add3_u32 v12, v12, v14, s77
	v_bfe_u32 v14, v13, 16, 1
	v_lshrrev_b32_e32 v12, 16, v12
	v_add3_u32 v13, v13, v14, s77
	v_and_or_b32 v12, v13, s4, v12
	v_bfe_u32 v13, v16, 16, 1
	v_add3_u32 v13, v16, v13, s77
	v_bfe_u32 v14, v17, 16, 1
	v_lshrrev_b32_e32 v13, 16, v13
	v_add3_u32 v14, v17, v14, s77
	v_and_or_b32 v13, v14, s4, v13
	global_store_dwordx4 v[8:9], v[10:13], off offset:1024
	s_nop 1
	v_mov_b64_e32 v[10:11], v[148:149]
	v_mov_b64_e32 v[12:13], v[150:151]
	s_nop 0
	v_mov_b64_e32 v[14:15], v[152:153]
	v_mov_b64_e32 v[16:17], v[154:155]
	v_pk_mul_f32 v[12:13], v[26:27], v[12:13]
	v_pk_mul_f32 v[14:15], v[28:29], v[14:15]
	v_pk_mul_f32 v[10:11], v[24:25], v[10:11]
	v_pk_mul_f32 v[14:15], v[36:37], v[14:15] op_sel_hi:[0,1]
	v_pk_mul_f32 v[18:19], v[36:37], v[12:13] op_sel_hi:[0,1]
	v_pk_mul_f32 v[12:13], v[36:37], v[10:11] op_sel_hi:[0,1]
	v_bfe_u32 v10, v14, 16, 1
	v_pk_mul_f32 v[16:17], v[30:31], v[16:17]
	v_add3_u32 v10, v14, v10, s77
	v_bfe_u32 v11, v15, 16, 1
	v_pk_mul_f32 v[16:17], v[36:37], v[16:17] op_sel_hi:[0,1]
	v_lshrrev_b32_e32 v10, 16, v10
	v_add3_u32 v11, v15, v11, s77
	v_and_or_b32 v10, v11, s4, v10
	v_bfe_u32 v11, v16, 16, 1
	v_add3_u32 v11, v16, v11, s77
	v_bfe_u32 v14, v17, 16, 1
	v_lshrrev_b32_e32 v11, 16, v11
	v_add3_u32 v14, v17, v14, s77
	v_and_or_b32 v11, v14, s4, v11
	v_bfe_u32 v14, v12, 16, 1
	v_add3_u32 v12, v12, v14, s77
	v_bfe_u32 v14, v13, 16, 1
	v_lshrrev_b32_e32 v12, 16, v12
	v_add3_u32 v13, v13, v14, s77
	v_and_or_b32 v12, v13, s4, v12
	v_bfe_u32 v13, v18, 16, 1
	v_add3_u32 v13, v18, v13, s77
	v_bfe_u32 v14, v19, 16, 1
	v_lshrrev_b32_e32 v13, 16, v13
	v_add3_u32 v14, v19, v14, s77
	v_and_or_b32 v13, v14, s4, v13
	global_store_dwordx4 v[8:9], v[10:13], off offset:2048
	s_nop 1
	v_mov_b64_e32 v[10:11], v[156:157]
	v_mov_b64_e32 v[12:13], v[158:159]
	s_nop 0
	v_mov_b64_e32 v[14:15], v[160:161]
	v_mov_b64_e32 v[16:17], v[162:163]
	v_pk_mul_f32 v[2:3], v[2:3], v[12:13]
	v_pk_mul_f32 v[4:5], v[4:5], v[14:15]
	v_pk_mul_f32 v[0:1], v[0:1], v[10:11]
	v_pk_mul_f32 v[4:5], v[36:37], v[4:5] op_sel_hi:[0,1]
	v_pk_mul_f32 v[10:11], v[36:37], v[2:3] op_sel_hi:[0,1]
	v_pk_mul_f32 v[2:3], v[36:37], v[0:1] op_sel_hi:[0,1]
	v_bfe_u32 v0, v4, 16, 1
	v_pk_mul_f32 v[6:7], v[6:7], v[16:17]
	v_add3_u32 v0, v4, v0, s77
	v_bfe_u32 v1, v5, 16, 1
	v_pk_mul_f32 v[6:7], v[36:37], v[6:7] op_sel_hi:[0,1]
	v_lshrrev_b32_e32 v0, 16, v0
	v_add3_u32 v1, v5, v1, s77
	v_and_or_b32 v0, v1, s4, v0
	v_bfe_u32 v1, v6, 16, 1
	v_add3_u32 v1, v6, v1, s77
	v_bfe_u32 v4, v7, 16, 1
	v_lshrrev_b32_e32 v1, 16, v1
	v_add3_u32 v4, v7, v4, s77
	v_and_or_b32 v1, v4, s4, v1
	v_bfe_u32 v4, v2, 16, 1
	v_add3_u32 v2, v2, v4, s77
	v_bfe_u32 v4, v3, 16, 1
	v_lshrrev_b32_e32 v2, 16, v2
	v_add3_u32 v3, v3, v4, s77
	v_and_or_b32 v2, v3, s4, v2
	v_bfe_u32 v3, v10, 16, 1
	v_add3_u32 v3, v10, v3, s77
	v_bfe_u32 v4, v11, 16, 1
	v_lshrrev_b32_e32 v3, 16, v3
	v_add3_u32 v4, v11, v4, s77
	v_and_or_b32 v3, v4, s4, v3
	global_store_dwordx4 v[8:9], v[0:3], off offset:3072
	s_branch .LBB0_745
	s_nop 0
